# early block barrier moved from before the last 2 to before the last 4 MFMAs (paired order)
# baseline (speedup 1.0000x reference)
.LBB0_257:
	s_or_b64 exec, exec, s[50:51]
	s_add_u32 s0, s12, s6
	ds_read_b128 v[146:149], v137
	ds_read_b128 v[150:153], v137 offset:1024
	ds_read_b128 v[154:157], v137 offset:2048
	ds_read_b128 v[158:161], v137 offset:3072
	ds_read_b128 v[162:165], v138
	ds_read_b128 v[166:169], v138 offset:1024
	ds_read_b128 v[170:173], v138 offset:2048
	ds_read_b128 v[174:177], v138 offset:3072
	s_addc_u32 s1, s13, s7
	s_add_u32 s50, s0, 0x20000
	s_addc_u32 s51, s1, 0
	s_add_u32 s52, s93, s6
	s_addc_u32 s53, s94, s7
	s_cmp_eq_u32 s6, 0x60000
	s_cselect_b32 s62, s95, s50
	s_cselect_b32 s63, s31, s51
	s_cselect_b32 s51, s29, s53
	s_cselect_b32 s50, s96, s52
	s_add_u32 s52, s62, 0x8000
	s_addc_u32 s53, s63, 0
	s_add_u32 s54, s50, 0x8000
	s_addc_u32 s55, s51, 0
	ds_read_b128 v[178:181], v139
	ds_read_b128 v[182:185], v139 offset:1024
	ds_read_b128 v[186:189], v139 offset:2048
	ds_read_b128 v[190:193], v139 offset:3072
	ds_read_b128 v[198:201], v139 offset:4096
	ds_read_b128 v[202:205], v139 offset:5120
	ds_read_b128 v[206:209], v139 offset:6144
	ds_read_b128 v[212:215], v139 offset:7168
	s_add_u32 s0, s0, 0x1c000
	s_addc_u32 s1, s1, 0
	s_mov_b32 m0, s78
	s_nop 0
	global_load_lds_dwordx4 v134, s[0:1]
	s_add_u32 m0, s78, 0x2000
	s_nop 0
	global_load_lds_dwordx4 v135, s[0:1]
	s_waitcnt vmcnt(8)
	s_waitcnt lgkmcnt(0)
	s_setprio 1
	s_barrier
	v_mfma_f32_16x16x32_bf16 v[122:125], v[146:149], v[178:181], v[122:125]
	v_mfma_f32_16x16x32_bf16 v[122:125], v[150:153], v[182:185], v[122:125]
	s_waitcnt lgkmcnt(5)
	v_mfma_f32_16x16x32_bf16 v[114:117], v[154:157], v[178:181], v[114:117]
	v_mfma_f32_16x16x32_bf16 v[114:117], v[158:161], v[182:185], v[114:117]
	s_waitcnt lgkmcnt(3)
	v_mfma_f32_16x16x32_bf16 v[106:109], v[146:149], v[186:189], v[106:109]
	v_mfma_f32_16x16x32_bf16 v[106:109], v[150:153], v[190:193], v[106:109]
	s_waitcnt lgkmcnt(1)
	v_mfma_f32_16x16x32_bf16 v[98:101], v[154:157], v[186:189], v[98:101]
	v_mfma_f32_16x16x32_bf16 v[98:101], v[158:161], v[190:193], v[98:101]
	v_mfma_f32_16x16x32_bf16 v[90:93], v[146:149], v[198:201], v[90:93]
	v_mfma_f32_16x16x32_bf16 v[90:93], v[150:153], v[202:205], v[90:93]
	v_mfma_f32_16x16x32_bf16 v[82:85], v[154:157], v[198:201], v[82:85]
	v_mfma_f32_16x16x32_bf16 v[82:85], v[158:161], v[202:205], v[82:85]
	v_mfma_f32_16x16x32_bf16 v[74:77], v[146:149], v[206:209], v[74:77]
	v_mfma_f32_16x16x32_bf16 v[74:77], v[150:153], v[212:215], v[74:77]
	s_waitcnt lgkmcnt(0)
	v_mfma_f32_16x16x32_bf16 v[66:69], v[154:157], v[206:209], v[66:69]
	v_mfma_f32_16x16x32_bf16 v[66:69], v[158:161], v[212:215], v[66:69]
	s_setprio 0
	s_setprio 1
	v_mfma_f32_16x16x32_bf16 v[126:129], v[162:165], v[178:181], v[126:129]
	v_mfma_f32_16x16x32_bf16 v[126:129], v[166:169], v[182:185], v[126:129]
	v_mfma_f32_16x16x32_bf16 v[118:121], v[170:173], v[178:181], v[118:121]
	v_mfma_f32_16x16x32_bf16 v[118:121], v[174:177], v[182:185], v[118:121]
	v_mfma_f32_16x16x32_bf16 v[110:113], v[162:165], v[186:189], v[110:113]
	v_mfma_f32_16x16x32_bf16 v[110:113], v[166:169], v[190:193], v[110:113]
	v_mfma_f32_16x16x32_bf16 v[102:105], v[170:173], v[186:189], v[102:105]
	v_mfma_f32_16x16x32_bf16 v[102:105], v[174:177], v[190:193], v[102:105]
	v_mfma_f32_16x16x32_bf16 v[94:97], v[162:165], v[198:201], v[94:97]
	v_mfma_f32_16x16x32_bf16 v[94:97], v[166:169], v[202:205], v[94:97]
	v_mfma_f32_16x16x32_bf16 v[86:89], v[170:173], v[198:201], v[86:89]
	v_mfma_f32_16x16x32_bf16 v[86:89], v[174:177], v[202:205], v[86:89]
	s_setprio 2
	s_barrier
	v_mfma_f32_16x16x32_bf16 v[78:81], v[162:165], v[206:209], v[78:81]
	v_mfma_f32_16x16x32_bf16 v[78:81], v[166:169], v[212:215], v[78:81]
	v_mfma_f32_16x16x32_bf16 v[70:73], v[170:173], v[206:209], v[70:73]
	v_mfma_f32_16x16x32_bf16 v[70:73], v[174:177], v[212:215], v[70:73]
	s_setprio 0
	s_nop 0
	ds_read_b128 v[178:181], v139 offset:16384
	ds_read_b128 v[182:185], v139 offset:17408
	ds_read_b128 v[186:189], v139 offset:18432
	ds_read_b128 v[190:193], v139 offset:19456
	ds_read_b128 v[198:201], v139 offset:20480
	ds_read_b128 v[202:205], v139 offset:21504
	ds_read_b128 v[206:209], v139 offset:22528
	ds_read_b128 v[212:215], v139 offset:23552
	s_mov_b32 m0, s11
	s_nop 0
	global_load_lds_dwordx4 v134, s[50:51]
	s_add_u32 m0, s11, 0x2000
	s_nop 0
	global_load_lds_dwordx4 v135, s[50:51]
	s_add_u32 s0, s50, 0x4000
	s_addc_u32 s1, s51, 0
	s_mov_b32 m0, s68
	s_nop 0
	global_load_lds_dwordx4 v134, s[0:1]
	s_add_u32 m0, s68, 0x2000
	s_nop 0
	global_load_lds_dwordx4 v135, s[0:1]
	s_nop 0
	s_mov_b32 m0, s65
	s_nop 0
	global_load_lds_dwordx4 v134, s[62:63]
	s_add_u32 m0, s65, 0x2000
	s_nop 0
	global_load_lds_dwordx4 v135, s[62:63]
	s_waitcnt vmcnt(8)
	s_waitcnt lgkmcnt(0)
	s_setprio 1
	s_barrier
	v_mfma_f32_16x16x32_bf16 v[58:61], v[146:149], v[178:181], v[58:61]
	v_mfma_f32_16x16x32_bf16 v[58:61], v[150:153], v[182:185], v[58:61]
	s_waitcnt lgkmcnt(5)
	v_mfma_f32_16x16x32_bf16 v[50:53], v[154:157], v[178:181], v[50:53]
	v_mfma_f32_16x16x32_bf16 v[50:53], v[158:161], v[182:185], v[50:53]
	s_waitcnt lgkmcnt(3)
	v_mfma_f32_16x16x32_bf16 v[42:45], v[146:149], v[186:189], v[42:45]
	v_mfma_f32_16x16x32_bf16 v[42:45], v[150:153], v[190:193], v[42:45]
	s_waitcnt lgkmcnt(1)
	v_mfma_f32_16x16x32_bf16 v[34:37], v[154:157], v[186:189], v[34:37]
	v_mfma_f32_16x16x32_bf16 v[34:37], v[158:161], v[190:193], v[34:37]
	v_mfma_f32_16x16x32_bf16 v[26:29], v[146:149], v[198:201], v[26:29]
	v_mfma_f32_16x16x32_bf16 v[26:29], v[150:153], v[202:205], v[26:29]
	v_mfma_f32_16x16x32_bf16 v[18:21], v[154:157], v[198:201], v[18:21]
	v_mfma_f32_16x16x32_bf16 v[18:21], v[158:161], v[202:205], v[18:21]
	v_mfma_f32_16x16x32_bf16 v[10:13], v[146:149], v[206:209], v[10:13]
	v_mfma_f32_16x16x32_bf16 v[10:13], v[150:153], v[212:215], v[10:13]
	s_waitcnt lgkmcnt(0)
	v_mfma_f32_16x16x32_bf16 v[2:5], v[154:157], v[206:209], v[2:5]
	v_mfma_f32_16x16x32_bf16 v[2:5], v[158:161], v[212:215], v[2:5]
	s_setprio 0
	s_setprio 1
	v_mfma_f32_16x16x32_bf16 v[62:65], v[162:165], v[178:181], v[62:65]
	v_mfma_f32_16x16x32_bf16 v[62:65], v[166:169], v[182:185], v[62:65]
	v_mfma_f32_16x16x32_bf16 v[54:57], v[170:173], v[178:181], v[54:57]
	v_mfma_f32_16x16x32_bf16 v[54:57], v[174:177], v[182:185], v[54:57]
	v_mfma_f32_16x16x32_bf16 v[46:49], v[162:165], v[186:189], v[46:49]
	v_mfma_f32_16x16x32_bf16 v[46:49], v[166:169], v[190:193], v[46:49]
	v_mfma_f32_16x16x32_bf16 v[38:41], v[170:173], v[186:189], v[38:41]
	v_mfma_f32_16x16x32_bf16 v[38:41], v[174:177], v[190:193], v[38:41]
	v_mfma_f32_16x16x32_bf16 v[30:33], v[162:165], v[198:201], v[30:33]
	v_mfma_f32_16x16x32_bf16 v[30:33], v[166:169], v[202:205], v[30:33]
	v_mfma_f32_16x16x32_bf16 v[22:25], v[170:173], v[198:201], v[22:25]
	v_mfma_f32_16x16x32_bf16 v[22:25], v[174:177], v[202:205], v[22:25]
	s_setprio 2
	s_barrier
	v_mfma_f32_16x16x32_bf16 v[14:17], v[162:165], v[206:209], v[14:17]
	v_mfma_f32_16x16x32_bf16 v[14:17], v[166:169], v[212:215], v[14:17]
	v_mfma_f32_16x16x32_bf16 v[6:9], v[170:173], v[206:209], v[6:9]
	v_mfma_f32_16x16x32_bf16 v[6:9], v[174:177], v[212:215], v[6:9]
	s_setprio 0
	s_nop 0
	ds_read_b128 v[146:149], v140
	ds_read_b128 v[150:153], v140 offset:1024
	ds_read_b128 v[154:157], v140 offset:2048
	ds_read_b128 v[158:161], v140 offset:3072
	ds_read_b128 v[162:165], v141
	ds_read_b128 v[166:169], v141 offset:1024
	ds_read_b128 v[170:173], v141 offset:2048
	ds_read_b128 v[174:177], v141 offset:3072
	ds_read_b128 v[178:181], v139 offset:32768
	ds_read_b128 v[182:185], v139 offset:33792
	ds_read_b128 v[186:189], v139 offset:34816
	ds_read_b128 v[190:193], v139 offset:35840
	ds_read_b128 v[198:201], v139 offset:36864
	ds_read_b128 v[202:205], v139 offset:37888
	ds_read_b128 v[206:209], v139 offset:38912
	ds_read_b128 v[212:215], v139 offset:39936
	s_add_u32 s0, s62, 0x4000
	s_addc_u32 s1, s63, 0
	s_mov_b32 m0, s69
	s_nop 0
	global_load_lds_dwordx4 v134, s[0:1]
	s_add_u32 m0, s69, 0x2000
	s_nop 0
	global_load_lds_dwordx4 v135, s[0:1]
	s_waitcnt vmcnt(8)
	s_waitcnt lgkmcnt(0)
	s_setprio 1
	s_barrier
	v_mfma_f32_16x16x32_bf16 v[122:125], v[146:149], v[178:181], v[122:125]
	v_mfma_f32_16x16x32_bf16 v[122:125], v[150:153], v[182:185], v[122:125]
	s_waitcnt lgkmcnt(5)
	v_mfma_f32_16x16x32_bf16 v[114:117], v[154:157], v[178:181], v[114:117]
	v_mfma_f32_16x16x32_bf16 v[114:117], v[158:161], v[182:185], v[114:117]
	s_waitcnt lgkmcnt(3)
	v_mfma_f32_16x16x32_bf16 v[106:109], v[146:149], v[186:189], v[106:109]
	v_mfma_f32_16x16x32_bf16 v[106:109], v[150:153], v[190:193], v[106:109]
	s_waitcnt lgkmcnt(1)
	v_mfma_f32_16x16x32_bf16 v[98:101], v[154:157], v[186:189], v[98:101]
	v_mfma_f32_16x16x32_bf16 v[98:101], v[158:161], v[190:193], v[98:101]
	v_mfma_f32_16x16x32_bf16 v[90:93], v[146:149], v[198:201], v[90:93]
	v_mfma_f32_16x16x32_bf16 v[90:93], v[150:153], v[202:205], v[90:93]
	v_mfma_f32_16x16x32_bf16 v[82:85], v[154:157], v[198:201], v[82:85]
	v_mfma_f32_16x16x32_bf16 v[82:85], v[158:161], v[202:205], v[82:85]
	v_mfma_f32_16x16x32_bf16 v[74:77], v[146:149], v[206:209], v[74:77]
	v_mfma_f32_16x16x32_bf16 v[74:77], v[150:153], v[212:215], v[74:77]
	s_waitcnt lgkmcnt(0)
	v_mfma_f32_16x16x32_bf16 v[66:69], v[154:157], v[206:209], v[66:69]
	v_mfma_f32_16x16x32_bf16 v[66:69], v[158:161], v[212:215], v[66:69]
	s_setprio 0
	s_setprio 1
	v_mfma_f32_16x16x32_bf16 v[126:129], v[162:165], v[178:181], v[126:129]
	v_mfma_f32_16x16x32_bf16 v[126:129], v[166:169], v[182:185], v[126:129]
	v_mfma_f32_16x16x32_bf16 v[118:121], v[170:173], v[178:181], v[118:121]
	v_mfma_f32_16x16x32_bf16 v[118:121], v[174:177], v[182:185], v[118:121]
	v_mfma_f32_16x16x32_bf16 v[110:113], v[162:165], v[186:189], v[110:113]
	v_mfma_f32_16x16x32_bf16 v[110:113], v[166:169], v[190:193], v[110:113]
	v_mfma_f32_16x16x32_bf16 v[102:105], v[170:173], v[186:189], v[102:105]
	v_mfma_f32_16x16x32_bf16 v[102:105], v[174:177], v[190:193], v[102:105]
	v_mfma_f32_16x16x32_bf16 v[94:97], v[162:165], v[198:201], v[94:97]
	v_mfma_f32_16x16x32_bf16 v[94:97], v[166:169], v[202:205], v[94:97]
	v_mfma_f32_16x16x32_bf16 v[86:89], v[170:173], v[198:201], v[86:89]
	v_mfma_f32_16x16x32_bf16 v[86:89], v[174:177], v[202:205], v[86:89]
	s_setprio 2
	s_barrier
	v_mfma_f32_16x16x32_bf16 v[78:81], v[162:165], v[206:209], v[78:81]
	v_mfma_f32_16x16x32_bf16 v[78:81], v[166:169], v[212:215], v[78:81]
	v_mfma_f32_16x16x32_bf16 v[70:73], v[170:173], v[206:209], v[70:73]
	v_mfma_f32_16x16x32_bf16 v[70:73], v[174:177], v[212:215], v[70:73]
	s_setprio 0
	s_nop 0
	ds_read_b128 v[178:181], v139 offset:49152
	ds_read_b128 v[182:185], v139 offset:50176
	ds_read_b128 v[186:189], v139 offset:51200
	ds_read_b128 v[190:193], v139 offset:52224
	ds_read_b128 v[198:201], v139 offset:53248
	ds_read_b128 v[202:205], v139 offset:54272
	ds_read_b128 v[206:209], v139 offset:55296
	ds_read_b128 v[212:215], v139 offset:56320
	s_mov_b32 m0, s74
	s_nop 0
	global_load_lds_dwordx4 v134, s[54:55]
	s_add_u32 m0, s74, 0x2000
	s_nop 0
	global_load_lds_dwordx4 v135, s[54:55]
	s_add_u32 s0, s50, 0xc000
	s_addc_u32 s1, s51, 0
	s_mov_b32 m0, s77
	s_nop 0
	global_load_lds_dwordx4 v134, s[0:1]
	s_add_u32 m0, s77, 0x2000
	s_nop 0
	global_load_lds_dwordx4 v135, s[0:1]
	s_nop 0
	s_mov_b32 m0, s76
	s_nop 0
	global_load_lds_dwordx4 v134, s[52:53]
	s_add_u32 m0, s76, 0x2000
	s_nop 0
	global_load_lds_dwordx4 v135, s[52:53]
	s_waitcnt vmcnt(8)
	s_waitcnt lgkmcnt(0)
	s_setprio 1
	s_barrier
	v_mfma_f32_16x16x32_bf16 v[58:61], v[146:149], v[178:181], v[58:61]
	v_mfma_f32_16x16x32_bf16 v[58:61], v[150:153], v[182:185], v[58:61]
	s_waitcnt lgkmcnt(5)
	v_mfma_f32_16x16x32_bf16 v[50:53], v[154:157], v[178:181], v[50:53]
	v_mfma_f32_16x16x32_bf16 v[50:53], v[158:161], v[182:185], v[50:53]
	s_waitcnt lgkmcnt(3)
	v_mfma_f32_16x16x32_bf16 v[42:45], v[146:149], v[186:189], v[42:45]
	v_mfma_f32_16x16x32_bf16 v[42:45], v[150:153], v[190:193], v[42:45]
	s_waitcnt lgkmcnt(1)
	v_mfma_f32_16x16x32_bf16 v[34:37], v[154:157], v[186:189], v[34:37]
	v_mfma_f32_16x16x32_bf16 v[34:37], v[158:161], v[190:193], v[34:37]
	v_mfma_f32_16x16x32_bf16 v[26:29], v[146:149], v[198:201], v[26:29]
	v_mfma_f32_16x16x32_bf16 v[26:29], v[150:153], v[202:205], v[26:29]
	v_mfma_f32_16x16x32_bf16 v[18:21], v[154:157], v[198:201], v[18:21]
	v_mfma_f32_16x16x32_bf16 v[18:21], v[158:161], v[202:205], v[18:21]
	v_mfma_f32_16x16x32_bf16 v[10:13], v[146:149], v[206:209], v[10:13]
	v_mfma_f32_16x16x32_bf16 v[10:13], v[150:153], v[212:215], v[10:13]
	s_waitcnt lgkmcnt(0)
	v_mfma_f32_16x16x32_bf16 v[2:5], v[154:157], v[206:209], v[2:5]
	v_mfma_f32_16x16x32_bf16 v[2:5], v[158:161], v[212:215], v[2:5]
	s_setprio 0
	s_setprio 1
	v_mfma_f32_16x16x32_bf16 v[62:65], v[162:165], v[178:181], v[62:65]
	v_mfma_f32_16x16x32_bf16 v[62:65], v[166:169], v[182:185], v[62:65]
	v_mfma_f32_16x16x32_bf16 v[54:57], v[170:173], v[178:181], v[54:57]
	v_mfma_f32_16x16x32_bf16 v[54:57], v[174:177], v[182:185], v[54:57]
	v_mfma_f32_16x16x32_bf16 v[46:49], v[162:165], v[186:189], v[46:49]
	v_mfma_f32_16x16x32_bf16 v[46:49], v[166:169], v[190:193], v[46:49]
	v_mfma_f32_16x16x32_bf16 v[38:41], v[170:173], v[186:189], v[38:41]
	v_mfma_f32_16x16x32_bf16 v[38:41], v[174:177], v[190:193], v[38:41]
	v_mfma_f32_16x16x32_bf16 v[30:33], v[162:165], v[198:201], v[30:33]
	v_mfma_f32_16x16x32_bf16 v[30:33], v[166:169], v[202:205], v[30:33]
	v_mfma_f32_16x16x32_bf16 v[22:25], v[170:173], v[198:201], v[22:25]
	v_mfma_f32_16x16x32_bf16 v[22:25], v[174:177], v[202:205], v[22:25]
	s_setprio 2
	s_barrier
	v_mfma_f32_16x16x32_bf16 v[14:17], v[162:165], v[206:209], v[14:17]
	v_mfma_f32_16x16x32_bf16 v[14:17], v[166:169], v[212:215], v[14:17]
	v_mfma_f32_16x16x32_bf16 v[6:9], v[170:173], v[206:209], v[6:9]
	v_mfma_f32_16x16x32_bf16 v[6:9], v[174:177], v[212:215], v[6:9]
	s_setprio 0
	s_nop 0
	s_add_i32 s97, s97, 2
	s_add_u32 s6, s6, 0x10000
	s_addc_u32 s7, s7, 0
	s_cmp_gt_u32 s97, 13
	s_cbranch_scc1 .LBB0_259
	v_mov_b32_e32 v145, v130
	s_branch .LBB0_255

.LBB0_364:
	s_add_i32 s26, s93, 2
	s_lshl_b64 s[62:63], s[26:27], 15
	s_add_u32 s64, s18, s62
	s_addc_u32 s65, s19, s63
	s_and_b64 s[52:53], s[50:51], exec
	s_cselect_b32 s53, s65, s39
	s_cselect_b32 s52, s64, s38
	s_add_u32 s62, s20, s62
	s_waitcnt vmcnt(8)
	s_addc_u32 s63, s21, s63
	s_waitcnt lgkmcnt(0)
	s_and_b64 s[50:51], s[50:51], exec
	s_cselect_b32 s51, s63, s49
	s_cselect_b32 s50, s62, s48
	s_setprio 1
	s_barrier
	v_mfma_f32_16x16x32_bf16 v[126:129], v[146:149], v[186:189], v[126:129]
	v_mfma_f32_16x16x32_bf16 v[126:129], v[150:153], v[190:193], v[126:129]
	s_waitcnt lgkmcnt(5)
	v_mfma_f32_16x16x32_bf16 v[122:125], v[154:157], v[186:189], v[122:125]
	v_mfma_f32_16x16x32_bf16 v[122:125], v[158:161], v[190:193], v[122:125]
	s_waitcnt lgkmcnt(3)
	v_mfma_f32_16x16x32_bf16 v[118:121], v[146:149], v[178:181], v[118:121]
	v_mfma_f32_16x16x32_bf16 v[118:121], v[150:153], v[182:185], v[118:121]
	s_waitcnt lgkmcnt(1)
	v_mfma_f32_16x16x32_bf16 v[114:117], v[154:157], v[178:181], v[114:117]
	v_mfma_f32_16x16x32_bf16 v[114:117], v[158:161], v[182:185], v[114:117]
	v_mfma_f32_16x16x32_bf16 v[110:113], v[146:149], v[170:173], v[110:113]
	v_mfma_f32_16x16x32_bf16 v[110:113], v[150:153], v[174:177], v[110:113]
	v_mfma_f32_16x16x32_bf16 v[106:109], v[154:157], v[170:173], v[106:109]
	v_mfma_f32_16x16x32_bf16 v[106:109], v[158:161], v[174:177], v[106:109]
	v_mfma_f32_16x16x32_bf16 v[102:105], v[146:149], v[162:165], v[102:105]
	v_mfma_f32_16x16x32_bf16 v[102:105], v[150:153], v[166:169], v[102:105]
	s_waitcnt lgkmcnt(0)
	v_mfma_f32_16x16x32_bf16 v[98:101], v[154:157], v[162:165], v[98:101]
	v_mfma_f32_16x16x32_bf16 v[98:101], v[158:161], v[166:169], v[98:101]
	s_setprio 0
	s_setprio 1
	v_mfma_f32_16x16x32_bf16 v[94:97], v[130:133], v[186:189], v[94:97]
	v_mfma_f32_16x16x32_bf16 v[94:97], v[134:137], v[190:193], v[94:97]
	v_mfma_f32_16x16x32_bf16 v[90:93], v[138:141], v[186:189], v[90:93]
	v_mfma_f32_16x16x32_bf16 v[90:93], v[142:145], v[190:193], v[90:93]
	v_mfma_f32_16x16x32_bf16 v[86:89], v[130:133], v[178:181], v[86:89]
	v_mfma_f32_16x16x32_bf16 v[86:89], v[134:137], v[182:185], v[86:89]
	v_mfma_f32_16x16x32_bf16 v[82:85], v[138:141], v[178:181], v[82:85]
	v_mfma_f32_16x16x32_bf16 v[82:85], v[142:145], v[182:185], v[82:85]
	v_mfma_f32_16x16x32_bf16 v[78:81], v[130:133], v[170:173], v[78:81]
	v_mfma_f32_16x16x32_bf16 v[78:81], v[134:137], v[174:177], v[78:81]
	v_mfma_f32_16x16x32_bf16 v[74:77], v[138:141], v[170:173], v[74:77]
	v_mfma_f32_16x16x32_bf16 v[74:77], v[142:145], v[174:177], v[74:77]
	s_setprio 2
	s_barrier
	v_mfma_f32_16x16x32_bf16 v[70:73], v[130:133], v[162:165], v[70:73]
	v_mfma_f32_16x16x32_bf16 v[70:73], v[134:137], v[166:169], v[70:73]
	v_mfma_f32_16x16x32_bf16 v[66:69], v[138:141], v[162:165], v[66:69]
	v_mfma_f32_16x16x32_bf16 v[66:69], v[142:145], v[166:169], v[66:69]
	s_setprio 0
	s_nop 0
	ds_read_b128 v[186:189], v219 offset:16384
	ds_read_b128 v[190:193], v219 offset:17408
	ds_read_b128 v[178:181], v219 offset:18432
	ds_read_b128 v[182:185], v219 offset:19456
	ds_read_b128 v[170:173], v219 offset:20480
	ds_read_b128 v[174:177], v219 offset:21504
	ds_read_b128 v[162:165], v219 offset:22528
	ds_read_b128 v[166:169], v219 offset:23552
	s_mov_b32 m0, s74
	s_nop 0
	global_load_lds_dwordx4 v195, s[50:51]
	s_add_u32 m0, s74, 0x2000
	s_nop 0
	global_load_lds_dwordx4 v212, s[50:51]
	s_add_u32 s62, s50, 0x4000
	s_addc_u32 s63, s51, 0
	s_mov_b32 m0, s75
	s_nop 0
	global_load_lds_dwordx4 v195, s[62:63]
	s_add_u32 m0, s75, 0x2000
	s_nop 0
	global_load_lds_dwordx4 v212, s[62:63]
	s_andn2_b64 vcc, exec, s[54:55]
	s_mov_b32 m0, s73
	s_nop 0
	global_load_lds_dwordx4 v195, s[52:53]
	s_add_u32 m0, s73, 0x2000
	s_nop 0
	global_load_lds_dwordx4 v212, s[52:53]
	s_cbranch_vccnz .LBB0_366
	v_mov_b32_e32 v2, 0
	v_mov_b32_e32 v3, v2
	v_mov_b32_e32 v4, v2
	v_mov_b32_e32 v5, v2
	v_mov_b32_e32 v6, v2
	v_mov_b32_e32 v7, v2
	v_mov_b32_e32 v8, v2
	v_mov_b32_e32 v9, v2
	v_mov_b32_e32 v10, v2
	v_mov_b32_e32 v11, v2
	v_mov_b32_e32 v12, v2
	v_mov_b32_e32 v13, v2
	v_mov_b32_e32 v14, v2
	v_mov_b32_e32 v15, v2
	v_mov_b32_e32 v16, v2
	v_mov_b32_e32 v17, v2
	v_mov_b32_e32 v18, v2
	v_mov_b32_e32 v19, v2
	v_mov_b32_e32 v20, v2
	v_mov_b32_e32 v21, v2
	v_mov_b32_e32 v22, v2
	v_mov_b32_e32 v23, v2
	v_mov_b32_e32 v24, v2
	v_mov_b32_e32 v25, v2
	v_mov_b32_e32 v26, v2
	v_mov_b32_e32 v27, v2
	v_mov_b32_e32 v28, v2
	v_mov_b32_e32 v29, v2
	v_mov_b32_e32 v30, v2
	v_mov_b32_e32 v31, v2
	v_mov_b32_e32 v32, v2
	v_mov_b32_e32 v33, v2
	v_mov_b32_e32 v34, v2
	v_mov_b32_e32 v35, v2
	v_mov_b32_e32 v36, v2
	v_mov_b32_e32 v37, v2
	v_mov_b32_e32 v38, v2
	v_mov_b32_e32 v39, v2
	v_mov_b32_e32 v40, v2
	v_mov_b32_e32 v41, v2
	v_mov_b32_e32 v42, v2
	v_mov_b32_e32 v43, v2
	v_mov_b32_e32 v44, v2
	v_mov_b32_e32 v45, v2
	v_mov_b32_e32 v46, v2
	v_mov_b32_e32 v47, v2
	v_mov_b32_e32 v48, v2
	v_mov_b32_e32 v49, v2
	v_mov_b32_e32 v50, v2
	v_mov_b32_e32 v51, v2
	v_mov_b32_e32 v52, v2
	v_mov_b32_e32 v53, v2
	v_mov_b32_e32 v54, v2
	v_mov_b32_e32 v55, v2
	v_mov_b32_e32 v56, v2
	v_mov_b32_e32 v57, v2
	v_mov_b32_e32 v58, v2
	v_mov_b32_e32 v59, v2
	v_mov_b32_e32 v60, v2
	v_mov_b32_e32 v61, v2
	v_mov_b32_e32 v62, v2
	v_mov_b32_e32 v63, v2
	v_mov_b32_e32 v64, v2
	v_mov_b32_e32 v65, v2
.LBB0_366:
	s_waitcnt vmcnt(8)
	s_add_u32 s54, s52, 0x8000
	s_waitcnt lgkmcnt(0)
	s_addc_u32 s55, s53, 0
	s_add_u32 s62, s50, 0x8000
	s_addc_u32 s63, s51, 0
	s_setprio 1
	s_barrier
	v_mfma_f32_16x16x32_bf16 v[62:65], v[146:149], v[186:189], v[62:65]
	v_mfma_f32_16x16x32_bf16 v[62:65], v[150:153], v[190:193], v[62:65]
	s_waitcnt lgkmcnt(5)
	v_mfma_f32_16x16x32_bf16 v[58:61], v[154:157], v[186:189], v[58:61]
	v_mfma_f32_16x16x32_bf16 v[58:61], v[158:161], v[190:193], v[58:61]
	s_waitcnt lgkmcnt(3)
	v_mfma_f32_16x16x32_bf16 v[54:57], v[146:149], v[178:181], v[54:57]
	v_mfma_f32_16x16x32_bf16 v[54:57], v[150:153], v[182:185], v[54:57]
	s_waitcnt lgkmcnt(1)
	v_mfma_f32_16x16x32_bf16 v[50:53], v[154:157], v[178:181], v[50:53]
	v_mfma_f32_16x16x32_bf16 v[50:53], v[158:161], v[182:185], v[50:53]
	v_mfma_f32_16x16x32_bf16 v[46:49], v[146:149], v[170:173], v[46:49]
	v_mfma_f32_16x16x32_bf16 v[46:49], v[150:153], v[174:177], v[46:49]
	v_mfma_f32_16x16x32_bf16 v[42:45], v[154:157], v[170:173], v[42:45]
	v_mfma_f32_16x16x32_bf16 v[42:45], v[158:161], v[174:177], v[42:45]
	v_mfma_f32_16x16x32_bf16 v[38:41], v[146:149], v[162:165], v[38:41]
	v_mfma_f32_16x16x32_bf16 v[38:41], v[150:153], v[166:169], v[38:41]
	s_waitcnt lgkmcnt(0)
	v_mfma_f32_16x16x32_bf16 v[34:37], v[154:157], v[162:165], v[34:37]
	v_mfma_f32_16x16x32_bf16 v[34:37], v[158:161], v[166:169], v[34:37]
	s_setprio 0
	s_setprio 1
	v_mfma_f32_16x16x32_bf16 v[30:33], v[130:133], v[186:189], v[30:33]
	v_mfma_f32_16x16x32_bf16 v[30:33], v[134:137], v[190:193], v[30:33]
	v_mfma_f32_16x16x32_bf16 v[26:29], v[138:141], v[186:189], v[26:29]
	v_mfma_f32_16x16x32_bf16 v[26:29], v[142:145], v[190:193], v[26:29]
	v_mfma_f32_16x16x32_bf16 v[22:25], v[130:133], v[178:181], v[22:25]
	v_mfma_f32_16x16x32_bf16 v[22:25], v[134:137], v[182:185], v[22:25]
	v_mfma_f32_16x16x32_bf16 v[18:21], v[138:141], v[178:181], v[18:21]
	v_mfma_f32_16x16x32_bf16 v[18:21], v[142:145], v[182:185], v[18:21]
	v_mfma_f32_16x16x32_bf16 v[14:17], v[130:133], v[170:173], v[14:17]
	v_mfma_f32_16x16x32_bf16 v[14:17], v[134:137], v[174:177], v[14:17]
	v_mfma_f32_16x16x32_bf16 v[10:13], v[138:141], v[170:173], v[10:13]
	v_mfma_f32_16x16x32_bf16 v[10:13], v[142:145], v[174:177], v[10:13]
	s_setprio 2
	s_barrier
	v_mfma_f32_16x16x32_bf16 v[6:9], v[130:133], v[162:165], v[6:9]
	v_mfma_f32_16x16x32_bf16 v[6:9], v[134:137], v[166:169], v[6:9]
	v_mfma_f32_16x16x32_bf16 v[2:5], v[138:141], v[162:165], v[2:5]
	v_mfma_f32_16x16x32_bf16 v[2:5], v[142:145], v[166:169], v[2:5]
	s_setprio 0
	s_nop 0
	v_add_u32_e32 v142, 0x18000, v218
	v_add_u32_e32 v158, 0x1c000, v218
	ds_read_b128 v[130:133], v142
	ds_read_b128 v[134:137], v142 offset:1024
	ds_read_b128 v[138:141], v142 offset:2048
	ds_read_b128 v[142:145], v142 offset:3072
	ds_read_b128 v[146:149], v158
	ds_read_b128 v[150:153], v158 offset:1024
	ds_read_b128 v[154:157], v158 offset:2048
	ds_read_b128 v[158:161], v158 offset:3072
	ds_read_b128 v[162:165], v219 offset:32768
	ds_read_b128 v[166:169], v219 offset:33792
	ds_read_b128 v[170:173], v219 offset:34816
	ds_read_b128 v[174:177], v219 offset:35840
	ds_read_b128 v[178:181], v219 offset:36864
	ds_read_b128 v[182:185], v219 offset:37888
	ds_read_b128 v[186:189], v219 offset:38912
	ds_read_b128 v[190:193], v219 offset:39936
	s_add_u32 s52, s52, 0x4000
	s_addc_u32 s53, s53, 0
	s_mov_b32 m0, s76
	s_nop 0
	global_load_lds_dwordx4 v195, s[52:53]
	s_add_u32 m0, s76, 0x2000
	s_nop 0
	global_load_lds_dwordx4 v212, s[52:53]
	s_waitcnt vmcnt(8)
	s_waitcnt lgkmcnt(0)
	s_setprio 1
	s_barrier
	v_mfma_f32_16x16x32_bf16 v[126:129], v[130:133], v[162:165], v[126:129]
	v_mfma_f32_16x16x32_bf16 v[126:129], v[134:137], v[166:169], v[126:129]
	s_waitcnt lgkmcnt(5)
	v_mfma_f32_16x16x32_bf16 v[122:125], v[138:141], v[162:165], v[122:125]
	v_mfma_f32_16x16x32_bf16 v[122:125], v[142:145], v[166:169], v[122:125]
	s_waitcnt lgkmcnt(3)
	v_mfma_f32_16x16x32_bf16 v[118:121], v[130:133], v[170:173], v[118:121]
	v_mfma_f32_16x16x32_bf16 v[118:121], v[134:137], v[174:177], v[118:121]
	s_waitcnt lgkmcnt(1)
	v_mfma_f32_16x16x32_bf16 v[114:117], v[138:141], v[170:173], v[114:117]
	v_mfma_f32_16x16x32_bf16 v[114:117], v[142:145], v[174:177], v[114:117]
	v_mfma_f32_16x16x32_bf16 v[110:113], v[130:133], v[178:181], v[110:113]
	v_mfma_f32_16x16x32_bf16 v[110:113], v[134:137], v[182:185], v[110:113]
	v_mfma_f32_16x16x32_bf16 v[106:109], v[138:141], v[178:181], v[106:109]
	v_mfma_f32_16x16x32_bf16 v[106:109], v[142:145], v[182:185], v[106:109]
	v_mfma_f32_16x16x32_bf16 v[102:105], v[130:133], v[186:189], v[102:105]
	v_mfma_f32_16x16x32_bf16 v[102:105], v[134:137], v[190:193], v[102:105]
	s_waitcnt lgkmcnt(0)
	v_mfma_f32_16x16x32_bf16 v[98:101], v[138:141], v[186:189], v[98:101]
	v_mfma_f32_16x16x32_bf16 v[98:101], v[142:145], v[190:193], v[98:101]
	s_setprio 0
	s_setprio 1
	v_mfma_f32_16x16x32_bf16 v[94:97], v[146:149], v[162:165], v[94:97]
	v_mfma_f32_16x16x32_bf16 v[94:97], v[150:153], v[166:169], v[94:97]
	v_mfma_f32_16x16x32_bf16 v[90:93], v[154:157], v[162:165], v[90:93]
	v_mfma_f32_16x16x32_bf16 v[90:93], v[158:161], v[166:169], v[90:93]
	v_mfma_f32_16x16x32_bf16 v[86:89], v[146:149], v[170:173], v[86:89]
	v_mfma_f32_16x16x32_bf16 v[86:89], v[150:153], v[174:177], v[86:89]
	v_mfma_f32_16x16x32_bf16 v[82:85], v[154:157], v[170:173], v[82:85]
	v_mfma_f32_16x16x32_bf16 v[82:85], v[158:161], v[174:177], v[82:85]
	v_mfma_f32_16x16x32_bf16 v[78:81], v[146:149], v[178:181], v[78:81]
	v_mfma_f32_16x16x32_bf16 v[78:81], v[150:153], v[182:185], v[78:81]
	v_mfma_f32_16x16x32_bf16 v[74:77], v[154:157], v[178:181], v[74:77]
	v_mfma_f32_16x16x32_bf16 v[74:77], v[158:161], v[182:185], v[74:77]
	s_setprio 2
	s_barrier
	v_mfma_f32_16x16x32_bf16 v[70:73], v[146:149], v[186:189], v[70:73]
	v_mfma_f32_16x16x32_bf16 v[70:73], v[150:153], v[190:193], v[70:73]
	v_mfma_f32_16x16x32_bf16 v[66:69], v[154:157], v[186:189], v[66:69]
	v_mfma_f32_16x16x32_bf16 v[66:69], v[158:161], v[190:193], v[66:69]
	s_setprio 0
	s_nop 0
	ds_read_b128 v[162:165], v219 offset:49152
	ds_read_b128 v[166:169], v219 offset:50176
	ds_read_b128 v[170:173], v219 offset:51200
	ds_read_b128 v[174:177], v219 offset:52224
	ds_read_b128 v[178:181], v219 offset:53248
	ds_read_b128 v[182:185], v219 offset:54272
	ds_read_b128 v[186:189], v219 offset:55296
	ds_read_b128 v[190:193], v219 offset:56320
	s_mov_b32 m0, s80
	s_nop 0
	global_load_lds_dwordx4 v195, s[62:63]
	s_add_u32 m0, s80, 0x2000
	s_nop 0
	global_load_lds_dwordx4 v212, s[62:63]
	s_add_u32 s50, s50, 0xc000
	s_addc_u32 s51, s51, 0
	s_mov_b32 m0, s82
	s_nop 0
	global_load_lds_dwordx4 v195, s[50:51]
	s_add_u32 m0, s82, 0x2000
	s_nop 0
	global_load_lds_dwordx4 v212, s[50:51]
	s_nop 0
	s_mov_b32 m0, s81
	s_nop 0
	global_load_lds_dwordx4 v195, s[54:55]
	s_add_u32 m0, s81, 0x2000
	s_nop 0
	global_load_lds_dwordx4 v212, s[54:55]
	s_waitcnt vmcnt(8)
	s_waitcnt lgkmcnt(0)
	s_setprio 1
	s_barrier
	v_mfma_f32_16x16x32_bf16 v[62:65], v[130:133], v[162:165], v[62:65]
	v_mfma_f32_16x16x32_bf16 v[62:65], v[134:137], v[166:169], v[62:65]
	s_waitcnt lgkmcnt(5)
	v_mfma_f32_16x16x32_bf16 v[58:61], v[138:141], v[162:165], v[58:61]
	v_mfma_f32_16x16x32_bf16 v[58:61], v[142:145], v[166:169], v[58:61]
	s_waitcnt lgkmcnt(3)
	v_mfma_f32_16x16x32_bf16 v[54:57], v[130:133], v[170:173], v[54:57]
	v_mfma_f32_16x16x32_bf16 v[54:57], v[134:137], v[174:177], v[54:57]
	s_waitcnt lgkmcnt(1)
	v_mfma_f32_16x16x32_bf16 v[50:53], v[138:141], v[170:173], v[50:53]
	v_mfma_f32_16x16x32_bf16 v[50:53], v[142:145], v[174:177], v[50:53]
	v_mfma_f32_16x16x32_bf16 v[46:49], v[130:133], v[178:181], v[46:49]
	v_mfma_f32_16x16x32_bf16 v[46:49], v[134:137], v[182:185], v[46:49]
	v_mfma_f32_16x16x32_bf16 v[42:45], v[138:141], v[178:181], v[42:45]
	v_mfma_f32_16x16x32_bf16 v[42:45], v[142:145], v[182:185], v[42:45]
	v_mfma_f32_16x16x32_bf16 v[38:41], v[130:133], v[186:189], v[38:41]
	v_mfma_f32_16x16x32_bf16 v[38:41], v[134:137], v[190:193], v[38:41]
	s_waitcnt lgkmcnt(0)
	v_mfma_f32_16x16x32_bf16 v[34:37], v[138:141], v[186:189], v[34:37]
	v_mfma_f32_16x16x32_bf16 v[34:37], v[142:145], v[190:193], v[34:37]
	s_setprio 0
	s_setprio 1
	v_mfma_f32_16x16x32_bf16 v[30:33], v[146:149], v[162:165], v[30:33]
	v_mfma_f32_16x16x32_bf16 v[30:33], v[150:153], v[166:169], v[30:33]
	v_mfma_f32_16x16x32_bf16 v[26:29], v[154:157], v[162:165], v[26:29]
	v_mfma_f32_16x16x32_bf16 v[26:29], v[158:161], v[166:169], v[26:29]
	v_mfma_f32_16x16x32_bf16 v[22:25], v[146:149], v[170:173], v[22:25]
	v_mfma_f32_16x16x32_bf16 v[22:25], v[150:153], v[174:177], v[22:25]
	v_mfma_f32_16x16x32_bf16 v[18:21], v[154:157], v[170:173], v[18:21]
	v_mfma_f32_16x16x32_bf16 v[18:21], v[158:161], v[174:177], v[18:21]
	v_mfma_f32_16x16x32_bf16 v[14:17], v[146:149], v[178:181], v[14:17]
	v_mfma_f32_16x16x32_bf16 v[14:17], v[150:153], v[182:185], v[14:17]
	v_mfma_f32_16x16x32_bf16 v[10:13], v[154:157], v[178:181], v[10:13]
	v_mfma_f32_16x16x32_bf16 v[10:13], v[158:161], v[182:185], v[10:13]
	s_setprio 2
	s_barrier
	v_mfma_f32_16x16x32_bf16 v[6:9], v[146:149], v[186:189], v[6:9]
	v_mfma_f32_16x16x32_bf16 v[6:9], v[150:153], v[190:193], v[6:9]
	v_mfma_f32_16x16x32_bf16 v[2:5], v[154:157], v[186:189], v[2:5]
	v_mfma_f32_16x16x32_bf16 v[2:5], v[158:161], v[190:193], v[2:5]
	s_setprio 0
	s_nop 0
	s_cmp_gt_u32 s93, 41
	s_cbranch_scc1 .LBB0_368
	v_mov_b32_e32 v130, v198
	s_mov_b32 s93, s26
	s_branch .LBB0_343

.LBB0_519:
	ds_read_b128 v[130:133], v141
	ds_read_b128 v[134:137], v141 offset:1024
	ds_read_b128 v[146:149], v141 offset:2048
	ds_read_b128 v[150:153], v141 offset:3072
	ds_read_b128 v[154:157], v142
	ds_read_b128 v[158:161], v142 offset:1024
	ds_read_b128 v[162:165], v142 offset:2048
	ds_read_b128 v[166:169], v142 offset:3072
	s_add_u32 s24, s26, 0x10000
	s_addc_u32 s25, s27, 0
	s_cmp_eq_u32 s77, 12
	s_cselect_b32 s48, s17, s24
	s_cselect_b32 s49, s1, s25
	s_cselect_b32 s30, s23, s75
	s_cselect_b32 s31, s15, s76
	s_add_u32 s28, s48, 0x8000
	s_addc_u32 s29, s49, 0
	ds_read_b128 v[170:173], v143
	ds_read_b128 v[174:177], v143 offset:1024
	ds_read_b128 v[178:181], v143 offset:2048
	ds_read_b128 v[182:185], v143 offset:3072
	ds_read_b128 v[186:189], v143 offset:4096
	ds_read_b128 v[190:193], v143 offset:5120
	ds_read_b128 v[198:201], v143 offset:6144
	ds_read_b128 v[202:205], v143 offset:7168
	s_add_u32 s38, s30, 0x8000
	s_addc_u32 s39, s31, 0
	s_add_u32 s26, s26, 0xc000
	s_addc_u32 s27, s27, 0
	s_mov_b32 m0, s72
	s_nop 0
	global_load_lds_dwordx4 v195, s[26:27]
	s_add_u32 m0, s72, 0x2000
	s_nop 0
	global_load_lds_dwordx4 v212, s[26:27]
	s_waitcnt vmcnt(8)
	s_waitcnt lgkmcnt(0)
	s_setprio 1
	s_barrier
	v_mfma_f32_16x16x32_bf16 v[122:125], v[130:133], v[170:173], v[122:125]
	v_mfma_f32_16x16x32_bf16 v[122:125], v[134:137], v[174:177], v[122:125]
	s_waitcnt lgkmcnt(5)
	v_mfma_f32_16x16x32_bf16 v[126:129], v[146:149], v[170:173], v[126:129]
	v_mfma_f32_16x16x32_bf16 v[126:129], v[150:153], v[174:177], v[126:129]
	s_waitcnt lgkmcnt(3)
	v_mfma_f32_16x16x32_bf16 v[110:113], v[130:133], v[178:181], v[110:113]
	v_mfma_f32_16x16x32_bf16 v[110:113], v[134:137], v[182:185], v[110:113]
	s_waitcnt lgkmcnt(1)
	v_mfma_f32_16x16x32_bf16 v[106:109], v[146:149], v[178:181], v[106:109]
	v_mfma_f32_16x16x32_bf16 v[106:109], v[150:153], v[182:185], v[106:109]
	v_mfma_f32_16x16x32_bf16 v[94:97], v[130:133], v[186:189], v[94:97]
	v_mfma_f32_16x16x32_bf16 v[94:97], v[134:137], v[190:193], v[94:97]
	v_mfma_f32_16x16x32_bf16 v[90:93], v[146:149], v[186:189], v[90:93]
	v_mfma_f32_16x16x32_bf16 v[90:93], v[150:153], v[190:193], v[90:93]
	v_mfma_f32_16x16x32_bf16 v[78:81], v[130:133], v[198:201], v[78:81]
	v_mfma_f32_16x16x32_bf16 v[78:81], v[134:137], v[202:205], v[78:81]
	s_waitcnt lgkmcnt(0)
	v_mfma_f32_16x16x32_bf16 v[74:77], v[146:149], v[198:201], v[74:77]
	v_mfma_f32_16x16x32_bf16 v[74:77], v[150:153], v[202:205], v[74:77]
	s_setprio 0
	s_setprio 1
	v_mfma_f32_16x16x32_bf16 v[114:117], v[154:157], v[170:173], v[114:117]
	v_mfma_f32_16x16x32_bf16 v[114:117], v[158:161], v[174:177], v[114:117]
	v_mfma_f32_16x16x32_bf16 v[118:121], v[162:165], v[170:173], v[118:121]
	v_mfma_f32_16x16x32_bf16 v[118:121], v[166:169], v[174:177], v[118:121]
	v_mfma_f32_16x16x32_bf16 v[98:101], v[154:157], v[178:181], v[98:101]
	v_mfma_f32_16x16x32_bf16 v[98:101], v[158:161], v[182:185], v[98:101]
	v_mfma_f32_16x16x32_bf16 v[102:105], v[162:165], v[178:181], v[102:105]
	v_mfma_f32_16x16x32_bf16 v[102:105], v[166:169], v[182:185], v[102:105]
	v_mfma_f32_16x16x32_bf16 v[82:85], v[154:157], v[186:189], v[82:85]
	v_mfma_f32_16x16x32_bf16 v[82:85], v[158:161], v[190:193], v[82:85]
	v_mfma_f32_16x16x32_bf16 v[86:89], v[162:165], v[186:189], v[86:89]
	v_mfma_f32_16x16x32_bf16 v[86:89], v[166:169], v[190:193], v[86:89]
	s_setprio 2
	s_barrier
	v_mfma_f32_16x16x32_bf16 v[66:69], v[154:157], v[198:201], v[66:69]
	v_mfma_f32_16x16x32_bf16 v[66:69], v[158:161], v[202:205], v[66:69]
	v_mfma_f32_16x16x32_bf16 v[70:73], v[162:165], v[198:201], v[70:73]
	v_mfma_f32_16x16x32_bf16 v[70:73], v[166:169], v[202:205], v[70:73]
	s_setprio 0
	s_nop 0
	ds_read_b128 v[170:173], v143 offset:16384
	ds_read_b128 v[174:177], v143 offset:17408
	ds_read_b128 v[178:181], v143 offset:18432
	ds_read_b128 v[182:185], v143 offset:19456
	ds_read_b128 v[186:189], v143 offset:20480
	ds_read_b128 v[190:193], v143 offset:21504
	ds_read_b128 v[198:201], v143 offset:22528
	ds_read_b128 v[202:205], v143 offset:23552
	s_mov_b32 m0, s55
	s_nop 0
	global_load_lds_dwordx4 v195, s[30:31]
	s_add_u32 m0, s55, 0x2000
	s_nop 0
	global_load_lds_dwordx4 v212, s[30:31]
	s_add_u32 s26, s30, 0x4000
	s_addc_u32 s27, s31, 0
	s_mov_b32 m0, s62
	s_nop 0
	global_load_lds_dwordx4 v195, s[26:27]
	s_add_u32 m0, s62, 0x2000
	s_nop 0
	global_load_lds_dwordx4 v212, s[26:27]
	s_nop 0
	s_mov_b32 m0, s54
	s_nop 0
	global_load_lds_dwordx4 v195, s[48:49]
	s_add_u32 m0, s54, 0x2000
	s_nop 0
	global_load_lds_dwordx4 v212, s[48:49]
	s_waitcnt vmcnt(8)
	s_waitcnt lgkmcnt(0)
	s_setprio 1
	s_barrier
	v_mfma_f32_16x16x32_bf16 v[62:65], v[130:133], v[170:173], v[62:65]
	v_mfma_f32_16x16x32_bf16 v[62:65], v[134:137], v[174:177], v[62:65]
	s_waitcnt lgkmcnt(5)
	v_mfma_f32_16x16x32_bf16 v[58:61], v[146:149], v[170:173], v[58:61]
	v_mfma_f32_16x16x32_bf16 v[58:61], v[150:153], v[174:177], v[58:61]
	s_waitcnt lgkmcnt(3)
	v_mfma_f32_16x16x32_bf16 v[46:49], v[130:133], v[178:181], v[46:49]
	v_mfma_f32_16x16x32_bf16 v[46:49], v[134:137], v[182:185], v[46:49]
	s_waitcnt lgkmcnt(1)
	v_mfma_f32_16x16x32_bf16 v[42:45], v[146:149], v[178:181], v[42:45]
	v_mfma_f32_16x16x32_bf16 v[42:45], v[150:153], v[182:185], v[42:45]
	v_mfma_f32_16x16x32_bf16 v[30:33], v[130:133], v[186:189], v[30:33]
	v_mfma_f32_16x16x32_bf16 v[30:33], v[134:137], v[190:193], v[30:33]
	v_mfma_f32_16x16x32_bf16 v[26:29], v[146:149], v[186:189], v[26:29]
	v_mfma_f32_16x16x32_bf16 v[26:29], v[150:153], v[190:193], v[26:29]
	v_mfma_f32_16x16x32_bf16 v[14:17], v[130:133], v[198:201], v[14:17]
	v_mfma_f32_16x16x32_bf16 v[14:17], v[134:137], v[202:205], v[14:17]
	s_waitcnt lgkmcnt(0)
	v_mfma_f32_16x16x32_bf16 v[10:13], v[146:149], v[198:201], v[10:13]
	v_mfma_f32_16x16x32_bf16 v[10:13], v[150:153], v[202:205], v[10:13]
	s_setprio 0
	s_setprio 1
	v_mfma_f32_16x16x32_bf16 v[50:53], v[154:157], v[170:173], v[50:53]
	v_mfma_f32_16x16x32_bf16 v[50:53], v[158:161], v[174:177], v[50:53]
	v_mfma_f32_16x16x32_bf16 v[54:57], v[162:165], v[170:173], v[54:57]
	v_mfma_f32_16x16x32_bf16 v[54:57], v[166:169], v[174:177], v[54:57]
	v_mfma_f32_16x16x32_bf16 v[34:37], v[154:157], v[178:181], v[34:37]
	v_mfma_f32_16x16x32_bf16 v[34:37], v[158:161], v[182:185], v[34:37]
	v_mfma_f32_16x16x32_bf16 v[38:41], v[162:165], v[178:181], v[38:41]
	v_mfma_f32_16x16x32_bf16 v[38:41], v[166:169], v[182:185], v[38:41]
	v_mfma_f32_16x16x32_bf16 v[18:21], v[154:157], v[186:189], v[18:21]
	v_mfma_f32_16x16x32_bf16 v[18:21], v[158:161], v[190:193], v[18:21]
	v_mfma_f32_16x16x32_bf16 v[22:25], v[162:165], v[186:189], v[22:25]
	v_mfma_f32_16x16x32_bf16 v[22:25], v[166:169], v[190:193], v[22:25]
	s_setprio 2
	s_barrier
	v_mfma_f32_16x16x32_bf16 v[2:5], v[154:157], v[198:201], v[2:5]
	v_mfma_f32_16x16x32_bf16 v[2:5], v[158:161], v[202:205], v[2:5]
	v_mfma_f32_16x16x32_bf16 v[6:9], v[162:165], v[198:201], v[6:9]
	v_mfma_f32_16x16x32_bf16 v[6:9], v[166:169], v[202:205], v[6:9]
	s_setprio 0
	s_nop 0
	ds_read_b128 v[130:133], v144
	ds_read_b128 v[134:137], v144 offset:1024
	ds_read_b128 v[146:149], v144 offset:2048
	ds_read_b128 v[150:153], v144 offset:3072
	ds_read_b128 v[154:157], v145
	ds_read_b128 v[158:161], v145 offset:1024
	ds_read_b128 v[162:165], v145 offset:2048
	ds_read_b128 v[166:169], v145 offset:3072
	ds_read_b128 v[170:173], v143 offset:32768
	ds_read_b128 v[174:177], v143 offset:33792
	ds_read_b128 v[178:181], v143 offset:34816
	ds_read_b128 v[182:185], v143 offset:35840
	ds_read_b128 v[186:189], v143 offset:36864
	ds_read_b128 v[190:193], v143 offset:37888
	ds_read_b128 v[198:201], v143 offset:38912
	ds_read_b128 v[202:205], v143 offset:39936
	s_add_u32 s26, s48, 0x4000
	s_addc_u32 s27, s49, 0
	s_mov_b32 m0, s63
	s_nop 0
	global_load_lds_dwordx4 v195, s[26:27]
	s_add_u32 m0, s63, 0x2000
	s_nop 0
	global_load_lds_dwordx4 v212, s[26:27]
	s_waitcnt vmcnt(8)
	s_waitcnt lgkmcnt(0)
	s_setprio 1
	s_barrier
	v_mfma_f32_16x16x32_bf16 v[122:125], v[130:133], v[170:173], v[122:125]
	v_mfma_f32_16x16x32_bf16 v[122:125], v[134:137], v[174:177], v[122:125]
	s_waitcnt lgkmcnt(5)
	v_mfma_f32_16x16x32_bf16 v[126:129], v[146:149], v[170:173], v[126:129]
	v_mfma_f32_16x16x32_bf16 v[126:129], v[150:153], v[174:177], v[126:129]
	s_waitcnt lgkmcnt(3)
	v_mfma_f32_16x16x32_bf16 v[110:113], v[130:133], v[178:181], v[110:113]
	v_mfma_f32_16x16x32_bf16 v[110:113], v[134:137], v[182:185], v[110:113]
	s_waitcnt lgkmcnt(1)
	v_mfma_f32_16x16x32_bf16 v[106:109], v[146:149], v[178:181], v[106:109]
	v_mfma_f32_16x16x32_bf16 v[106:109], v[150:153], v[182:185], v[106:109]
	v_mfma_f32_16x16x32_bf16 v[94:97], v[130:133], v[186:189], v[94:97]
	v_mfma_f32_16x16x32_bf16 v[94:97], v[134:137], v[190:193], v[94:97]
	v_mfma_f32_16x16x32_bf16 v[90:93], v[146:149], v[186:189], v[90:93]
	v_mfma_f32_16x16x32_bf16 v[90:93], v[150:153], v[190:193], v[90:93]
	v_mfma_f32_16x16x32_bf16 v[78:81], v[130:133], v[198:201], v[78:81]
	v_mfma_f32_16x16x32_bf16 v[78:81], v[134:137], v[202:205], v[78:81]
	s_waitcnt lgkmcnt(0)
	v_mfma_f32_16x16x32_bf16 v[74:77], v[146:149], v[198:201], v[74:77]
	v_mfma_f32_16x16x32_bf16 v[74:77], v[150:153], v[202:205], v[74:77]
	s_setprio 0
	s_setprio 1
	v_mfma_f32_16x16x32_bf16 v[114:117], v[154:157], v[170:173], v[114:117]
	v_mfma_f32_16x16x32_bf16 v[114:117], v[158:161], v[174:177], v[114:117]
	v_mfma_f32_16x16x32_bf16 v[118:121], v[162:165], v[170:173], v[118:121]
	v_mfma_f32_16x16x32_bf16 v[118:121], v[166:169], v[174:177], v[118:121]
	v_mfma_f32_16x16x32_bf16 v[98:101], v[154:157], v[178:181], v[98:101]
	v_mfma_f32_16x16x32_bf16 v[98:101], v[158:161], v[182:185], v[98:101]
	v_mfma_f32_16x16x32_bf16 v[102:105], v[162:165], v[178:181], v[102:105]
	v_mfma_f32_16x16x32_bf16 v[102:105], v[166:169], v[182:185], v[102:105]
	v_mfma_f32_16x16x32_bf16 v[82:85], v[154:157], v[186:189], v[82:85]
	v_mfma_f32_16x16x32_bf16 v[82:85], v[158:161], v[190:193], v[82:85]
	v_mfma_f32_16x16x32_bf16 v[86:89], v[162:165], v[186:189], v[86:89]
	v_mfma_f32_16x16x32_bf16 v[86:89], v[166:169], v[190:193], v[86:89]
	s_setprio 2
	s_barrier
	v_mfma_f32_16x16x32_bf16 v[66:69], v[154:157], v[198:201], v[66:69]
	v_mfma_f32_16x16x32_bf16 v[66:69], v[158:161], v[202:205], v[66:69]
	v_mfma_f32_16x16x32_bf16 v[70:73], v[162:165], v[198:201], v[70:73]
	v_mfma_f32_16x16x32_bf16 v[70:73], v[166:169], v[202:205], v[70:73]
	s_setprio 0
	s_nop 0
	ds_read_b128 v[170:173], v143 offset:49152
	ds_read_b128 v[174:177], v143 offset:50176
	ds_read_b128 v[178:181], v143 offset:51200
	ds_read_b128 v[182:185], v143 offset:52224
	ds_read_b128 v[186:189], v143 offset:53248
	ds_read_b128 v[190:193], v143 offset:54272
	ds_read_b128 v[198:201], v143 offset:55296
	ds_read_b128 v[202:205], v143 offset:56320
	s_mov_b32 m0, s69
	s_nop 0
	global_load_lds_dwordx4 v195, s[38:39]
	s_add_u32 m0, s69, 0x2000
	s_nop 0
	global_load_lds_dwordx4 v212, s[38:39]
	s_add_u32 s26, s30, 0xc000
	s_addc_u32 s27, s31, 0
	s_mov_b32 m0, s71
	s_nop 0
	global_load_lds_dwordx4 v195, s[26:27]
	s_add_u32 m0, s71, 0x2000
	s_nop 0
	global_load_lds_dwordx4 v212, s[26:27]
	s_nop 0
	s_mov_b32 m0, s70
	s_nop 0
	global_load_lds_dwordx4 v195, s[28:29]
	s_add_u32 m0, s70, 0x2000
	s_nop 0
	global_load_lds_dwordx4 v212, s[28:29]
	s_waitcnt vmcnt(8)
	s_waitcnt lgkmcnt(0)
	s_setprio 1
	s_barrier
	v_mfma_f32_16x16x32_bf16 v[62:65], v[130:133], v[170:173], v[62:65]
	v_mfma_f32_16x16x32_bf16 v[62:65], v[134:137], v[174:177], v[62:65]
	s_waitcnt lgkmcnt(5)
	v_mfma_f32_16x16x32_bf16 v[58:61], v[146:149], v[170:173], v[58:61]
	v_mfma_f32_16x16x32_bf16 v[58:61], v[150:153], v[174:177], v[58:61]
	s_waitcnt lgkmcnt(3)
	v_mfma_f32_16x16x32_bf16 v[46:49], v[130:133], v[178:181], v[46:49]
	v_mfma_f32_16x16x32_bf16 v[46:49], v[134:137], v[182:185], v[46:49]
	s_waitcnt lgkmcnt(1)
	v_mfma_f32_16x16x32_bf16 v[42:45], v[146:149], v[178:181], v[42:45]
	v_mfma_f32_16x16x32_bf16 v[42:45], v[150:153], v[182:185], v[42:45]
	v_mfma_f32_16x16x32_bf16 v[30:33], v[130:133], v[186:189], v[30:33]
	v_mfma_f32_16x16x32_bf16 v[30:33], v[134:137], v[190:193], v[30:33]
	v_mfma_f32_16x16x32_bf16 v[26:29], v[146:149], v[186:189], v[26:29]
	v_mfma_f32_16x16x32_bf16 v[26:29], v[150:153], v[190:193], v[26:29]
	v_mfma_f32_16x16x32_bf16 v[14:17], v[130:133], v[198:201], v[14:17]
	v_mfma_f32_16x16x32_bf16 v[14:17], v[134:137], v[202:205], v[14:17]
	s_waitcnt lgkmcnt(0)
	v_mfma_f32_16x16x32_bf16 v[10:13], v[146:149], v[198:201], v[10:13]
	v_mfma_f32_16x16x32_bf16 v[10:13], v[150:153], v[202:205], v[10:13]
	s_setprio 0
	s_setprio 1
	v_mfma_f32_16x16x32_bf16 v[50:53], v[154:157], v[170:173], v[50:53]
	v_mfma_f32_16x16x32_bf16 v[50:53], v[158:161], v[174:177], v[50:53]
	v_mfma_f32_16x16x32_bf16 v[54:57], v[162:165], v[170:173], v[54:57]
	v_mfma_f32_16x16x32_bf16 v[54:57], v[166:169], v[174:177], v[54:57]
	v_mfma_f32_16x16x32_bf16 v[34:37], v[154:157], v[178:181], v[34:37]
	v_mfma_f32_16x16x32_bf16 v[34:37], v[158:161], v[182:185], v[34:37]
	v_mfma_f32_16x16x32_bf16 v[38:41], v[162:165], v[178:181], v[38:41]
	v_mfma_f32_16x16x32_bf16 v[38:41], v[166:169], v[182:185], v[38:41]
	v_mfma_f32_16x16x32_bf16 v[18:21], v[154:157], v[186:189], v[18:21]
	v_mfma_f32_16x16x32_bf16 v[18:21], v[158:161], v[190:193], v[18:21]
	v_mfma_f32_16x16x32_bf16 v[22:25], v[162:165], v[186:189], v[22:25]
	v_mfma_f32_16x16x32_bf16 v[22:25], v[166:169], v[190:193], v[22:25]
	s_setprio 2
	s_barrier
	v_mfma_f32_16x16x32_bf16 v[2:5], v[154:157], v[198:201], v[2:5]
	v_mfma_f32_16x16x32_bf16 v[2:5], v[158:161], v[202:205], v[2:5]
	v_mfma_f32_16x16x32_bf16 v[6:9], v[162:165], v[198:201], v[6:9]
	v_mfma_f32_16x16x32_bf16 v[6:9], v[166:169], v[202:205], v[6:9]
	s_setprio 0
	s_nop 0
	s_add_i32 s77, s77, 2
	s_add_u32 s75, s75, 0x10000
	s_addc_u32 s76, s76, 0
	s_cmp_gt_u32 s77, 13
	s_mov_b64 s[26:27], s[24:25]
	s_cbranch_scc0 .LBB0_519
	s_and_b64 vcc, exec, s[10:11]
	s_cbranch_vccz .LBB0_522
	s_barrier
	s_setprio 1

.LBB0_635:
	s_add_u32 s28, s24, 0x10000
	s_addc_u32 s29, s25, 0
	s_and_b64 s[24:25], s[22:23], exec
	s_cselect_b32 s25, s29, s15
	s_cselect_b32 s24, s28, s33
	s_add_u32 s3, s52, s3
	s_addc_u32 s28, s53, 0
	s_add_u32 s3, s3, 0x10000
	s_waitcnt vmcnt(8)
	s_addc_u32 s28, s28, 0
	s_waitcnt lgkmcnt(0)
	s_and_b64 s[22:23], s[22:23], exec
	s_cselect_b32 s23, s28, s13
	s_cselect_b32 s22, s3, s70
	s_setprio 1
	s_barrier
	v_mfma_f32_16x16x32_bf16 v[126:129], v[146:149], v[186:189], v[126:129]
	v_mfma_f32_16x16x32_bf16 v[126:129], v[150:153], v[190:193], v[126:129]
	s_waitcnt lgkmcnt(5)
	v_mfma_f32_16x16x32_bf16 v[122:125], v[154:157], v[186:189], v[122:125]
	v_mfma_f32_16x16x32_bf16 v[122:125], v[158:161], v[190:193], v[122:125]
	s_waitcnt lgkmcnt(3)
	v_mfma_f32_16x16x32_bf16 v[118:121], v[146:149], v[178:181], v[118:121]
	v_mfma_f32_16x16x32_bf16 v[118:121], v[150:153], v[182:185], v[118:121]
	s_waitcnt lgkmcnt(1)
	v_mfma_f32_16x16x32_bf16 v[114:117], v[154:157], v[178:181], v[114:117]
	v_mfma_f32_16x16x32_bf16 v[114:117], v[158:161], v[182:185], v[114:117]
	v_mfma_f32_16x16x32_bf16 v[110:113], v[146:149], v[170:173], v[110:113]
	v_mfma_f32_16x16x32_bf16 v[110:113], v[150:153], v[174:177], v[110:113]
	v_mfma_f32_16x16x32_bf16 v[106:109], v[154:157], v[170:173], v[106:109]
	v_mfma_f32_16x16x32_bf16 v[106:109], v[158:161], v[174:177], v[106:109]
	v_mfma_f32_16x16x32_bf16 v[102:105], v[146:149], v[162:165], v[102:105]
	v_mfma_f32_16x16x32_bf16 v[102:105], v[150:153], v[166:169], v[102:105]
	s_waitcnt lgkmcnt(0)
	v_mfma_f32_16x16x32_bf16 v[98:101], v[154:157], v[162:165], v[98:101]
	v_mfma_f32_16x16x32_bf16 v[98:101], v[158:161], v[166:169], v[98:101]
	s_setprio 0
	s_setprio 1
	v_mfma_f32_16x16x32_bf16 v[94:97], v[130:133], v[186:189], v[94:97]
	v_mfma_f32_16x16x32_bf16 v[94:97], v[134:137], v[190:193], v[94:97]
	v_mfma_f32_16x16x32_bf16 v[90:93], v[138:141], v[186:189], v[90:93]
	v_mfma_f32_16x16x32_bf16 v[90:93], v[142:145], v[190:193], v[90:93]
	v_mfma_f32_16x16x32_bf16 v[86:89], v[130:133], v[178:181], v[86:89]
	v_mfma_f32_16x16x32_bf16 v[86:89], v[134:137], v[182:185], v[86:89]
	v_mfma_f32_16x16x32_bf16 v[82:85], v[138:141], v[178:181], v[82:85]
	v_mfma_f32_16x16x32_bf16 v[82:85], v[142:145], v[182:185], v[82:85]
	v_mfma_f32_16x16x32_bf16 v[78:81], v[130:133], v[170:173], v[78:81]
	v_mfma_f32_16x16x32_bf16 v[78:81], v[134:137], v[174:177], v[78:81]
	v_mfma_f32_16x16x32_bf16 v[74:77], v[138:141], v[170:173], v[74:77]
	v_mfma_f32_16x16x32_bf16 v[74:77], v[142:145], v[174:177], v[74:77]
	s_setprio 2
	s_barrier
	v_mfma_f32_16x16x32_bf16 v[70:73], v[130:133], v[162:165], v[70:73]
	v_mfma_f32_16x16x32_bf16 v[70:73], v[134:137], v[166:169], v[70:73]
	v_mfma_f32_16x16x32_bf16 v[66:69], v[138:141], v[162:165], v[66:69]
	v_mfma_f32_16x16x32_bf16 v[66:69], v[142:145], v[166:169], v[66:69]
	s_setprio 0
	s_nop 0
	ds_read_b128 v[186:189], v219 offset:16384
	ds_read_b128 v[190:193], v219 offset:17408
	ds_read_b128 v[178:181], v219 offset:18432
	ds_read_b128 v[182:185], v219 offset:19456
	ds_read_b128 v[170:173], v219 offset:20480
	ds_read_b128 v[174:177], v219 offset:21504
	ds_read_b128 v[162:165], v219 offset:22528
	ds_read_b128 v[166:169], v219 offset:23552
	s_mov_b32 m0, s89
	s_nop 0
	global_load_lds_dwordx4 v195, s[22:23]
	s_add_u32 m0, s89, 0x2000
	s_nop 0
	global_load_lds_dwordx4 v213, s[22:23]
	s_add_u32 s28, s22, 0x4000
	s_addc_u32 s29, s23, 0
	s_mov_b32 m0, s54
	s_nop 0
	global_load_lds_dwordx4 v195, s[28:29]
	s_add_u32 m0, s54, 0x2000
	s_nop 0
	global_load_lds_dwordx4 v213, s[28:29]
	s_andn2_b64 vcc, exec, s[26:27]
	s_mov_b32 m0, s39
	s_nop 0
	global_load_lds_dwordx4 v195, s[24:25]
	s_add_u32 m0, s39, 0x2000
	s_nop 0
	global_load_lds_dwordx4 v213, s[24:25]
	s_cbranch_vccnz .LBB0_637
	v_mov_b32_e32 v2, 0
	v_mov_b32_e32 v3, v2
	v_mov_b32_e32 v4, v2
	v_mov_b32_e32 v5, v2
	v_mov_b32_e32 v6, v2
	v_mov_b32_e32 v7, v2
	v_mov_b32_e32 v8, v2
	v_mov_b32_e32 v9, v2
	v_mov_b32_e32 v10, v2
	v_mov_b32_e32 v11, v2
	v_mov_b32_e32 v12, v2
	v_mov_b32_e32 v13, v2
	v_mov_b32_e32 v14, v2
	v_mov_b32_e32 v15, v2
	v_mov_b32_e32 v16, v2
	v_mov_b32_e32 v17, v2
	v_mov_b32_e32 v18, v2
	v_mov_b32_e32 v19, v2
	v_mov_b32_e32 v20, v2
	v_mov_b32_e32 v21, v2
	v_mov_b32_e32 v22, v2
	v_mov_b32_e32 v23, v2
	v_mov_b32_e32 v24, v2
	v_mov_b32_e32 v25, v2
	v_mov_b32_e32 v26, v2
	v_mov_b32_e32 v27, v2
	v_mov_b32_e32 v28, v2
	v_mov_b32_e32 v29, v2
	v_mov_b32_e32 v30, v2
	v_mov_b32_e32 v31, v2
	v_mov_b32_e32 v32, v2
	v_mov_b32_e32 v33, v2
	v_mov_b32_e32 v34, v2
	v_mov_b32_e32 v35, v2
	v_mov_b32_e32 v36, v2
	v_mov_b32_e32 v37, v2
	v_mov_b32_e32 v38, v2
	v_mov_b32_e32 v39, v2
	v_mov_b32_e32 v40, v2
	v_mov_b32_e32 v41, v2
	v_mov_b32_e32 v42, v2
	v_mov_b32_e32 v43, v2
	v_mov_b32_e32 v44, v2
	v_mov_b32_e32 v45, v2
	v_mov_b32_e32 v46, v2
	v_mov_b32_e32 v47, v2
	v_mov_b32_e32 v48, v2
	v_mov_b32_e32 v49, v2
	v_mov_b32_e32 v50, v2
	v_mov_b32_e32 v51, v2
	v_mov_b32_e32 v52, v2
	v_mov_b32_e32 v53, v2
	v_mov_b32_e32 v54, v2
	v_mov_b32_e32 v55, v2
	v_mov_b32_e32 v56, v2
	v_mov_b32_e32 v57, v2
	v_mov_b32_e32 v58, v2
	v_mov_b32_e32 v59, v2
	v_mov_b32_e32 v60, v2
	v_mov_b32_e32 v61, v2
	v_mov_b32_e32 v62, v2
	v_mov_b32_e32 v63, v2
	v_mov_b32_e32 v64, v2
	v_mov_b32_e32 v65, v2
.LBB0_637:
	s_waitcnt vmcnt(8)
	s_add_u32 s26, s24, 0x8000
	s_waitcnt lgkmcnt(0)
	s_addc_u32 s27, s25, 0
	s_add_u32 s28, s22, 0x8000
	s_addc_u32 s29, s23, 0
	s_setprio 1
	s_barrier
	v_mfma_f32_16x16x32_bf16 v[62:65], v[146:149], v[186:189], v[62:65]
	v_mfma_f32_16x16x32_bf16 v[62:65], v[150:153], v[190:193], v[62:65]
	s_waitcnt lgkmcnt(5)
	v_mfma_f32_16x16x32_bf16 v[58:61], v[154:157], v[186:189], v[58:61]
	v_mfma_f32_16x16x32_bf16 v[58:61], v[158:161], v[190:193], v[58:61]
	s_waitcnt lgkmcnt(3)
	v_mfma_f32_16x16x32_bf16 v[54:57], v[146:149], v[178:181], v[54:57]
	v_mfma_f32_16x16x32_bf16 v[54:57], v[150:153], v[182:185], v[54:57]
	s_waitcnt lgkmcnt(1)
	v_mfma_f32_16x16x32_bf16 v[50:53], v[154:157], v[178:181], v[50:53]
	v_mfma_f32_16x16x32_bf16 v[50:53], v[158:161], v[182:185], v[50:53]
	v_mfma_f32_16x16x32_bf16 v[46:49], v[146:149], v[170:173], v[46:49]
	v_mfma_f32_16x16x32_bf16 v[46:49], v[150:153], v[174:177], v[46:49]
	v_mfma_f32_16x16x32_bf16 v[42:45], v[154:157], v[170:173], v[42:45]
	v_mfma_f32_16x16x32_bf16 v[42:45], v[158:161], v[174:177], v[42:45]
	v_mfma_f32_16x16x32_bf16 v[38:41], v[146:149], v[162:165], v[38:41]
	v_mfma_f32_16x16x32_bf16 v[38:41], v[150:153], v[166:169], v[38:41]
	s_waitcnt lgkmcnt(0)
	v_mfma_f32_16x16x32_bf16 v[34:37], v[154:157], v[162:165], v[34:37]
	v_mfma_f32_16x16x32_bf16 v[34:37], v[158:161], v[166:169], v[34:37]
	s_setprio 0
	s_setprio 1
	v_mfma_f32_16x16x32_bf16 v[30:33], v[130:133], v[186:189], v[30:33]
	v_mfma_f32_16x16x32_bf16 v[30:33], v[134:137], v[190:193], v[30:33]
	v_mfma_f32_16x16x32_bf16 v[26:29], v[138:141], v[186:189], v[26:29]
	v_mfma_f32_16x16x32_bf16 v[26:29], v[142:145], v[190:193], v[26:29]
	v_mfma_f32_16x16x32_bf16 v[22:25], v[130:133], v[178:181], v[22:25]
	v_mfma_f32_16x16x32_bf16 v[22:25], v[134:137], v[182:185], v[22:25]
	v_mfma_f32_16x16x32_bf16 v[18:21], v[138:141], v[178:181], v[18:21]
	v_mfma_f32_16x16x32_bf16 v[18:21], v[142:145], v[182:185], v[18:21]
	v_mfma_f32_16x16x32_bf16 v[14:17], v[130:133], v[170:173], v[14:17]
	v_mfma_f32_16x16x32_bf16 v[14:17], v[134:137], v[174:177], v[14:17]
	v_mfma_f32_16x16x32_bf16 v[10:13], v[138:141], v[170:173], v[10:13]
	v_mfma_f32_16x16x32_bf16 v[10:13], v[142:145], v[174:177], v[10:13]
	s_setprio 2
	s_barrier
	v_mfma_f32_16x16x32_bf16 v[6:9], v[130:133], v[162:165], v[6:9]
	v_mfma_f32_16x16x32_bf16 v[6:9], v[134:137], v[166:169], v[6:9]
	v_mfma_f32_16x16x32_bf16 v[2:5], v[138:141], v[162:165], v[2:5]
	v_mfma_f32_16x16x32_bf16 v[2:5], v[142:145], v[166:169], v[2:5]
	s_setprio 0
	s_nop 0
	v_add_u32_e32 v142, 0x18000, v218
	v_add_u32_e32 v158, 0x1c000, v218
	ds_read_b128 v[130:133], v142
	ds_read_b128 v[134:137], v142 offset:1024
	ds_read_b128 v[138:141], v142 offset:2048
	ds_read_b128 v[142:145], v142 offset:3072
	ds_read_b128 v[146:149], v158
	ds_read_b128 v[150:153], v158 offset:1024
	ds_read_b128 v[154:157], v158 offset:2048
	ds_read_b128 v[158:161], v158 offset:3072
	ds_read_b128 v[162:165], v219 offset:32768
	ds_read_b128 v[166:169], v219 offset:33792
	ds_read_b128 v[170:173], v219 offset:34816
	ds_read_b128 v[174:177], v219 offset:35840
	ds_read_b128 v[178:181], v219 offset:36864
	ds_read_b128 v[182:185], v219 offset:37888
	ds_read_b128 v[186:189], v219 offset:38912
	ds_read_b128 v[190:193], v219 offset:39936
	s_add_u32 s24, s24, 0x4000
	s_addc_u32 s25, s25, 0
	s_mov_b32 m0, s55
	s_nop 0
	global_load_lds_dwordx4 v195, s[24:25]
	s_add_u32 m0, s55, 0x2000
	s_nop 0
	global_load_lds_dwordx4 v213, s[24:25]
	s_waitcnt vmcnt(8)
	s_waitcnt lgkmcnt(0)
	s_setprio 1
	s_barrier
	v_mfma_f32_16x16x32_bf16 v[126:129], v[130:133], v[162:165], v[126:129]
	v_mfma_f32_16x16x32_bf16 v[126:129], v[134:137], v[166:169], v[126:129]
	s_waitcnt lgkmcnt(5)
	v_mfma_f32_16x16x32_bf16 v[122:125], v[138:141], v[162:165], v[122:125]
	v_mfma_f32_16x16x32_bf16 v[122:125], v[142:145], v[166:169], v[122:125]
	s_waitcnt lgkmcnt(3)
	v_mfma_f32_16x16x32_bf16 v[118:121], v[130:133], v[170:173], v[118:121]
	v_mfma_f32_16x16x32_bf16 v[118:121], v[134:137], v[174:177], v[118:121]
	s_waitcnt lgkmcnt(1)
	v_mfma_f32_16x16x32_bf16 v[114:117], v[138:141], v[170:173], v[114:117]
	v_mfma_f32_16x16x32_bf16 v[114:117], v[142:145], v[174:177], v[114:117]
	v_mfma_f32_16x16x32_bf16 v[110:113], v[130:133], v[178:181], v[110:113]
	v_mfma_f32_16x16x32_bf16 v[110:113], v[134:137], v[182:185], v[110:113]
	v_mfma_f32_16x16x32_bf16 v[106:109], v[138:141], v[178:181], v[106:109]
	v_mfma_f32_16x16x32_bf16 v[106:109], v[142:145], v[182:185], v[106:109]
	v_mfma_f32_16x16x32_bf16 v[102:105], v[130:133], v[186:189], v[102:105]
	v_mfma_f32_16x16x32_bf16 v[102:105], v[134:137], v[190:193], v[102:105]
	s_waitcnt lgkmcnt(0)
	v_mfma_f32_16x16x32_bf16 v[98:101], v[138:141], v[186:189], v[98:101]
	v_mfma_f32_16x16x32_bf16 v[98:101], v[142:145], v[190:193], v[98:101]
	s_setprio 0
	s_setprio 1
	v_mfma_f32_16x16x32_bf16 v[94:97], v[146:149], v[162:165], v[94:97]
	v_mfma_f32_16x16x32_bf16 v[94:97], v[150:153], v[166:169], v[94:97]
	v_mfma_f32_16x16x32_bf16 v[90:93], v[154:157], v[162:165], v[90:93]
	v_mfma_f32_16x16x32_bf16 v[90:93], v[158:161], v[166:169], v[90:93]
	v_mfma_f32_16x16x32_bf16 v[86:89], v[146:149], v[170:173], v[86:89]
	v_mfma_f32_16x16x32_bf16 v[86:89], v[150:153], v[174:177], v[86:89]
	v_mfma_f32_16x16x32_bf16 v[82:85], v[154:157], v[170:173], v[82:85]
	v_mfma_f32_16x16x32_bf16 v[82:85], v[158:161], v[174:177], v[82:85]
	v_mfma_f32_16x16x32_bf16 v[78:81], v[146:149], v[178:181], v[78:81]
	v_mfma_f32_16x16x32_bf16 v[78:81], v[150:153], v[182:185], v[78:81]
	v_mfma_f32_16x16x32_bf16 v[74:77], v[154:157], v[178:181], v[74:77]
	v_mfma_f32_16x16x32_bf16 v[74:77], v[158:161], v[182:185], v[74:77]
	s_setprio 2
	s_barrier
	v_mfma_f32_16x16x32_bf16 v[70:73], v[146:149], v[186:189], v[70:73]
	v_mfma_f32_16x16x32_bf16 v[70:73], v[150:153], v[190:193], v[70:73]
	v_mfma_f32_16x16x32_bf16 v[66:69], v[154:157], v[186:189], v[66:69]
	v_mfma_f32_16x16x32_bf16 v[66:69], v[158:161], v[190:193], v[66:69]
	s_setprio 0
	s_nop 0
	ds_read_b128 v[162:165], v219 offset:49152
	ds_read_b128 v[166:169], v219 offset:50176
	ds_read_b128 v[170:173], v219 offset:51200
	ds_read_b128 v[174:177], v219 offset:52224
	ds_read_b128 v[178:181], v219 offset:53248
	ds_read_b128 v[182:185], v219 offset:54272
	ds_read_b128 v[186:189], v219 offset:55296
	ds_read_b128 v[190:193], v219 offset:56320
	s_mov_b32 m0, s83
	s_nop 0
	global_load_lds_dwordx4 v195, s[28:29]
	s_add_u32 m0, s83, 0x2000
	s_nop 0
	global_load_lds_dwordx4 v213, s[28:29]
	s_add_u32 s22, s22, 0xc000
	s_addc_u32 s23, s23, 0
	s_mov_b32 m0, s91
	s_nop 0
	global_load_lds_dwordx4 v195, s[22:23]
	s_add_u32 m0, s91, 0x2000
	s_nop 0
	global_load_lds_dwordx4 v213, s[22:23]
	s_nop 0
	s_mov_b32 m0, s90
	s_nop 0
	global_load_lds_dwordx4 v195, s[26:27]
	s_add_u32 m0, s90, 0x2000
	s_nop 0
	global_load_lds_dwordx4 v213, s[26:27]
	s_waitcnt vmcnt(8)
	s_waitcnt lgkmcnt(0)
	s_setprio 1
	s_barrier
	v_mfma_f32_16x16x32_bf16 v[62:65], v[130:133], v[162:165], v[62:65]
	v_mfma_f32_16x16x32_bf16 v[62:65], v[134:137], v[166:169], v[62:65]
	s_waitcnt lgkmcnt(5)
	v_mfma_f32_16x16x32_bf16 v[58:61], v[138:141], v[162:165], v[58:61]
	v_mfma_f32_16x16x32_bf16 v[58:61], v[142:145], v[166:169], v[58:61]
	s_waitcnt lgkmcnt(3)
	v_mfma_f32_16x16x32_bf16 v[54:57], v[130:133], v[170:173], v[54:57]
	v_mfma_f32_16x16x32_bf16 v[54:57], v[134:137], v[174:177], v[54:57]
	s_waitcnt lgkmcnt(1)
	v_mfma_f32_16x16x32_bf16 v[50:53], v[138:141], v[170:173], v[50:53]
	v_mfma_f32_16x16x32_bf16 v[50:53], v[142:145], v[174:177], v[50:53]
	v_mfma_f32_16x16x32_bf16 v[46:49], v[130:133], v[178:181], v[46:49]
	v_mfma_f32_16x16x32_bf16 v[46:49], v[134:137], v[182:185], v[46:49]
	v_mfma_f32_16x16x32_bf16 v[42:45], v[138:141], v[178:181], v[42:45]
	v_mfma_f32_16x16x32_bf16 v[42:45], v[142:145], v[182:185], v[42:45]
	v_mfma_f32_16x16x32_bf16 v[38:41], v[130:133], v[186:189], v[38:41]
	v_mfma_f32_16x16x32_bf16 v[38:41], v[134:137], v[190:193], v[38:41]
	s_waitcnt lgkmcnt(0)
	v_mfma_f32_16x16x32_bf16 v[34:37], v[138:141], v[186:189], v[34:37]
	v_mfma_f32_16x16x32_bf16 v[34:37], v[142:145], v[190:193], v[34:37]
	s_setprio 0
	s_setprio 1
	v_mfma_f32_16x16x32_bf16 v[30:33], v[146:149], v[162:165], v[30:33]
	v_mfma_f32_16x16x32_bf16 v[30:33], v[150:153], v[166:169], v[30:33]
	v_mfma_f32_16x16x32_bf16 v[26:29], v[154:157], v[162:165], v[26:29]
	v_mfma_f32_16x16x32_bf16 v[26:29], v[158:161], v[166:169], v[26:29]
	v_mfma_f32_16x16x32_bf16 v[22:25], v[146:149], v[170:173], v[22:25]
	v_mfma_f32_16x16x32_bf16 v[22:25], v[150:153], v[174:177], v[22:25]
	v_mfma_f32_16x16x32_bf16 v[18:21], v[154:157], v[170:173], v[18:21]
	v_mfma_f32_16x16x32_bf16 v[18:21], v[158:161], v[174:177], v[18:21]
	v_mfma_f32_16x16x32_bf16 v[14:17], v[146:149], v[178:181], v[14:17]
	v_mfma_f32_16x16x32_bf16 v[14:17], v[150:153], v[182:185], v[14:17]
	v_mfma_f32_16x16x32_bf16 v[10:13], v[154:157], v[178:181], v[10:13]
	v_mfma_f32_16x16x32_bf16 v[10:13], v[158:161], v[182:185], v[10:13]
	s_setprio 2
	s_barrier
	v_mfma_f32_16x16x32_bf16 v[6:9], v[146:149], v[186:189], v[6:9]
	v_mfma_f32_16x16x32_bf16 v[6:9], v[150:153], v[190:193], v[6:9]
	v_mfma_f32_16x16x32_bf16 v[2:5], v[154:157], v[186:189], v[2:5]
	v_mfma_f32_16x16x32_bf16 v[2:5], v[158:161], v[190:193], v[2:5]
	s_setprio 0
	s_nop 0
	s_add_i32 s3, s71, 2
	s_cmp_gt_u32 s71, 13
	s_cbranch_scc1 .LBB0_639
	s_mov_b32 s71, s3
	s_branch .LBB0_616

.LBB0_1068:
	s_or_b64 exec, exec, s[62:63]
	s_add_u32 s88, s12, s0
	ds_read_b128 v[132:135], v214
	ds_read_b128 v[136:139], v214 offset:1024
	ds_read_b128 v[140:143], v214 offset:2048
	ds_read_b128 v[144:147], v214 offset:3072
	ds_read_b128 v[154:157], v215
	ds_read_b128 v[158:161], v215 offset:1024
	ds_read_b128 v[162:165], v215 offset:2048
	ds_read_b128 v[166:169], v215 offset:3072
	s_addc_u32 s89, s13, s1
	s_add_u32 s62, s88, 0x20000
	s_addc_u32 s63, s89, 0
	s_add_u32 s64, s94, s0
	s_addc_u32 s65, s96, s1
	s_cmp_eq_u32 s0, 0x60000
	s_cselect_b32 s68, s53, s62
	s_cselect_b32 s69, s33, s63
	s_cselect_b32 s63, s51, s65
	s_cselect_b32 s62, s95, s64
	s_add_u32 s64, s68, 0x8000
	s_addc_u32 s65, s69, 0
	s_add_u32 s66, s62, 0x8000
	s_addc_u32 s67, s63, 0
	ds_read_b128 v[170:173], v216
	ds_read_b128 v[174:177], v216 offset:1024
	ds_read_b128 v[178:181], v216 offset:2048
	ds_read_b128 v[182:185], v216 offset:3072
	ds_read_b128 v[186:189], v216 offset:4096
	ds_read_b128 v[190:193], v216 offset:5120
	ds_read_b128 v[198:201], v216 offset:6144
	ds_read_b128 v[202:205], v216 offset:7168
	s_add_u32 s88, s88, 0x1c000
	s_addc_u32 s89, s89, 0
	s_mov_b32 m0, s79
	s_nop 0
	global_load_lds_dwordx4 v195, s[88:89]
	s_add_u32 m0, s79, 0x2000
	s_nop 0
	global_load_lds_dwordx4 v212, s[88:89]
	s_waitcnt vmcnt(8)
	s_waitcnt lgkmcnt(0)
	s_setprio 1
	s_barrier
	v_mfma_f32_16x16x32_bf16 v[126:129], v[132:135], v[170:173], v[126:129]
	v_mfma_f32_16x16x32_bf16 v[126:129], v[136:139], v[174:177], v[126:129]
	s_waitcnt lgkmcnt(5)
	v_mfma_f32_16x16x32_bf16 v[122:125], v[140:143], v[170:173], v[122:125]
	v_mfma_f32_16x16x32_bf16 v[122:125], v[144:147], v[174:177], v[122:125]
	s_waitcnt lgkmcnt(3)
	v_mfma_f32_16x16x32_bf16 v[110:113], v[132:135], v[178:181], v[110:113]
	v_mfma_f32_16x16x32_bf16 v[110:113], v[136:139], v[182:185], v[110:113]
	s_waitcnt lgkmcnt(1)
	v_mfma_f32_16x16x32_bf16 v[106:109], v[140:143], v[178:181], v[106:109]
	v_mfma_f32_16x16x32_bf16 v[106:109], v[144:147], v[182:185], v[106:109]
	v_mfma_f32_16x16x32_bf16 v[94:97], v[132:135], v[186:189], v[94:97]
	v_mfma_f32_16x16x32_bf16 v[94:97], v[136:139], v[190:193], v[94:97]
	v_mfma_f32_16x16x32_bf16 v[90:93], v[140:143], v[186:189], v[90:93]
	v_mfma_f32_16x16x32_bf16 v[90:93], v[144:147], v[190:193], v[90:93]
	v_mfma_f32_16x16x32_bf16 v[78:81], v[132:135], v[198:201], v[78:81]
	v_mfma_f32_16x16x32_bf16 v[78:81], v[136:139], v[202:205], v[78:81]
	s_waitcnt lgkmcnt(0)
	v_mfma_f32_16x16x32_bf16 v[74:77], v[140:143], v[198:201], v[74:77]
	v_mfma_f32_16x16x32_bf16 v[74:77], v[144:147], v[202:205], v[74:77]
	s_setprio 0
	s_setprio 1
	v_mfma_f32_16x16x32_bf16 v[118:121], v[154:157], v[170:173], v[118:121]
	v_mfma_f32_16x16x32_bf16 v[118:121], v[158:161], v[174:177], v[118:121]
	v_mfma_f32_16x16x32_bf16 v[114:117], v[162:165], v[170:173], v[114:117]
	v_mfma_f32_16x16x32_bf16 v[114:117], v[166:169], v[174:177], v[114:117]
	v_mfma_f32_16x16x32_bf16 v[102:105], v[154:157], v[178:181], v[102:105]
	v_mfma_f32_16x16x32_bf16 v[102:105], v[158:161], v[182:185], v[102:105]
	v_mfma_f32_16x16x32_bf16 v[98:101], v[162:165], v[178:181], v[98:101]
	v_mfma_f32_16x16x32_bf16 v[98:101], v[166:169], v[182:185], v[98:101]
	v_mfma_f32_16x16x32_bf16 v[86:89], v[154:157], v[186:189], v[86:89]
	v_mfma_f32_16x16x32_bf16 v[86:89], v[158:161], v[190:193], v[86:89]
	v_mfma_f32_16x16x32_bf16 v[82:85], v[162:165], v[186:189], v[82:85]
	v_mfma_f32_16x16x32_bf16 v[82:85], v[166:169], v[190:193], v[82:85]
	s_setprio 2
	s_barrier
	v_mfma_f32_16x16x32_bf16 v[70:73], v[154:157], v[198:201], v[70:73]
	v_mfma_f32_16x16x32_bf16 v[70:73], v[158:161], v[202:205], v[70:73]
	v_mfma_f32_16x16x32_bf16 v[66:69], v[162:165], v[198:201], v[66:69]
	v_mfma_f32_16x16x32_bf16 v[66:69], v[166:169], v[202:205], v[66:69]
	s_setprio 0
	s_nop 0
	ds_read_b128 v[170:173], v216 offset:16384
	ds_read_b128 v[174:177], v216 offset:17408
	ds_read_b128 v[178:181], v216 offset:18432
	ds_read_b128 v[182:185], v216 offset:19456
	ds_read_b128 v[186:189], v216 offset:20480
	ds_read_b128 v[190:193], v216 offset:21504
	ds_read_b128 v[198:201], v216 offset:22528
	ds_read_b128 v[202:205], v216 offset:23552
	s_mov_b32 m0, s3
	s_nop 0
	global_load_lds_dwordx4 v195, s[62:63]
	s_add_u32 m0, s3, 0x2000
	s_nop 0
	global_load_lds_dwordx4 v212, s[62:63]
	s_add_u32 s88, s62, 0x4000
	s_addc_u32 s89, s63, 0
	s_mov_b32 m0, s71
	s_nop 0
	global_load_lds_dwordx4 v195, s[88:89]
	s_add_u32 m0, s71, 0x2000
	s_nop 0
	global_load_lds_dwordx4 v212, s[88:89]
	s_nop 0
	s_mov_b32 m0, s70
	s_nop 0
	global_load_lds_dwordx4 v195, s[68:69]
	s_add_u32 m0, s70, 0x2000
	s_nop 0
	global_load_lds_dwordx4 v212, s[68:69]
	s_waitcnt vmcnt(8)
	s_waitcnt lgkmcnt(0)
	s_setprio 1
	s_barrier
	v_mfma_f32_16x16x32_bf16 v[62:65], v[132:135], v[170:173], v[62:65]
	v_mfma_f32_16x16x32_bf16 v[62:65], v[136:139], v[174:177], v[62:65]
	s_waitcnt lgkmcnt(5)
	v_mfma_f32_16x16x32_bf16 v[58:61], v[140:143], v[170:173], v[58:61]
	v_mfma_f32_16x16x32_bf16 v[58:61], v[144:147], v[174:177], v[58:61]
	s_waitcnt lgkmcnt(3)
	v_mfma_f32_16x16x32_bf16 v[46:49], v[132:135], v[178:181], v[46:49]
	v_mfma_f32_16x16x32_bf16 v[46:49], v[136:139], v[182:185], v[46:49]
	s_waitcnt lgkmcnt(1)
	v_mfma_f32_16x16x32_bf16 v[42:45], v[140:143], v[178:181], v[42:45]
	v_mfma_f32_16x16x32_bf16 v[42:45], v[144:147], v[182:185], v[42:45]
	v_mfma_f32_16x16x32_bf16 v[30:33], v[132:135], v[186:189], v[30:33]
	v_mfma_f32_16x16x32_bf16 v[30:33], v[136:139], v[190:193], v[30:33]
	v_mfma_f32_16x16x32_bf16 v[26:29], v[140:143], v[186:189], v[26:29]
	v_mfma_f32_16x16x32_bf16 v[26:29], v[144:147], v[190:193], v[26:29]
	v_mfma_f32_16x16x32_bf16 v[14:17], v[132:135], v[198:201], v[14:17]
	v_mfma_f32_16x16x32_bf16 v[14:17], v[136:139], v[202:205], v[14:17]
	s_waitcnt lgkmcnt(0)
	v_mfma_f32_16x16x32_bf16 v[10:13], v[140:143], v[198:201], v[10:13]
	v_mfma_f32_16x16x32_bf16 v[10:13], v[144:147], v[202:205], v[10:13]
	s_setprio 0
	s_setprio 1
	v_mfma_f32_16x16x32_bf16 v[54:57], v[154:157], v[170:173], v[54:57]
	v_mfma_f32_16x16x32_bf16 v[54:57], v[158:161], v[174:177], v[54:57]
	v_mfma_f32_16x16x32_bf16 v[50:53], v[162:165], v[170:173], v[50:53]
	v_mfma_f32_16x16x32_bf16 v[50:53], v[166:169], v[174:177], v[50:53]
	v_mfma_f32_16x16x32_bf16 v[38:41], v[154:157], v[178:181], v[38:41]
	v_mfma_f32_16x16x32_bf16 v[38:41], v[158:161], v[182:185], v[38:41]
	v_mfma_f32_16x16x32_bf16 v[34:37], v[162:165], v[178:181], v[34:37]
	v_mfma_f32_16x16x32_bf16 v[34:37], v[166:169], v[182:185], v[34:37]
	v_mfma_f32_16x16x32_bf16 v[22:25], v[154:157], v[186:189], v[22:25]
	v_mfma_f32_16x16x32_bf16 v[22:25], v[158:161], v[190:193], v[22:25]
	v_mfma_f32_16x16x32_bf16 v[18:21], v[162:165], v[186:189], v[18:21]
	v_mfma_f32_16x16x32_bf16 v[18:21], v[166:169], v[190:193], v[18:21]
	s_setprio 2
	s_barrier
	v_mfma_f32_16x16x32_bf16 v[6:9], v[154:157], v[198:201], v[6:9]
	v_mfma_f32_16x16x32_bf16 v[6:9], v[158:161], v[202:205], v[6:9]
	v_mfma_f32_16x16x32_bf16 v[2:5], v[162:165], v[198:201], v[2:5]
	v_mfma_f32_16x16x32_bf16 v[2:5], v[166:169], v[202:205], v[2:5]
	s_setprio 0
	s_nop 0
	ds_read_b128 v[132:135], v217
	ds_read_b128 v[136:139], v217 offset:1024
	ds_read_b128 v[140:143], v217 offset:2048
	ds_read_b128 v[144:147], v217 offset:3072
	ds_read_b128 v[154:157], v218
	ds_read_b128 v[158:161], v218 offset:1024
	ds_read_b128 v[162:165], v218 offset:2048
	ds_read_b128 v[166:169], v218 offset:3072
	ds_read_b128 v[170:173], v216 offset:32768
	ds_read_b128 v[174:177], v216 offset:33792
	ds_read_b128 v[178:181], v216 offset:34816
	ds_read_b128 v[182:185], v216 offset:35840
	ds_read_b128 v[186:189], v216 offset:36864
	ds_read_b128 v[190:193], v216 offset:37888
	ds_read_b128 v[198:201], v216 offset:38912
	ds_read_b128 v[202:205], v216 offset:39936
	s_add_u32 s68, s68, 0x4000
	s_addc_u32 s69, s69, 0
	s_mov_b32 m0, s72
	s_nop 0
	global_load_lds_dwordx4 v195, s[68:69]
	s_add_u32 m0, s72, 0x2000
	s_nop 0
	global_load_lds_dwordx4 v212, s[68:69]
	s_waitcnt vmcnt(8)
	s_waitcnt lgkmcnt(0)
	s_setprio 1
	s_barrier
	v_mfma_f32_16x16x32_bf16 v[126:129], v[132:135], v[170:173], v[126:129]
	v_mfma_f32_16x16x32_bf16 v[126:129], v[136:139], v[174:177], v[126:129]
	s_waitcnt lgkmcnt(5)
	v_mfma_f32_16x16x32_bf16 v[122:125], v[140:143], v[170:173], v[122:125]
	v_mfma_f32_16x16x32_bf16 v[122:125], v[144:147], v[174:177], v[122:125]
	s_waitcnt lgkmcnt(3)
	v_mfma_f32_16x16x32_bf16 v[110:113], v[132:135], v[178:181], v[110:113]
	v_mfma_f32_16x16x32_bf16 v[110:113], v[136:139], v[182:185], v[110:113]
	s_waitcnt lgkmcnt(1)
	v_mfma_f32_16x16x32_bf16 v[106:109], v[140:143], v[178:181], v[106:109]
	v_mfma_f32_16x16x32_bf16 v[106:109], v[144:147], v[182:185], v[106:109]
	v_mfma_f32_16x16x32_bf16 v[94:97], v[132:135], v[186:189], v[94:97]
	v_mfma_f32_16x16x32_bf16 v[94:97], v[136:139], v[190:193], v[94:97]
	v_mfma_f32_16x16x32_bf16 v[90:93], v[140:143], v[186:189], v[90:93]
	v_mfma_f32_16x16x32_bf16 v[90:93], v[144:147], v[190:193], v[90:93]
	v_mfma_f32_16x16x32_bf16 v[78:81], v[132:135], v[198:201], v[78:81]
	v_mfma_f32_16x16x32_bf16 v[78:81], v[136:139], v[202:205], v[78:81]
	s_waitcnt lgkmcnt(0)
	v_mfma_f32_16x16x32_bf16 v[74:77], v[140:143], v[198:201], v[74:77]
	v_mfma_f32_16x16x32_bf16 v[74:77], v[144:147], v[202:205], v[74:77]
	s_setprio 0
	s_setprio 1
	v_mfma_f32_16x16x32_bf16 v[118:121], v[154:157], v[170:173], v[118:121]
	v_mfma_f32_16x16x32_bf16 v[118:121], v[158:161], v[174:177], v[118:121]
	v_mfma_f32_16x16x32_bf16 v[114:117], v[162:165], v[170:173], v[114:117]
	v_mfma_f32_16x16x32_bf16 v[114:117], v[166:169], v[174:177], v[114:117]
	v_mfma_f32_16x16x32_bf16 v[102:105], v[154:157], v[178:181], v[102:105]
	v_mfma_f32_16x16x32_bf16 v[102:105], v[158:161], v[182:185], v[102:105]
	v_mfma_f32_16x16x32_bf16 v[98:101], v[162:165], v[178:181], v[98:101]
	v_mfma_f32_16x16x32_bf16 v[98:101], v[166:169], v[182:185], v[98:101]
	v_mfma_f32_16x16x32_bf16 v[86:89], v[154:157], v[186:189], v[86:89]
	v_mfma_f32_16x16x32_bf16 v[86:89], v[158:161], v[190:193], v[86:89]
	v_mfma_f32_16x16x32_bf16 v[82:85], v[162:165], v[186:189], v[82:85]
	v_mfma_f32_16x16x32_bf16 v[82:85], v[166:169], v[190:193], v[82:85]
	s_setprio 2
	s_barrier
	v_mfma_f32_16x16x32_bf16 v[70:73], v[154:157], v[198:201], v[70:73]
	v_mfma_f32_16x16x32_bf16 v[70:73], v[158:161], v[202:205], v[70:73]
	v_mfma_f32_16x16x32_bf16 v[66:69], v[162:165], v[198:201], v[66:69]
	v_mfma_f32_16x16x32_bf16 v[66:69], v[166:169], v[202:205], v[66:69]
	s_setprio 0
	s_nop 0
	ds_read_b128 v[170:173], v216 offset:49152
	ds_read_b128 v[174:177], v216 offset:50176
	ds_read_b128 v[178:181], v216 offset:51200
	ds_read_b128 v[182:185], v216 offset:52224
	ds_read_b128 v[186:189], v216 offset:53248
	ds_read_b128 v[190:193], v216 offset:54272
	ds_read_b128 v[198:201], v216 offset:55296
	ds_read_b128 v[202:205], v216 offset:56320
	s_mov_b32 m0, s76
	s_nop 0
	global_load_lds_dwordx4 v195, s[66:67]
	s_add_u32 m0, s76, 0x2000
	s_nop 0
	global_load_lds_dwordx4 v212, s[66:67]
	s_add_u32 s62, s62, 0xc000
	s_addc_u32 s63, s63, 0
	s_mov_b32 m0, s78
	s_nop 0
	global_load_lds_dwordx4 v195, s[62:63]
	s_add_u32 m0, s78, 0x2000
	s_nop 0
	global_load_lds_dwordx4 v212, s[62:63]
	s_nop 0
	s_mov_b32 m0, s77
	s_nop 0
	global_load_lds_dwordx4 v195, s[64:65]
	s_add_u32 m0, s77, 0x2000
	s_nop 0
	global_load_lds_dwordx4 v212, s[64:65]
	s_waitcnt vmcnt(8)
	s_waitcnt lgkmcnt(0)
	s_setprio 1
	s_barrier
	v_mfma_f32_16x16x32_bf16 v[62:65], v[132:135], v[170:173], v[62:65]
	v_mfma_f32_16x16x32_bf16 v[62:65], v[136:139], v[174:177], v[62:65]
	s_waitcnt lgkmcnt(5)
	v_mfma_f32_16x16x32_bf16 v[58:61], v[140:143], v[170:173], v[58:61]
	v_mfma_f32_16x16x32_bf16 v[58:61], v[144:147], v[174:177], v[58:61]
	s_waitcnt lgkmcnt(3)
	v_mfma_f32_16x16x32_bf16 v[46:49], v[132:135], v[178:181], v[46:49]
	v_mfma_f32_16x16x32_bf16 v[46:49], v[136:139], v[182:185], v[46:49]
	s_waitcnt lgkmcnt(1)
	v_mfma_f32_16x16x32_bf16 v[42:45], v[140:143], v[178:181], v[42:45]
	v_mfma_f32_16x16x32_bf16 v[42:45], v[144:147], v[182:185], v[42:45]
	v_mfma_f32_16x16x32_bf16 v[30:33], v[132:135], v[186:189], v[30:33]
	v_mfma_f32_16x16x32_bf16 v[30:33], v[136:139], v[190:193], v[30:33]
	v_mfma_f32_16x16x32_bf16 v[26:29], v[140:143], v[186:189], v[26:29]
	v_mfma_f32_16x16x32_bf16 v[26:29], v[144:147], v[190:193], v[26:29]
	v_mfma_f32_16x16x32_bf16 v[14:17], v[132:135], v[198:201], v[14:17]
	v_mfma_f32_16x16x32_bf16 v[14:17], v[136:139], v[202:205], v[14:17]
	s_waitcnt lgkmcnt(0)
	v_mfma_f32_16x16x32_bf16 v[10:13], v[140:143], v[198:201], v[10:13]
	v_mfma_f32_16x16x32_bf16 v[10:13], v[144:147], v[202:205], v[10:13]
	s_setprio 0
	s_setprio 1
	v_mfma_f32_16x16x32_bf16 v[54:57], v[154:157], v[170:173], v[54:57]
	v_mfma_f32_16x16x32_bf16 v[54:57], v[158:161], v[174:177], v[54:57]
	v_mfma_f32_16x16x32_bf16 v[50:53], v[162:165], v[170:173], v[50:53]
	v_mfma_f32_16x16x32_bf16 v[50:53], v[166:169], v[174:177], v[50:53]
	v_mfma_f32_16x16x32_bf16 v[38:41], v[154:157], v[178:181], v[38:41]
	v_mfma_f32_16x16x32_bf16 v[38:41], v[158:161], v[182:185], v[38:41]
	v_mfma_f32_16x16x32_bf16 v[34:37], v[162:165], v[178:181], v[34:37]
	v_mfma_f32_16x16x32_bf16 v[34:37], v[166:169], v[182:185], v[34:37]
	v_mfma_f32_16x16x32_bf16 v[22:25], v[154:157], v[186:189], v[22:25]
	v_mfma_f32_16x16x32_bf16 v[22:25], v[158:161], v[190:193], v[22:25]
	v_mfma_f32_16x16x32_bf16 v[18:21], v[162:165], v[186:189], v[18:21]
	v_mfma_f32_16x16x32_bf16 v[18:21], v[166:169], v[190:193], v[18:21]
	s_setprio 2
	s_barrier
	v_mfma_f32_16x16x32_bf16 v[6:9], v[154:157], v[198:201], v[6:9]
	v_mfma_f32_16x16x32_bf16 v[6:9], v[158:161], v[202:205], v[6:9]
	v_mfma_f32_16x16x32_bf16 v[2:5], v[162:165], v[198:201], v[2:5]
	v_mfma_f32_16x16x32_bf16 v[2:5], v[166:169], v[202:205], v[2:5]
	s_setprio 0
	s_nop 0
	s_add_i32 s97, s97, 2
	s_add_u32 s0, s0, 0x10000
	s_addc_u32 s1, s1, 0
	s_cmp_gt_u32 s97, 13
	s_cbranch_scc1 .LBB0_1070
	v_mov_b32_e32 v131, v130
	s_branch .LBB0_1066

.LBB0_1336:
	s_add_u32 s50, s46, 0x10000
	s_addc_u32 s51, s47, 0
	s_and_b64 s[46:47], s[42:43], exec
	s_cselect_b32 s47, s51, s23
	s_cselect_b32 s46, s50, s75
	s_add_u32 s13, s16, s13
	s_addc_u32 s50, s17, 0
	s_add_u32 s13, s13, 0x10000
	s_waitcnt vmcnt(8)
	s_addc_u32 s50, s50, 0
	s_waitcnt lgkmcnt(0)
	s_and_b64 s[42:43], s[42:43], exec
	s_cselect_b32 s43, s50, s25
	s_cselect_b32 s42, s13, s76
	s_setprio 1
	s_barrier
	v_mfma_f32_16x16x32_bf16 v[126:129], v[146:149], v[186:189], v[126:129]
	v_mfma_f32_16x16x32_bf16 v[126:129], v[150:153], v[190:193], v[126:129]
	s_waitcnt lgkmcnt(5)
	v_mfma_f32_16x16x32_bf16 v[122:125], v[154:157], v[186:189], v[122:125]
	v_mfma_f32_16x16x32_bf16 v[122:125], v[158:161], v[190:193], v[122:125]
	s_waitcnt lgkmcnt(3)
	v_mfma_f32_16x16x32_bf16 v[118:121], v[146:149], v[178:181], v[118:121]
	v_mfma_f32_16x16x32_bf16 v[118:121], v[150:153], v[182:185], v[118:121]
	s_waitcnt lgkmcnt(1)
	v_mfma_f32_16x16x32_bf16 v[114:117], v[154:157], v[178:181], v[114:117]
	v_mfma_f32_16x16x32_bf16 v[114:117], v[158:161], v[182:185], v[114:117]
	v_mfma_f32_16x16x32_bf16 v[110:113], v[146:149], v[170:173], v[110:113]
	v_mfma_f32_16x16x32_bf16 v[110:113], v[150:153], v[174:177], v[110:113]
	v_mfma_f32_16x16x32_bf16 v[106:109], v[154:157], v[170:173], v[106:109]
	v_mfma_f32_16x16x32_bf16 v[106:109], v[158:161], v[174:177], v[106:109]
	v_mfma_f32_16x16x32_bf16 v[102:105], v[146:149], v[162:165], v[102:105]
	v_mfma_f32_16x16x32_bf16 v[102:105], v[150:153], v[166:169], v[102:105]
	s_waitcnt lgkmcnt(0)
	v_mfma_f32_16x16x32_bf16 v[98:101], v[154:157], v[162:165], v[98:101]
	v_mfma_f32_16x16x32_bf16 v[98:101], v[158:161], v[166:169], v[98:101]
	s_setprio 0
	s_setprio 1
	v_mfma_f32_16x16x32_bf16 v[94:97], v[130:133], v[186:189], v[94:97]
	v_mfma_f32_16x16x32_bf16 v[94:97], v[134:137], v[190:193], v[94:97]
	v_mfma_f32_16x16x32_bf16 v[90:93], v[138:141], v[186:189], v[90:93]
	v_mfma_f32_16x16x32_bf16 v[90:93], v[142:145], v[190:193], v[90:93]
	v_mfma_f32_16x16x32_bf16 v[86:89], v[130:133], v[178:181], v[86:89]
	v_mfma_f32_16x16x32_bf16 v[86:89], v[134:137], v[182:185], v[86:89]
	v_mfma_f32_16x16x32_bf16 v[82:85], v[138:141], v[178:181], v[82:85]
	v_mfma_f32_16x16x32_bf16 v[82:85], v[142:145], v[182:185], v[82:85]
	v_mfma_f32_16x16x32_bf16 v[78:81], v[130:133], v[170:173], v[78:81]
	v_mfma_f32_16x16x32_bf16 v[78:81], v[134:137], v[174:177], v[78:81]
	v_mfma_f32_16x16x32_bf16 v[74:77], v[138:141], v[170:173], v[74:77]
	v_mfma_f32_16x16x32_bf16 v[74:77], v[142:145], v[174:177], v[74:77]
	s_setprio 2
	s_barrier
	v_mfma_f32_16x16x32_bf16 v[70:73], v[130:133], v[162:165], v[70:73]
	v_mfma_f32_16x16x32_bf16 v[70:73], v[134:137], v[166:169], v[70:73]
	v_mfma_f32_16x16x32_bf16 v[66:69], v[138:141], v[162:165], v[66:69]
	v_mfma_f32_16x16x32_bf16 v[66:69], v[142:145], v[166:169], v[66:69]
	s_setprio 0
	s_nop 0
	ds_read_b128 v[186:189], v208 offset:16384
	ds_read_b128 v[190:193], v208 offset:17408
	ds_read_b128 v[178:181], v208 offset:18432
	ds_read_b128 v[182:185], v208 offset:19456
	ds_read_b128 v[170:173], v208 offset:20480
	ds_read_b128 v[174:177], v208 offset:21504
	ds_read_b128 v[162:165], v208 offset:22528
	ds_read_b128 v[166:169], v208 offset:23552
	s_mov_b32 m0, s58
	s_nop 0
	global_load_lds_dwordx4 v202, s[42:43]
	s_add_u32 m0, s58, 0x2000
	s_nop 0
	global_load_lds_dwordx4 v203, s[42:43]
	s_add_u32 s50, s42, 0x4000
	s_addc_u32 s51, s43, 0
	s_mov_b32 m0, s59
	s_nop 0
	global_load_lds_dwordx4 v202, s[50:51]
	s_add_u32 m0, s59, 0x2000
	s_nop 0
	global_load_lds_dwordx4 v203, s[50:51]
	s_andn2_b64 vcc, exec, s[48:49]
	s_mov_b32 m0, s7
	s_nop 0
	global_load_lds_dwordx4 v202, s[46:47]
	s_add_u32 m0, s7, 0x2000
	s_nop 0
	global_load_lds_dwordx4 v203, s[46:47]
	s_cbranch_vccnz .LBB0_1338
	v_mov_b32_e32 v2, 0
	v_mov_b32_e32 v3, v2
	v_mov_b32_e32 v4, v2
	v_mov_b32_e32 v5, v2
	v_mov_b32_e32 v6, v2
	v_mov_b32_e32 v7, v2
	v_mov_b32_e32 v8, v2
	v_mov_b32_e32 v9, v2
	v_mov_b32_e32 v10, v2
	v_mov_b32_e32 v11, v2
	v_mov_b32_e32 v12, v2
	v_mov_b32_e32 v13, v2
	v_mov_b32_e32 v14, v2
	v_mov_b32_e32 v15, v2
	v_mov_b32_e32 v16, v2
	v_mov_b32_e32 v17, v2
	v_mov_b32_e32 v18, v2
	v_mov_b32_e32 v19, v2
	v_mov_b32_e32 v20, v2
	v_mov_b32_e32 v21, v2
	v_mov_b32_e32 v22, v2
	v_mov_b32_e32 v23, v2
	v_mov_b32_e32 v24, v2
	v_mov_b32_e32 v25, v2
	v_mov_b32_e32 v26, v2
	v_mov_b32_e32 v27, v2
	v_mov_b32_e32 v28, v2
	v_mov_b32_e32 v29, v2
	v_mov_b32_e32 v30, v2
	v_mov_b32_e32 v31, v2
	v_mov_b32_e32 v32, v2
	v_mov_b32_e32 v33, v2
	v_mov_b32_e32 v34, v2
	v_mov_b32_e32 v35, v2
	v_mov_b32_e32 v36, v2
	v_mov_b32_e32 v37, v2
	v_mov_b32_e32 v38, v2
	v_mov_b32_e32 v39, v2
	v_mov_b32_e32 v40, v2
	v_mov_b32_e32 v41, v2
	v_mov_b32_e32 v42, v2
	v_mov_b32_e32 v43, v2
	v_mov_b32_e32 v44, v2
	v_mov_b32_e32 v45, v2
	v_mov_b32_e32 v46, v2
	v_mov_b32_e32 v47, v2
	v_mov_b32_e32 v48, v2
	v_mov_b32_e32 v49, v2
	v_mov_b32_e32 v50, v2
	v_mov_b32_e32 v51, v2
	v_mov_b32_e32 v52, v2
	v_mov_b32_e32 v53, v2
	v_mov_b32_e32 v54, v2
	v_mov_b32_e32 v55, v2
	v_mov_b32_e32 v56, v2
	v_mov_b32_e32 v57, v2
	v_mov_b32_e32 v58, v2
	v_mov_b32_e32 v59, v2
	v_mov_b32_e32 v60, v2
	v_mov_b32_e32 v61, v2
	v_mov_b32_e32 v62, v2
	v_mov_b32_e32 v63, v2
	v_mov_b32_e32 v64, v2
	v_mov_b32_e32 v65, v2
.LBB0_1338:
	s_waitcnt vmcnt(8)
	s_add_u32 s48, s46, 0x8000
	s_waitcnt lgkmcnt(0)
	s_addc_u32 s49, s47, 0
	s_add_u32 s50, s42, 0x8000
	s_addc_u32 s51, s43, 0
	s_setprio 1
	s_barrier
	v_mfma_f32_16x16x32_bf16 v[62:65], v[146:149], v[186:189], v[62:65]
	v_mfma_f32_16x16x32_bf16 v[62:65], v[150:153], v[190:193], v[62:65]
	s_waitcnt lgkmcnt(5)
	v_mfma_f32_16x16x32_bf16 v[58:61], v[154:157], v[186:189], v[58:61]
	v_mfma_f32_16x16x32_bf16 v[58:61], v[158:161], v[190:193], v[58:61]
	s_waitcnt lgkmcnt(3)
	v_mfma_f32_16x16x32_bf16 v[54:57], v[146:149], v[178:181], v[54:57]
	v_mfma_f32_16x16x32_bf16 v[54:57], v[150:153], v[182:185], v[54:57]
	s_waitcnt lgkmcnt(1)
	v_mfma_f32_16x16x32_bf16 v[50:53], v[154:157], v[178:181], v[50:53]
	v_mfma_f32_16x16x32_bf16 v[50:53], v[158:161], v[182:185], v[50:53]
	v_mfma_f32_16x16x32_bf16 v[46:49], v[146:149], v[170:173], v[46:49]
	v_mfma_f32_16x16x32_bf16 v[46:49], v[150:153], v[174:177], v[46:49]
	v_mfma_f32_16x16x32_bf16 v[42:45], v[154:157], v[170:173], v[42:45]
	v_mfma_f32_16x16x32_bf16 v[42:45], v[158:161], v[174:177], v[42:45]
	v_mfma_f32_16x16x32_bf16 v[38:41], v[146:149], v[162:165], v[38:41]
	v_mfma_f32_16x16x32_bf16 v[38:41], v[150:153], v[166:169], v[38:41]
	s_waitcnt lgkmcnt(0)
	v_mfma_f32_16x16x32_bf16 v[34:37], v[154:157], v[162:165], v[34:37]
	v_mfma_f32_16x16x32_bf16 v[34:37], v[158:161], v[166:169], v[34:37]
	s_setprio 0
	s_setprio 1
	v_mfma_f32_16x16x32_bf16 v[30:33], v[130:133], v[186:189], v[30:33]
	v_mfma_f32_16x16x32_bf16 v[30:33], v[134:137], v[190:193], v[30:33]
	v_mfma_f32_16x16x32_bf16 v[26:29], v[138:141], v[186:189], v[26:29]
	v_mfma_f32_16x16x32_bf16 v[26:29], v[142:145], v[190:193], v[26:29]
	v_mfma_f32_16x16x32_bf16 v[22:25], v[130:133], v[178:181], v[22:25]
	v_mfma_f32_16x16x32_bf16 v[22:25], v[134:137], v[182:185], v[22:25]
	v_mfma_f32_16x16x32_bf16 v[18:21], v[138:141], v[178:181], v[18:21]
	v_mfma_f32_16x16x32_bf16 v[18:21], v[142:145], v[182:185], v[18:21]
	v_mfma_f32_16x16x32_bf16 v[14:17], v[130:133], v[170:173], v[14:17]
	v_mfma_f32_16x16x32_bf16 v[14:17], v[134:137], v[174:177], v[14:17]
	v_mfma_f32_16x16x32_bf16 v[10:13], v[138:141], v[170:173], v[10:13]
	v_mfma_f32_16x16x32_bf16 v[10:13], v[142:145], v[174:177], v[10:13]
	s_setprio 2
	s_barrier
	v_mfma_f32_16x16x32_bf16 v[6:9], v[130:133], v[162:165], v[6:9]
	v_mfma_f32_16x16x32_bf16 v[6:9], v[134:137], v[166:169], v[6:9]
	v_mfma_f32_16x16x32_bf16 v[2:5], v[138:141], v[162:165], v[2:5]
	v_mfma_f32_16x16x32_bf16 v[2:5], v[142:145], v[166:169], v[2:5]
	s_setprio 0
	s_nop 0
	v_add_u32_e32 v142, 0x18000, v207
	v_add_u32_e32 v158, 0x1c000, v207
	ds_read_b128 v[130:133], v142
	ds_read_b128 v[134:137], v142 offset:1024
	ds_read_b128 v[138:141], v142 offset:2048
	ds_read_b128 v[142:145], v142 offset:3072
	ds_read_b128 v[146:149], v158
	ds_read_b128 v[150:153], v158 offset:1024
	ds_read_b128 v[154:157], v158 offset:2048
	ds_read_b128 v[158:161], v158 offset:3072
	ds_read_b128 v[162:165], v208 offset:32768
	ds_read_b128 v[166:169], v208 offset:33792
	ds_read_b128 v[170:173], v208 offset:34816
	ds_read_b128 v[174:177], v208 offset:35840
	ds_read_b128 v[178:181], v208 offset:36864
	ds_read_b128 v[182:185], v208 offset:37888
	ds_read_b128 v[186:189], v208 offset:38912
	ds_read_b128 v[190:193], v208 offset:39936
	s_add_u32 s46, s46, 0x4000
	s_addc_u32 s47, s47, 0
	s_mov_b32 m0, s60
	s_nop 0
	global_load_lds_dwordx4 v202, s[46:47]
	s_add_u32 m0, s60, 0x2000
	s_nop 0
	global_load_lds_dwordx4 v203, s[46:47]
	s_waitcnt vmcnt(8)
	s_waitcnt lgkmcnt(0)
	s_setprio 1
	s_barrier
	v_mfma_f32_16x16x32_bf16 v[126:129], v[130:133], v[162:165], v[126:129]
	v_mfma_f32_16x16x32_bf16 v[126:129], v[134:137], v[166:169], v[126:129]
	s_waitcnt lgkmcnt(5)
	v_mfma_f32_16x16x32_bf16 v[122:125], v[138:141], v[162:165], v[122:125]
	v_mfma_f32_16x16x32_bf16 v[122:125], v[142:145], v[166:169], v[122:125]
	s_waitcnt lgkmcnt(3)
	v_mfma_f32_16x16x32_bf16 v[118:121], v[130:133], v[170:173], v[118:121]
	v_mfma_f32_16x16x32_bf16 v[118:121], v[134:137], v[174:177], v[118:121]
	s_waitcnt lgkmcnt(1)
	v_mfma_f32_16x16x32_bf16 v[114:117], v[138:141], v[170:173], v[114:117]
	v_mfma_f32_16x16x32_bf16 v[114:117], v[142:145], v[174:177], v[114:117]
	v_mfma_f32_16x16x32_bf16 v[110:113], v[130:133], v[178:181], v[110:113]
	v_mfma_f32_16x16x32_bf16 v[110:113], v[134:137], v[182:185], v[110:113]
	v_mfma_f32_16x16x32_bf16 v[106:109], v[138:141], v[178:181], v[106:109]
	v_mfma_f32_16x16x32_bf16 v[106:109], v[142:145], v[182:185], v[106:109]
	v_mfma_f32_16x16x32_bf16 v[102:105], v[130:133], v[186:189], v[102:105]
	v_mfma_f32_16x16x32_bf16 v[102:105], v[134:137], v[190:193], v[102:105]
	s_waitcnt lgkmcnt(0)
	v_mfma_f32_16x16x32_bf16 v[98:101], v[138:141], v[186:189], v[98:101]
	v_mfma_f32_16x16x32_bf16 v[98:101], v[142:145], v[190:193], v[98:101]
	s_setprio 0
	s_setprio 1
	v_mfma_f32_16x16x32_bf16 v[94:97], v[146:149], v[162:165], v[94:97]
	v_mfma_f32_16x16x32_bf16 v[94:97], v[150:153], v[166:169], v[94:97]
	v_mfma_f32_16x16x32_bf16 v[90:93], v[154:157], v[162:165], v[90:93]
	v_mfma_f32_16x16x32_bf16 v[90:93], v[158:161], v[166:169], v[90:93]
	v_mfma_f32_16x16x32_bf16 v[86:89], v[146:149], v[170:173], v[86:89]
	v_mfma_f32_16x16x32_bf16 v[86:89], v[150:153], v[174:177], v[86:89]
	v_mfma_f32_16x16x32_bf16 v[82:85], v[154:157], v[170:173], v[82:85]
	v_mfma_f32_16x16x32_bf16 v[82:85], v[158:161], v[174:177], v[82:85]
	v_mfma_f32_16x16x32_bf16 v[78:81], v[146:149], v[178:181], v[78:81]
	v_mfma_f32_16x16x32_bf16 v[78:81], v[150:153], v[182:185], v[78:81]
	v_mfma_f32_16x16x32_bf16 v[74:77], v[154:157], v[178:181], v[74:77]
	v_mfma_f32_16x16x32_bf16 v[74:77], v[158:161], v[182:185], v[74:77]
	s_setprio 2
	s_barrier
	v_mfma_f32_16x16x32_bf16 v[70:73], v[146:149], v[186:189], v[70:73]
	v_mfma_f32_16x16x32_bf16 v[70:73], v[150:153], v[190:193], v[70:73]
	v_mfma_f32_16x16x32_bf16 v[66:69], v[154:157], v[186:189], v[66:69]
	v_mfma_f32_16x16x32_bf16 v[66:69], v[158:161], v[190:193], v[66:69]
	s_setprio 0
	s_nop 0
	ds_read_b128 v[162:165], v208 offset:49152
	ds_read_b128 v[166:169], v208 offset:50176
	ds_read_b128 v[170:173], v208 offset:51200
	ds_read_b128 v[174:177], v208 offset:52224
	ds_read_b128 v[178:181], v208 offset:53248
	ds_read_b128 v[182:185], v208 offset:54272
	ds_read_b128 v[186:189], v208 offset:55296
	ds_read_b128 v[190:193], v208 offset:56320
	s_mov_b32 m0, s64
	s_nop 0
	global_load_lds_dwordx4 v202, s[50:51]
	s_add_u32 m0, s64, 0x2000
	s_nop 0
	global_load_lds_dwordx4 v203, s[50:51]
	s_add_u32 s42, s42, 0xc000
	s_addc_u32 s43, s43, 0
	s_mov_b32 m0, s66
	s_nop 0
	global_load_lds_dwordx4 v202, s[42:43]
	s_add_u32 m0, s66, 0x2000
	s_nop 0
	global_load_lds_dwordx4 v203, s[42:43]
	s_nop 0
	s_mov_b32 m0, s65
	s_nop 0
	global_load_lds_dwordx4 v202, s[48:49]
	s_add_u32 m0, s65, 0x2000
	s_nop 0
	global_load_lds_dwordx4 v203, s[48:49]
	s_waitcnt vmcnt(8)
	s_waitcnt lgkmcnt(0)
	s_setprio 1
	s_barrier
	v_mfma_f32_16x16x32_bf16 v[62:65], v[130:133], v[162:165], v[62:65]
	v_mfma_f32_16x16x32_bf16 v[62:65], v[134:137], v[166:169], v[62:65]
	s_waitcnt lgkmcnt(5)
	v_mfma_f32_16x16x32_bf16 v[58:61], v[138:141], v[162:165], v[58:61]
	v_mfma_f32_16x16x32_bf16 v[58:61], v[142:145], v[166:169], v[58:61]
	s_waitcnt lgkmcnt(3)
	v_mfma_f32_16x16x32_bf16 v[54:57], v[130:133], v[170:173], v[54:57]
	v_mfma_f32_16x16x32_bf16 v[54:57], v[134:137], v[174:177], v[54:57]
	s_waitcnt lgkmcnt(1)
	v_mfma_f32_16x16x32_bf16 v[50:53], v[138:141], v[170:173], v[50:53]
	v_mfma_f32_16x16x32_bf16 v[50:53], v[142:145], v[174:177], v[50:53]
	v_mfma_f32_16x16x32_bf16 v[46:49], v[130:133], v[178:181], v[46:49]
	v_mfma_f32_16x16x32_bf16 v[46:49], v[134:137], v[182:185], v[46:49]
	v_mfma_f32_16x16x32_bf16 v[42:45], v[138:141], v[178:181], v[42:45]
	v_mfma_f32_16x16x32_bf16 v[42:45], v[142:145], v[182:185], v[42:45]
	v_mfma_f32_16x16x32_bf16 v[38:41], v[130:133], v[186:189], v[38:41]
	v_mfma_f32_16x16x32_bf16 v[38:41], v[134:137], v[190:193], v[38:41]
	s_waitcnt lgkmcnt(0)
	v_mfma_f32_16x16x32_bf16 v[34:37], v[138:141], v[186:189], v[34:37]
	v_mfma_f32_16x16x32_bf16 v[34:37], v[142:145], v[190:193], v[34:37]
	s_setprio 0
	s_setprio 1
	v_mfma_f32_16x16x32_bf16 v[30:33], v[146:149], v[162:165], v[30:33]
	v_mfma_f32_16x16x32_bf16 v[30:33], v[150:153], v[166:169], v[30:33]
	v_mfma_f32_16x16x32_bf16 v[26:29], v[154:157], v[162:165], v[26:29]
	v_mfma_f32_16x16x32_bf16 v[26:29], v[158:161], v[166:169], v[26:29]
	v_mfma_f32_16x16x32_bf16 v[22:25], v[146:149], v[170:173], v[22:25]
	v_mfma_f32_16x16x32_bf16 v[22:25], v[150:153], v[174:177], v[22:25]
	v_mfma_f32_16x16x32_bf16 v[18:21], v[154:157], v[170:173], v[18:21]
	v_mfma_f32_16x16x32_bf16 v[18:21], v[158:161], v[174:177], v[18:21]
	v_mfma_f32_16x16x32_bf16 v[14:17], v[146:149], v[178:181], v[14:17]
	v_mfma_f32_16x16x32_bf16 v[14:17], v[150:153], v[182:185], v[14:17]
	v_mfma_f32_16x16x32_bf16 v[10:13], v[154:157], v[178:181], v[10:13]
	v_mfma_f32_16x16x32_bf16 v[10:13], v[158:161], v[182:185], v[10:13]
	s_setprio 2
	s_barrier
	v_mfma_f32_16x16x32_bf16 v[6:9], v[146:149], v[186:189], v[6:9]
	v_mfma_f32_16x16x32_bf16 v[6:9], v[150:153], v[190:193], v[6:9]
	v_mfma_f32_16x16x32_bf16 v[2:5], v[154:157], v[186:189], v[2:5]
	v_mfma_f32_16x16x32_bf16 v[2:5], v[158:161], v[190:193], v[2:5]
	s_setprio 0
	s_nop 0
	s_add_i32 s13, s77, 2
	s_cmp_gt_u32 s77, 5
	s_cbranch_scc1 .LBB0_1340
	s_mov_b32 s77, s13
	s_branch .LBB0_1317

.LBB0_1374:
	s_or_b64 exec, exec, s[40:41]
	s_add_u32 s76, s16, s6
	ds_read_b128 v[132:135], v168
	ds_read_b128 v[136:139], v168 offset:1024
	ds_read_b128 v[140:143], v168 offset:2048
	ds_read_b128 v[144:147], v168 offset:3072
	ds_read_b128 v[148:151], v169
	ds_read_b128 v[158:161], v169 offset:1024
	ds_read_b128 v[162:165], v169 offset:2048
	ds_read_b128 v[174:177], v169 offset:3072
	s_addc_u32 s77, s17, s7
	s_add_u32 s40, s76, 0x20000
	s_addc_u32 s41, s77, 0
	s_add_u32 s42, s71, s6
	s_addc_u32 s43, s72, s7
	s_cmp_eq_u32 s6, 0x20000
	s_cselect_b32 s48, s73, s40
	s_cselect_b32 s49, s27, s41
	s_cselect_b32 s41, s25, s43
	s_cselect_b32 s40, s74, s42
	s_add_u32 s42, s48, 0x8000
	s_addc_u32 s43, s49, 0
	s_add_u32 s46, s40, 0x8000
	s_addc_u32 s47, s41, 0
	ds_read_b128 v[178:181], v170
	ds_read_b128 v[182:185], v170 offset:1024
	ds_read_b128 v[186:189], v170 offset:2048
	ds_read_b128 v[190:193], v170 offset:3072
	ds_read_b128 v[198:201], v170 offset:4096
	ds_read_b128 v[204:207], v170 offset:5120
	ds_read_b128 v[212:215], v170 offset:6144
	ds_read_b128 v[216:219], v170 offset:7168
	s_add_u32 s76, s76, 0x1c000
	s_addc_u32 s77, s77, 0
	s_mov_b32 m0, s63
	s_nop 0
	global_load_lds_dwordx4 v202, s[76:77]
	s_add_u32 m0, s63, 0x2000
	s_nop 0
	global_load_lds_dwordx4 v203, s[76:77]
	s_waitcnt vmcnt(8)
	s_waitcnt lgkmcnt(0)
	s_setprio 1
	s_barrier
	v_mfma_f32_16x16x32_bf16 v[126:129], v[132:135], v[178:181], v[126:129]
	v_mfma_f32_16x16x32_bf16 v[126:129], v[136:139], v[182:185], v[126:129]
	s_waitcnt lgkmcnt(5)
	v_mfma_f32_16x16x32_bf16 v[122:125], v[140:143], v[178:181], v[122:125]
	v_mfma_f32_16x16x32_bf16 v[122:125], v[144:147], v[182:185], v[122:125]
	s_waitcnt lgkmcnt(3)
	v_mfma_f32_16x16x32_bf16 v[110:113], v[132:135], v[186:189], v[110:113]
	v_mfma_f32_16x16x32_bf16 v[110:113], v[136:139], v[190:193], v[110:113]
	s_waitcnt lgkmcnt(1)
	v_mfma_f32_16x16x32_bf16 v[106:109], v[140:143], v[186:189], v[106:109]
	v_mfma_f32_16x16x32_bf16 v[106:109], v[144:147], v[190:193], v[106:109]
	v_mfma_f32_16x16x32_bf16 v[94:97], v[132:135], v[198:201], v[94:97]
	v_mfma_f32_16x16x32_bf16 v[94:97], v[136:139], v[204:207], v[94:97]
	v_mfma_f32_16x16x32_bf16 v[90:93], v[140:143], v[198:201], v[90:93]
	v_mfma_f32_16x16x32_bf16 v[90:93], v[144:147], v[204:207], v[90:93]
	v_mfma_f32_16x16x32_bf16 v[78:81], v[132:135], v[212:215], v[78:81]
	v_mfma_f32_16x16x32_bf16 v[78:81], v[136:139], v[216:219], v[78:81]
	s_waitcnt lgkmcnt(0)
	v_mfma_f32_16x16x32_bf16 v[74:77], v[140:143], v[212:215], v[74:77]
	v_mfma_f32_16x16x32_bf16 v[74:77], v[144:147], v[216:219], v[74:77]
	s_setprio 0
	s_setprio 1
	v_mfma_f32_16x16x32_bf16 v[118:121], v[148:151], v[178:181], v[118:121]
	v_mfma_f32_16x16x32_bf16 v[118:121], v[158:161], v[182:185], v[118:121]
	v_mfma_f32_16x16x32_bf16 v[114:117], v[162:165], v[178:181], v[114:117]
	v_mfma_f32_16x16x32_bf16 v[114:117], v[174:177], v[182:185], v[114:117]
	v_mfma_f32_16x16x32_bf16 v[102:105], v[148:151], v[186:189], v[102:105]
	v_mfma_f32_16x16x32_bf16 v[102:105], v[158:161], v[190:193], v[102:105]
	v_mfma_f32_16x16x32_bf16 v[98:101], v[162:165], v[186:189], v[98:101]
	v_mfma_f32_16x16x32_bf16 v[98:101], v[174:177], v[190:193], v[98:101]
	v_mfma_f32_16x16x32_bf16 v[86:89], v[148:151], v[198:201], v[86:89]
	v_mfma_f32_16x16x32_bf16 v[86:89], v[158:161], v[204:207], v[86:89]
	v_mfma_f32_16x16x32_bf16 v[82:85], v[162:165], v[198:201], v[82:85]
	v_mfma_f32_16x16x32_bf16 v[82:85], v[174:177], v[204:207], v[82:85]
	s_setprio 2
	s_barrier
	v_mfma_f32_16x16x32_bf16 v[70:73], v[148:151], v[212:215], v[70:73]
	v_mfma_f32_16x16x32_bf16 v[70:73], v[158:161], v[216:219], v[70:73]
	v_mfma_f32_16x16x32_bf16 v[66:69], v[162:165], v[212:215], v[66:69]
	v_mfma_f32_16x16x32_bf16 v[66:69], v[174:177], v[216:219], v[66:69]
	s_setprio 0
	s_nop 0
	ds_read_b128 v[178:181], v170 offset:16384
	ds_read_b128 v[182:185], v170 offset:17408
	ds_read_b128 v[186:189], v170 offset:18432
	ds_read_b128 v[190:193], v170 offset:19456
	ds_read_b128 v[198:201], v170 offset:20480
	ds_read_b128 v[204:207], v170 offset:21504
	ds_read_b128 v[212:215], v170 offset:22528
	ds_read_b128 v[216:219], v170 offset:23552
	s_mov_b32 m0, s13
	s_nop 0
	global_load_lds_dwordx4 v202, s[40:41]
	s_add_u32 m0, s13, 0x2000
	s_nop 0
	global_load_lds_dwordx4 v203, s[40:41]
	s_add_u32 s76, s40, 0x4000
	s_addc_u32 s77, s41, 0
	s_mov_b32 m0, s55
	s_nop 0
	global_load_lds_dwordx4 v202, s[76:77]
	s_add_u32 m0, s55, 0x2000
	s_nop 0
	global_load_lds_dwordx4 v203, s[76:77]
	s_nop 0
	s_mov_b32 m0, s54
	s_nop 0
	global_load_lds_dwordx4 v202, s[48:49]
	s_add_u32 m0, s54, 0x2000
	s_nop 0
	global_load_lds_dwordx4 v203, s[48:49]
	s_waitcnt vmcnt(8)
	s_waitcnt lgkmcnt(0)
	s_setprio 1
	s_barrier
	v_mfma_f32_16x16x32_bf16 v[62:65], v[132:135], v[178:181], v[62:65]
	v_mfma_f32_16x16x32_bf16 v[62:65], v[136:139], v[182:185], v[62:65]
	s_waitcnt lgkmcnt(5)
	v_mfma_f32_16x16x32_bf16 v[58:61], v[140:143], v[178:181], v[58:61]
	v_mfma_f32_16x16x32_bf16 v[58:61], v[144:147], v[182:185], v[58:61]
	s_waitcnt lgkmcnt(3)
	v_mfma_f32_16x16x32_bf16 v[46:49], v[132:135], v[186:189], v[46:49]
	v_mfma_f32_16x16x32_bf16 v[46:49], v[136:139], v[190:193], v[46:49]
	s_waitcnt lgkmcnt(1)
	v_mfma_f32_16x16x32_bf16 v[42:45], v[140:143], v[186:189], v[42:45]
	v_mfma_f32_16x16x32_bf16 v[42:45], v[144:147], v[190:193], v[42:45]
	v_mfma_f32_16x16x32_bf16 v[30:33], v[132:135], v[198:201], v[30:33]
	v_mfma_f32_16x16x32_bf16 v[30:33], v[136:139], v[204:207], v[30:33]
	v_mfma_f32_16x16x32_bf16 v[26:29], v[140:143], v[198:201], v[26:29]
	v_mfma_f32_16x16x32_bf16 v[26:29], v[144:147], v[204:207], v[26:29]
	v_mfma_f32_16x16x32_bf16 v[14:17], v[132:135], v[212:215], v[14:17]
	v_mfma_f32_16x16x32_bf16 v[14:17], v[136:139], v[216:219], v[14:17]
	s_waitcnt lgkmcnt(0)
	v_mfma_f32_16x16x32_bf16 v[10:13], v[140:143], v[212:215], v[10:13]
	v_mfma_f32_16x16x32_bf16 v[10:13], v[144:147], v[216:219], v[10:13]
	s_setprio 0
	s_setprio 1
	v_mfma_f32_16x16x32_bf16 v[54:57], v[148:151], v[178:181], v[54:57]
	v_mfma_f32_16x16x32_bf16 v[54:57], v[158:161], v[182:185], v[54:57]
	v_mfma_f32_16x16x32_bf16 v[50:53], v[162:165], v[178:181], v[50:53]
	v_mfma_f32_16x16x32_bf16 v[50:53], v[174:177], v[182:185], v[50:53]
	v_mfma_f32_16x16x32_bf16 v[38:41], v[148:151], v[186:189], v[38:41]
	v_mfma_f32_16x16x32_bf16 v[38:41], v[158:161], v[190:193], v[38:41]
	v_mfma_f32_16x16x32_bf16 v[34:37], v[162:165], v[186:189], v[34:37]
	v_mfma_f32_16x16x32_bf16 v[34:37], v[174:177], v[190:193], v[34:37]
	v_mfma_f32_16x16x32_bf16 v[22:25], v[148:151], v[198:201], v[22:25]
	v_mfma_f32_16x16x32_bf16 v[22:25], v[158:161], v[204:207], v[22:25]
	v_mfma_f32_16x16x32_bf16 v[18:21], v[162:165], v[198:201], v[18:21]
	v_mfma_f32_16x16x32_bf16 v[18:21], v[174:177], v[204:207], v[18:21]
	s_setprio 2
	s_barrier
	v_mfma_f32_16x16x32_bf16 v[6:9], v[148:151], v[212:215], v[6:9]
	v_mfma_f32_16x16x32_bf16 v[6:9], v[158:161], v[216:219], v[6:9]
	v_mfma_f32_16x16x32_bf16 v[2:5], v[162:165], v[212:215], v[2:5]
	v_mfma_f32_16x16x32_bf16 v[2:5], v[174:177], v[216:219], v[2:5]
	s_setprio 0
	s_nop 0
	ds_read_b128 v[132:135], v171
	ds_read_b128 v[136:139], v171 offset:1024
	ds_read_b128 v[140:143], v171 offset:2048
	ds_read_b128 v[144:147], v171 offset:3072
	ds_read_b128 v[148:151], v172
	ds_read_b128 v[158:161], v172 offset:1024
	ds_read_b128 v[162:165], v172 offset:2048
	ds_read_b128 v[174:177], v172 offset:3072
	ds_read_b128 v[178:181], v170 offset:32768
	ds_read_b128 v[182:185], v170 offset:33792
	ds_read_b128 v[186:189], v170 offset:34816
	ds_read_b128 v[190:193], v170 offset:35840
	ds_read_b128 v[198:201], v170 offset:36864
	ds_read_b128 v[204:207], v170 offset:37888
	ds_read_b128 v[212:215], v170 offset:38912
	ds_read_b128 v[216:219], v170 offset:39936
	s_add_u32 s48, s48, 0x4000
	s_addc_u32 s49, s49, 0
	s_mov_b32 m0, s56
	s_nop 0
	global_load_lds_dwordx4 v202, s[48:49]
	s_add_u32 m0, s56, 0x2000
	s_nop 0
	global_load_lds_dwordx4 v203, s[48:49]
	s_waitcnt vmcnt(8)
	s_waitcnt lgkmcnt(0)
	s_setprio 1
	s_barrier
	v_mfma_f32_16x16x32_bf16 v[126:129], v[132:135], v[178:181], v[126:129]
	v_mfma_f32_16x16x32_bf16 v[126:129], v[136:139], v[182:185], v[126:129]
	s_waitcnt lgkmcnt(5)
	v_mfma_f32_16x16x32_bf16 v[122:125], v[140:143], v[178:181], v[122:125]
	v_mfma_f32_16x16x32_bf16 v[122:125], v[144:147], v[182:185], v[122:125]
	s_waitcnt lgkmcnt(3)
	v_mfma_f32_16x16x32_bf16 v[110:113], v[132:135], v[186:189], v[110:113]
	v_mfma_f32_16x16x32_bf16 v[110:113], v[136:139], v[190:193], v[110:113]
	s_waitcnt lgkmcnt(1)
	v_mfma_f32_16x16x32_bf16 v[106:109], v[140:143], v[186:189], v[106:109]
	v_mfma_f32_16x16x32_bf16 v[106:109], v[144:147], v[190:193], v[106:109]
	v_mfma_f32_16x16x32_bf16 v[94:97], v[132:135], v[198:201], v[94:97]
	v_mfma_f32_16x16x32_bf16 v[94:97], v[136:139], v[204:207], v[94:97]
	v_mfma_f32_16x16x32_bf16 v[90:93], v[140:143], v[198:201], v[90:93]
	v_mfma_f32_16x16x32_bf16 v[90:93], v[144:147], v[204:207], v[90:93]
	v_mfma_f32_16x16x32_bf16 v[78:81], v[132:135], v[212:215], v[78:81]
	v_mfma_f32_16x16x32_bf16 v[78:81], v[136:139], v[216:219], v[78:81]
	s_waitcnt lgkmcnt(0)
	v_mfma_f32_16x16x32_bf16 v[74:77], v[140:143], v[212:215], v[74:77]
	v_mfma_f32_16x16x32_bf16 v[74:77], v[144:147], v[216:219], v[74:77]
	s_setprio 0
	s_setprio 1
	v_mfma_f32_16x16x32_bf16 v[118:121], v[148:151], v[178:181], v[118:121]
	v_mfma_f32_16x16x32_bf16 v[118:121], v[158:161], v[182:185], v[118:121]
	v_mfma_f32_16x16x32_bf16 v[114:117], v[162:165], v[178:181], v[114:117]
	v_mfma_f32_16x16x32_bf16 v[114:117], v[174:177], v[182:185], v[114:117]
	v_mfma_f32_16x16x32_bf16 v[102:105], v[148:151], v[186:189], v[102:105]
	v_mfma_f32_16x16x32_bf16 v[102:105], v[158:161], v[190:193], v[102:105]
	v_mfma_f32_16x16x32_bf16 v[98:101], v[162:165], v[186:189], v[98:101]
	v_mfma_f32_16x16x32_bf16 v[98:101], v[174:177], v[190:193], v[98:101]
	v_mfma_f32_16x16x32_bf16 v[86:89], v[148:151], v[198:201], v[86:89]
	v_mfma_f32_16x16x32_bf16 v[86:89], v[158:161], v[204:207], v[86:89]
	v_mfma_f32_16x16x32_bf16 v[82:85], v[162:165], v[198:201], v[82:85]
	v_mfma_f32_16x16x32_bf16 v[82:85], v[174:177], v[204:207], v[82:85]
	s_setprio 2
	s_barrier
	v_mfma_f32_16x16x32_bf16 v[70:73], v[148:151], v[212:215], v[70:73]
	v_mfma_f32_16x16x32_bf16 v[70:73], v[158:161], v[216:219], v[70:73]
	v_mfma_f32_16x16x32_bf16 v[66:69], v[162:165], v[212:215], v[66:69]
	v_mfma_f32_16x16x32_bf16 v[66:69], v[174:177], v[216:219], v[66:69]
	s_setprio 0
	s_nop 0
	ds_read_b128 v[178:181], v170 offset:49152
	ds_read_b128 v[182:185], v170 offset:50176
	ds_read_b128 v[186:189], v170 offset:51200
	ds_read_b128 v[190:193], v170 offset:52224
	ds_read_b128 v[198:201], v170 offset:53248
	ds_read_b128 v[204:207], v170 offset:54272
	ds_read_b128 v[212:215], v170 offset:55296
	ds_read_b128 v[216:219], v170 offset:56320
	s_mov_b32 m0, s59
	s_nop 0
	global_load_lds_dwordx4 v202, s[46:47]
	s_add_u32 m0, s59, 0x2000
	s_nop 0
	global_load_lds_dwordx4 v203, s[46:47]
	s_add_u32 s40, s40, 0xc000
	s_addc_u32 s41, s41, 0
	s_mov_b32 m0, s62
	s_nop 0
	global_load_lds_dwordx4 v202, s[40:41]
	s_add_u32 m0, s62, 0x2000
	s_nop 0
	global_load_lds_dwordx4 v203, s[40:41]
	s_nop 0
	s_mov_b32 m0, s61
	s_nop 0
	global_load_lds_dwordx4 v202, s[42:43]
	s_add_u32 m0, s61, 0x2000
	s_nop 0
	global_load_lds_dwordx4 v203, s[42:43]
	s_waitcnt vmcnt(8)
	s_waitcnt lgkmcnt(0)
	s_setprio 1
	s_barrier
	v_mfma_f32_16x16x32_bf16 v[62:65], v[132:135], v[178:181], v[62:65]
	v_mfma_f32_16x16x32_bf16 v[62:65], v[136:139], v[182:185], v[62:65]
	s_waitcnt lgkmcnt(5)
	v_mfma_f32_16x16x32_bf16 v[58:61], v[140:143], v[178:181], v[58:61]
	v_mfma_f32_16x16x32_bf16 v[58:61], v[144:147], v[182:185], v[58:61]
	s_waitcnt lgkmcnt(3)
	v_mfma_f32_16x16x32_bf16 v[46:49], v[132:135], v[186:189], v[46:49]
	v_mfma_f32_16x16x32_bf16 v[46:49], v[136:139], v[190:193], v[46:49]
	s_waitcnt lgkmcnt(1)
	v_mfma_f32_16x16x32_bf16 v[42:45], v[140:143], v[186:189], v[42:45]
	v_mfma_f32_16x16x32_bf16 v[42:45], v[144:147], v[190:193], v[42:45]
	v_mfma_f32_16x16x32_bf16 v[30:33], v[132:135], v[198:201], v[30:33]
	v_mfma_f32_16x16x32_bf16 v[30:33], v[136:139], v[204:207], v[30:33]
	v_mfma_f32_16x16x32_bf16 v[26:29], v[140:143], v[198:201], v[26:29]
	v_mfma_f32_16x16x32_bf16 v[26:29], v[144:147], v[204:207], v[26:29]
	v_mfma_f32_16x16x32_bf16 v[14:17], v[132:135], v[212:215], v[14:17]
	v_mfma_f32_16x16x32_bf16 v[14:17], v[136:139], v[216:219], v[14:17]
	s_waitcnt lgkmcnt(0)
	v_mfma_f32_16x16x32_bf16 v[10:13], v[140:143], v[212:215], v[10:13]
	v_mfma_f32_16x16x32_bf16 v[10:13], v[144:147], v[216:219], v[10:13]
	s_setprio 0
	s_setprio 1
	v_mfma_f32_16x16x32_bf16 v[54:57], v[148:151], v[178:181], v[54:57]
	v_mfma_f32_16x16x32_bf16 v[54:57], v[158:161], v[182:185], v[54:57]
	v_mfma_f32_16x16x32_bf16 v[50:53], v[162:165], v[178:181], v[50:53]
	v_mfma_f32_16x16x32_bf16 v[50:53], v[174:177], v[182:185], v[50:53]
	v_mfma_f32_16x16x32_bf16 v[38:41], v[148:151], v[186:189], v[38:41]
	v_mfma_f32_16x16x32_bf16 v[38:41], v[158:161], v[190:193], v[38:41]
	v_mfma_f32_16x16x32_bf16 v[34:37], v[162:165], v[186:189], v[34:37]
	v_mfma_f32_16x16x32_bf16 v[34:37], v[174:177], v[190:193], v[34:37]
	v_mfma_f32_16x16x32_bf16 v[22:25], v[148:151], v[198:201], v[22:25]
	v_mfma_f32_16x16x32_bf16 v[22:25], v[158:161], v[204:207], v[22:25]
	v_mfma_f32_16x16x32_bf16 v[18:21], v[162:165], v[198:201], v[18:21]
	v_mfma_f32_16x16x32_bf16 v[18:21], v[174:177], v[204:207], v[18:21]
	s_setprio 2
	s_barrier
	v_mfma_f32_16x16x32_bf16 v[6:9], v[148:151], v[212:215], v[6:9]
	v_mfma_f32_16x16x32_bf16 v[6:9], v[158:161], v[216:219], v[6:9]
	v_mfma_f32_16x16x32_bf16 v[2:5], v[162:165], v[212:215], v[2:5]
	v_mfma_f32_16x16x32_bf16 v[2:5], v[174:177], v[216:219], v[2:5]
	s_setprio 0
	s_nop 0
	s_add_i32 s75, s75, 2
	s_add_u32 s6, s6, 0x10000
	s_addc_u32 s7, s7, 0
	s_cmp_gt_u32 s75, 5
	s_cbranch_scc1 .LBB0_1376
	v_mov_b32_e32 v131, v130
	s_branch .LBB0_1372

.LBB0_1519:
	s_add_i32 s26, s58, 2
	s_lshl_b64 s[54:55], s[26:27], 15
	s_add_u32 s17, s18, s54
	s_addc_u32 s59, s19, s55
	s_and_b64 s[50:51], s[12:13], exec
	s_cselect_b32 s51, s59, s41
	s_cselect_b32 s50, s17, s56
	s_add_u32 s17, s20, s54
	s_waitcnt vmcnt(8)
	s_addc_u32 s54, s21, s55
	s_waitcnt lgkmcnt(0)
	s_and_b64 s[12:13], s[12:13], exec
	s_cselect_b32 s13, s54, s39
	s_cselect_b32 s12, s17, s57
	s_setprio 1
	s_barrier
	v_mfma_f32_16x16x32_bf16 v[126:129], v[146:149], v[186:189], v[126:129]
	v_mfma_f32_16x16x32_bf16 v[126:129], v[150:153], v[190:193], v[126:129]
	s_waitcnt lgkmcnt(5)
	v_mfma_f32_16x16x32_bf16 v[122:125], v[154:157], v[186:189], v[122:125]
	v_mfma_f32_16x16x32_bf16 v[122:125], v[158:161], v[190:193], v[122:125]
	s_waitcnt lgkmcnt(3)
	v_mfma_f32_16x16x32_bf16 v[118:121], v[146:149], v[178:181], v[118:121]
	v_mfma_f32_16x16x32_bf16 v[118:121], v[150:153], v[182:185], v[118:121]
	s_waitcnt lgkmcnt(1)
	v_mfma_f32_16x16x32_bf16 v[114:117], v[154:157], v[178:181], v[114:117]
	v_mfma_f32_16x16x32_bf16 v[114:117], v[158:161], v[182:185], v[114:117]
	v_mfma_f32_16x16x32_bf16 v[110:113], v[146:149], v[170:173], v[110:113]
	v_mfma_f32_16x16x32_bf16 v[110:113], v[150:153], v[174:177], v[110:113]
	v_mfma_f32_16x16x32_bf16 v[106:109], v[154:157], v[170:173], v[106:109]
	v_mfma_f32_16x16x32_bf16 v[106:109], v[158:161], v[174:177], v[106:109]
	v_mfma_f32_16x16x32_bf16 v[102:105], v[146:149], v[162:165], v[102:105]
	v_mfma_f32_16x16x32_bf16 v[102:105], v[150:153], v[166:169], v[102:105]
	s_waitcnt lgkmcnt(0)
	v_mfma_f32_16x16x32_bf16 v[98:101], v[154:157], v[162:165], v[98:101]
	v_mfma_f32_16x16x32_bf16 v[98:101], v[158:161], v[166:169], v[98:101]
	s_setprio 0
	s_setprio 1
	v_mfma_f32_16x16x32_bf16 v[94:97], v[130:133], v[186:189], v[94:97]
	v_mfma_f32_16x16x32_bf16 v[94:97], v[134:137], v[190:193], v[94:97]
	v_mfma_f32_16x16x32_bf16 v[90:93], v[138:141], v[186:189], v[90:93]
	v_mfma_f32_16x16x32_bf16 v[90:93], v[142:145], v[190:193], v[90:93]
	v_mfma_f32_16x16x32_bf16 v[86:89], v[130:133], v[178:181], v[86:89]
	v_mfma_f32_16x16x32_bf16 v[86:89], v[134:137], v[182:185], v[86:89]
	v_mfma_f32_16x16x32_bf16 v[82:85], v[138:141], v[178:181], v[82:85]
	v_mfma_f32_16x16x32_bf16 v[82:85], v[142:145], v[182:185], v[82:85]
	v_mfma_f32_16x16x32_bf16 v[78:81], v[130:133], v[170:173], v[78:81]
	v_mfma_f32_16x16x32_bf16 v[78:81], v[134:137], v[174:177], v[78:81]
	v_mfma_f32_16x16x32_bf16 v[74:77], v[138:141], v[170:173], v[74:77]
	v_mfma_f32_16x16x32_bf16 v[74:77], v[142:145], v[174:177], v[74:77]
	s_setprio 2
	s_barrier
	v_mfma_f32_16x16x32_bf16 v[70:73], v[130:133], v[162:165], v[70:73]
	v_mfma_f32_16x16x32_bf16 v[70:73], v[134:137], v[166:169], v[70:73]
	v_mfma_f32_16x16x32_bf16 v[66:69], v[138:141], v[162:165], v[66:69]
	v_mfma_f32_16x16x32_bf16 v[66:69], v[142:145], v[166:169], v[66:69]
	s_setprio 0
	s_nop 0
	ds_read_b128 v[186:189], v217 offset:16384
	ds_read_b128 v[190:193], v217 offset:17408
	ds_read_b128 v[178:181], v217 offset:18432
	ds_read_b128 v[182:185], v217 offset:19456
	ds_read_b128 v[170:173], v217 offset:20480
	ds_read_b128 v[174:177], v217 offset:21504
	ds_read_b128 v[162:165], v217 offset:22528
	ds_read_b128 v[166:169], v217 offset:23552
	s_mov_b32 m0, s66
	s_nop 0
	global_load_lds_dwordx4 v195, s[12:13]
	s_add_u32 m0, s66, 0x2000
	s_nop 0
	global_load_lds_dwordx4 v212, s[12:13]
	s_add_u32 s54, s12, 0x4000
	s_addc_u32 s55, s13, 0
	s_mov_b32 m0, s67
	s_nop 0
	global_load_lds_dwordx4 v195, s[54:55]
	s_add_u32 m0, s67, 0x2000
	s_nop 0
	global_load_lds_dwordx4 v212, s[54:55]
	s_andn2_b64 vcc, exec, s[52:53]
	s_mov_b32 m0, s15
	s_nop 0
	global_load_lds_dwordx4 v195, s[50:51]
	s_add_u32 m0, s15, 0x2000
	s_nop 0
	global_load_lds_dwordx4 v212, s[50:51]
	s_cbranch_vccnz .LBB0_1521
	v_mov_b32_e32 v2, 0
	v_mov_b32_e32 v3, v2
	v_mov_b32_e32 v4, v2
	v_mov_b32_e32 v5, v2
	v_mov_b32_e32 v6, v2
	v_mov_b32_e32 v7, v2
	v_mov_b32_e32 v8, v2
	v_mov_b32_e32 v9, v2
	v_mov_b32_e32 v10, v2
	v_mov_b32_e32 v11, v2
	v_mov_b32_e32 v12, v2
	v_mov_b32_e32 v13, v2
	v_mov_b32_e32 v14, v2
	v_mov_b32_e32 v15, v2
	v_mov_b32_e32 v16, v2
	v_mov_b32_e32 v17, v2
	v_mov_b32_e32 v18, v2
	v_mov_b32_e32 v19, v2
	v_mov_b32_e32 v20, v2
	v_mov_b32_e32 v21, v2
	v_mov_b32_e32 v22, v2
	v_mov_b32_e32 v23, v2
	v_mov_b32_e32 v24, v2
	v_mov_b32_e32 v25, v2
	v_mov_b32_e32 v26, v2
	v_mov_b32_e32 v27, v2
	v_mov_b32_e32 v28, v2
	v_mov_b32_e32 v29, v2
	v_mov_b32_e32 v30, v2
	v_mov_b32_e32 v31, v2
	v_mov_b32_e32 v32, v2
	v_mov_b32_e32 v33, v2
	v_mov_b32_e32 v34, v2
	v_mov_b32_e32 v35, v2
	v_mov_b32_e32 v36, v2
	v_mov_b32_e32 v37, v2
	v_mov_b32_e32 v38, v2
	v_mov_b32_e32 v39, v2
	v_mov_b32_e32 v40, v2
	v_mov_b32_e32 v41, v2
	v_mov_b32_e32 v42, v2
	v_mov_b32_e32 v43, v2
	v_mov_b32_e32 v44, v2
	v_mov_b32_e32 v45, v2
	v_mov_b32_e32 v46, v2
	v_mov_b32_e32 v47, v2
	v_mov_b32_e32 v48, v2
	v_mov_b32_e32 v49, v2
	v_mov_b32_e32 v50, v2
	v_mov_b32_e32 v51, v2
	v_mov_b32_e32 v52, v2
	v_mov_b32_e32 v53, v2
	v_mov_b32_e32 v54, v2
	v_mov_b32_e32 v55, v2
	v_mov_b32_e32 v56, v2
	v_mov_b32_e32 v57, v2
	v_mov_b32_e32 v58, v2
	v_mov_b32_e32 v59, v2
	v_mov_b32_e32 v60, v2
	v_mov_b32_e32 v61, v2
	v_mov_b32_e32 v62, v2
	v_mov_b32_e32 v63, v2
	v_mov_b32_e32 v64, v2
	v_mov_b32_e32 v65, v2
.LBB0_1521:
	s_waitcnt vmcnt(8)
	s_add_u32 s52, s50, 0x8000
	s_waitcnt lgkmcnt(0)
	s_addc_u32 s53, s51, 0
	s_add_u32 s54, s12, 0x8000
	s_addc_u32 s55, s13, 0
	s_setprio 1
	s_barrier
	v_mfma_f32_16x16x32_bf16 v[62:65], v[146:149], v[186:189], v[62:65]
	v_mfma_f32_16x16x32_bf16 v[62:65], v[150:153], v[190:193], v[62:65]
	s_waitcnt lgkmcnt(5)
	v_mfma_f32_16x16x32_bf16 v[58:61], v[154:157], v[186:189], v[58:61]
	v_mfma_f32_16x16x32_bf16 v[58:61], v[158:161], v[190:193], v[58:61]
	s_waitcnt lgkmcnt(3)
	v_mfma_f32_16x16x32_bf16 v[54:57], v[146:149], v[178:181], v[54:57]
	v_mfma_f32_16x16x32_bf16 v[54:57], v[150:153], v[182:185], v[54:57]
	s_waitcnt lgkmcnt(1)
	v_mfma_f32_16x16x32_bf16 v[50:53], v[154:157], v[178:181], v[50:53]
	v_mfma_f32_16x16x32_bf16 v[50:53], v[158:161], v[182:185], v[50:53]
	v_mfma_f32_16x16x32_bf16 v[46:49], v[146:149], v[170:173], v[46:49]
	v_mfma_f32_16x16x32_bf16 v[46:49], v[150:153], v[174:177], v[46:49]
	v_mfma_f32_16x16x32_bf16 v[42:45], v[154:157], v[170:173], v[42:45]
	v_mfma_f32_16x16x32_bf16 v[42:45], v[158:161], v[174:177], v[42:45]
	v_mfma_f32_16x16x32_bf16 v[38:41], v[146:149], v[162:165], v[38:41]
	v_mfma_f32_16x16x32_bf16 v[38:41], v[150:153], v[166:169], v[38:41]
	s_waitcnt lgkmcnt(0)
	v_mfma_f32_16x16x32_bf16 v[34:37], v[154:157], v[162:165], v[34:37]
	v_mfma_f32_16x16x32_bf16 v[34:37], v[158:161], v[166:169], v[34:37]
	s_setprio 0
	s_setprio 1
	v_mfma_f32_16x16x32_bf16 v[30:33], v[130:133], v[186:189], v[30:33]
	v_mfma_f32_16x16x32_bf16 v[30:33], v[134:137], v[190:193], v[30:33]
	v_mfma_f32_16x16x32_bf16 v[26:29], v[138:141], v[186:189], v[26:29]
	v_mfma_f32_16x16x32_bf16 v[26:29], v[142:145], v[190:193], v[26:29]
	v_mfma_f32_16x16x32_bf16 v[22:25], v[130:133], v[178:181], v[22:25]
	v_mfma_f32_16x16x32_bf16 v[22:25], v[134:137], v[182:185], v[22:25]
	v_mfma_f32_16x16x32_bf16 v[18:21], v[138:141], v[178:181], v[18:21]
	v_mfma_f32_16x16x32_bf16 v[18:21], v[142:145], v[182:185], v[18:21]
	v_mfma_f32_16x16x32_bf16 v[14:17], v[130:133], v[170:173], v[14:17]
	v_mfma_f32_16x16x32_bf16 v[14:17], v[134:137], v[174:177], v[14:17]
	v_mfma_f32_16x16x32_bf16 v[10:13], v[138:141], v[170:173], v[10:13]
	v_mfma_f32_16x16x32_bf16 v[10:13], v[142:145], v[174:177], v[10:13]
	s_setprio 2
	s_barrier
	v_mfma_f32_16x16x32_bf16 v[6:9], v[130:133], v[162:165], v[6:9]
	v_mfma_f32_16x16x32_bf16 v[6:9], v[134:137], v[166:169], v[6:9]
	v_mfma_f32_16x16x32_bf16 v[2:5], v[138:141], v[162:165], v[2:5]
	v_mfma_f32_16x16x32_bf16 v[2:5], v[142:145], v[166:169], v[2:5]
	s_setprio 0
	s_nop 0
	v_add_u32_e32 v142, 0x18000, v216
	v_add_u32_e32 v158, 0x1c000, v216
	ds_read_b128 v[130:133], v142
	ds_read_b128 v[134:137], v142 offset:1024
	ds_read_b128 v[138:141], v142 offset:2048
	ds_read_b128 v[142:145], v142 offset:3072
	ds_read_b128 v[146:149], v158
	ds_read_b128 v[150:153], v158 offset:1024
	ds_read_b128 v[154:157], v158 offset:2048
	ds_read_b128 v[158:161], v158 offset:3072
	ds_read_b128 v[162:165], v217 offset:32768
	ds_read_b128 v[166:169], v217 offset:33792
	ds_read_b128 v[170:173], v217 offset:34816
	ds_read_b128 v[174:177], v217 offset:35840
	ds_read_b128 v[178:181], v217 offset:36864
	ds_read_b128 v[182:185], v217 offset:37888
	ds_read_b128 v[186:189], v217 offset:38912
	ds_read_b128 v[190:193], v217 offset:39936
	s_add_u32 s50, s50, 0x4000
	s_addc_u32 s51, s51, 0
	s_mov_b32 m0, s68
	s_nop 0
	global_load_lds_dwordx4 v195, s[50:51]
	s_add_u32 m0, s68, 0x2000
	s_nop 0
	global_load_lds_dwordx4 v212, s[50:51]
	s_waitcnt vmcnt(8)
	s_waitcnt lgkmcnt(0)
	s_setprio 1
	s_barrier
	v_mfma_f32_16x16x32_bf16 v[126:129], v[130:133], v[162:165], v[126:129]
	v_mfma_f32_16x16x32_bf16 v[126:129], v[134:137], v[166:169], v[126:129]
	s_waitcnt lgkmcnt(5)
	v_mfma_f32_16x16x32_bf16 v[122:125], v[138:141], v[162:165], v[122:125]
	v_mfma_f32_16x16x32_bf16 v[122:125], v[142:145], v[166:169], v[122:125]
	s_waitcnt lgkmcnt(3)
	v_mfma_f32_16x16x32_bf16 v[118:121], v[130:133], v[170:173], v[118:121]
	v_mfma_f32_16x16x32_bf16 v[118:121], v[134:137], v[174:177], v[118:121]
	s_waitcnt lgkmcnt(1)
	v_mfma_f32_16x16x32_bf16 v[114:117], v[138:141], v[170:173], v[114:117]
	v_mfma_f32_16x16x32_bf16 v[114:117], v[142:145], v[174:177], v[114:117]
	v_mfma_f32_16x16x32_bf16 v[110:113], v[130:133], v[178:181], v[110:113]
	v_mfma_f32_16x16x32_bf16 v[110:113], v[134:137], v[182:185], v[110:113]
	v_mfma_f32_16x16x32_bf16 v[106:109], v[138:141], v[178:181], v[106:109]
	v_mfma_f32_16x16x32_bf16 v[106:109], v[142:145], v[182:185], v[106:109]
	v_mfma_f32_16x16x32_bf16 v[102:105], v[130:133], v[186:189], v[102:105]
	v_mfma_f32_16x16x32_bf16 v[102:105], v[134:137], v[190:193], v[102:105]
	s_waitcnt lgkmcnt(0)
	v_mfma_f32_16x16x32_bf16 v[98:101], v[138:141], v[186:189], v[98:101]
	v_mfma_f32_16x16x32_bf16 v[98:101], v[142:145], v[190:193], v[98:101]
	s_setprio 0
	s_setprio 1
	v_mfma_f32_16x16x32_bf16 v[94:97], v[146:149], v[162:165], v[94:97]
	v_mfma_f32_16x16x32_bf16 v[94:97], v[150:153], v[166:169], v[94:97]
	v_mfma_f32_16x16x32_bf16 v[90:93], v[154:157], v[162:165], v[90:93]
	v_mfma_f32_16x16x32_bf16 v[90:93], v[158:161], v[166:169], v[90:93]
	v_mfma_f32_16x16x32_bf16 v[86:89], v[146:149], v[170:173], v[86:89]
	v_mfma_f32_16x16x32_bf16 v[86:89], v[150:153], v[174:177], v[86:89]
	v_mfma_f32_16x16x32_bf16 v[82:85], v[154:157], v[170:173], v[82:85]
	v_mfma_f32_16x16x32_bf16 v[82:85], v[158:161], v[174:177], v[82:85]
	v_mfma_f32_16x16x32_bf16 v[78:81], v[146:149], v[178:181], v[78:81]
	v_mfma_f32_16x16x32_bf16 v[78:81], v[150:153], v[182:185], v[78:81]
	v_mfma_f32_16x16x32_bf16 v[74:77], v[154:157], v[178:181], v[74:77]
	v_mfma_f32_16x16x32_bf16 v[74:77], v[158:161], v[182:185], v[74:77]
	s_setprio 2
	s_barrier
	v_mfma_f32_16x16x32_bf16 v[70:73], v[146:149], v[186:189], v[70:73]
	v_mfma_f32_16x16x32_bf16 v[70:73], v[150:153], v[190:193], v[70:73]
	v_mfma_f32_16x16x32_bf16 v[66:69], v[154:157], v[186:189], v[66:69]
	v_mfma_f32_16x16x32_bf16 v[66:69], v[158:161], v[190:193], v[66:69]
	s_setprio 0
	s_nop 0
	ds_read_b128 v[162:165], v217 offset:49152
	ds_read_b128 v[166:169], v217 offset:50176
	ds_read_b128 v[170:173], v217 offset:51200
	ds_read_b128 v[174:177], v217 offset:52224
	ds_read_b128 v[178:181], v217 offset:53248
	ds_read_b128 v[182:185], v217 offset:54272
	ds_read_b128 v[186:189], v217 offset:55296
	ds_read_b128 v[190:193], v217 offset:56320
	s_mov_b32 m0, s72
	s_nop 0
	global_load_lds_dwordx4 v195, s[54:55]
	s_add_u32 m0, s72, 0x2000
	s_nop 0
	global_load_lds_dwordx4 v212, s[54:55]
	s_add_u32 s12, s12, 0xc000
	s_addc_u32 s13, s13, 0
	s_mov_b32 m0, s74
	s_nop 0
	global_load_lds_dwordx4 v195, s[12:13]
	s_add_u32 m0, s74, 0x2000
	s_nop 0
	global_load_lds_dwordx4 v212, s[12:13]
	s_nop 0
	s_mov_b32 m0, s73
	s_nop 0
	global_load_lds_dwordx4 v195, s[52:53]
	s_add_u32 m0, s73, 0x2000
	s_nop 0
	global_load_lds_dwordx4 v212, s[52:53]
	s_waitcnt vmcnt(8)
	s_waitcnt lgkmcnt(0)
	s_setprio 1
	s_barrier
	v_mfma_f32_16x16x32_bf16 v[62:65], v[130:133], v[162:165], v[62:65]
	v_mfma_f32_16x16x32_bf16 v[62:65], v[134:137], v[166:169], v[62:65]
	s_waitcnt lgkmcnt(5)
	v_mfma_f32_16x16x32_bf16 v[58:61], v[138:141], v[162:165], v[58:61]
	v_mfma_f32_16x16x32_bf16 v[58:61], v[142:145], v[166:169], v[58:61]
	s_waitcnt lgkmcnt(3)
	v_mfma_f32_16x16x32_bf16 v[54:57], v[130:133], v[170:173], v[54:57]
	v_mfma_f32_16x16x32_bf16 v[54:57], v[134:137], v[174:177], v[54:57]
	s_waitcnt lgkmcnt(1)
	v_mfma_f32_16x16x32_bf16 v[50:53], v[138:141], v[170:173], v[50:53]
	v_mfma_f32_16x16x32_bf16 v[50:53], v[142:145], v[174:177], v[50:53]
	v_mfma_f32_16x16x32_bf16 v[46:49], v[130:133], v[178:181], v[46:49]
	v_mfma_f32_16x16x32_bf16 v[46:49], v[134:137], v[182:185], v[46:49]
	v_mfma_f32_16x16x32_bf16 v[42:45], v[138:141], v[178:181], v[42:45]
	v_mfma_f32_16x16x32_bf16 v[42:45], v[142:145], v[182:185], v[42:45]
	v_mfma_f32_16x16x32_bf16 v[38:41], v[130:133], v[186:189], v[38:41]
	v_mfma_f32_16x16x32_bf16 v[38:41], v[134:137], v[190:193], v[38:41]
	s_waitcnt lgkmcnt(0)
	v_mfma_f32_16x16x32_bf16 v[34:37], v[138:141], v[186:189], v[34:37]
	v_mfma_f32_16x16x32_bf16 v[34:37], v[142:145], v[190:193], v[34:37]
	s_setprio 0
	s_setprio 1
	v_mfma_f32_16x16x32_bf16 v[30:33], v[146:149], v[162:165], v[30:33]
	v_mfma_f32_16x16x32_bf16 v[30:33], v[150:153], v[166:169], v[30:33]
	v_mfma_f32_16x16x32_bf16 v[26:29], v[154:157], v[162:165], v[26:29]
	v_mfma_f32_16x16x32_bf16 v[26:29], v[158:161], v[166:169], v[26:29]
	v_mfma_f32_16x16x32_bf16 v[22:25], v[146:149], v[170:173], v[22:25]
	v_mfma_f32_16x16x32_bf16 v[22:25], v[150:153], v[174:177], v[22:25]
	v_mfma_f32_16x16x32_bf16 v[18:21], v[154:157], v[170:173], v[18:21]
	v_mfma_f32_16x16x32_bf16 v[18:21], v[158:161], v[174:177], v[18:21]
	v_mfma_f32_16x16x32_bf16 v[14:17], v[146:149], v[178:181], v[14:17]
	v_mfma_f32_16x16x32_bf16 v[14:17], v[150:153], v[182:185], v[14:17]
	v_mfma_f32_16x16x32_bf16 v[10:13], v[154:157], v[178:181], v[10:13]
	v_mfma_f32_16x16x32_bf16 v[10:13], v[158:161], v[182:185], v[10:13]
	s_setprio 2
	s_barrier
	v_mfma_f32_16x16x32_bf16 v[6:9], v[146:149], v[186:189], v[6:9]
	v_mfma_f32_16x16x32_bf16 v[6:9], v[150:153], v[190:193], v[6:9]
	v_mfma_f32_16x16x32_bf16 v[2:5], v[154:157], v[186:189], v[2:5]
	v_mfma_f32_16x16x32_bf16 v[2:5], v[158:161], v[190:193], v[2:5]
	s_setprio 0
	s_nop 0
	s_cmp_gt_u32 s58, 13
	s_cbranch_scc1 .LBB0_1523
	v_mov_b32_e32 v130, v198
	s_mov_b32 s58, s26
	s_branch .LBB0_1498

.LBB0_1712:
	s_add_u32 s52, s48, 0x10000
	s_addc_u32 s53, s49, 0
	s_and_b64 s[48:49], s[46:47], exec
	s_cselect_b32 s49, s53, s25
	s_cselect_b32 s48, s52, s75
	s_add_u32 s13, s16, s13
	s_addc_u32 s52, s17, 0
	s_add_u32 s13, s13, 0x10000
	s_waitcnt vmcnt(8)
	s_addc_u32 s52, s52, 0
	s_waitcnt lgkmcnt(0)
	s_and_b64 s[46:47], s[46:47], exec
	s_cselect_b32 s47, s52, s27
	s_cselect_b32 s46, s13, s76
	s_setprio 1
	s_barrier
	v_mfma_f32_16x16x32_bf16 v[126:129], v[146:149], v[186:189], v[126:129]
	v_mfma_f32_16x16x32_bf16 v[126:129], v[150:153], v[190:193], v[126:129]
	s_waitcnt lgkmcnt(5)
	v_mfma_f32_16x16x32_bf16 v[122:125], v[154:157], v[186:189], v[122:125]
	v_mfma_f32_16x16x32_bf16 v[122:125], v[158:161], v[190:193], v[122:125]
	s_waitcnt lgkmcnt(3)
	v_mfma_f32_16x16x32_bf16 v[118:121], v[146:149], v[178:181], v[118:121]
	v_mfma_f32_16x16x32_bf16 v[118:121], v[150:153], v[182:185], v[118:121]
	s_waitcnt lgkmcnt(1)
	v_mfma_f32_16x16x32_bf16 v[114:117], v[154:157], v[178:181], v[114:117]
	v_mfma_f32_16x16x32_bf16 v[114:117], v[158:161], v[182:185], v[114:117]
	v_mfma_f32_16x16x32_bf16 v[110:113], v[146:149], v[170:173], v[110:113]
	v_mfma_f32_16x16x32_bf16 v[110:113], v[150:153], v[174:177], v[110:113]
	v_mfma_f32_16x16x32_bf16 v[106:109], v[154:157], v[170:173], v[106:109]
	v_mfma_f32_16x16x32_bf16 v[106:109], v[158:161], v[174:177], v[106:109]
	v_mfma_f32_16x16x32_bf16 v[102:105], v[146:149], v[162:165], v[102:105]
	v_mfma_f32_16x16x32_bf16 v[102:105], v[150:153], v[166:169], v[102:105]
	s_waitcnt lgkmcnt(0)
	v_mfma_f32_16x16x32_bf16 v[98:101], v[154:157], v[162:165], v[98:101]
	v_mfma_f32_16x16x32_bf16 v[98:101], v[158:161], v[166:169], v[98:101]
	s_setprio 0
	s_setprio 1
	v_mfma_f32_16x16x32_bf16 v[94:97], v[130:133], v[186:189], v[94:97]
	v_mfma_f32_16x16x32_bf16 v[94:97], v[134:137], v[190:193], v[94:97]
	v_mfma_f32_16x16x32_bf16 v[90:93], v[138:141], v[186:189], v[90:93]
	v_mfma_f32_16x16x32_bf16 v[90:93], v[142:145], v[190:193], v[90:93]
	v_mfma_f32_16x16x32_bf16 v[86:89], v[130:133], v[178:181], v[86:89]
	v_mfma_f32_16x16x32_bf16 v[86:89], v[134:137], v[182:185], v[86:89]
	v_mfma_f32_16x16x32_bf16 v[82:85], v[138:141], v[178:181], v[82:85]
	v_mfma_f32_16x16x32_bf16 v[82:85], v[142:145], v[182:185], v[82:85]
	v_mfma_f32_16x16x32_bf16 v[78:81], v[130:133], v[170:173], v[78:81]
	v_mfma_f32_16x16x32_bf16 v[78:81], v[134:137], v[174:177], v[78:81]
	v_mfma_f32_16x16x32_bf16 v[74:77], v[138:141], v[170:173], v[74:77]
	v_mfma_f32_16x16x32_bf16 v[74:77], v[142:145], v[174:177], v[74:77]
	s_setprio 2
	s_barrier
	v_mfma_f32_16x16x32_bf16 v[70:73], v[130:133], v[162:165], v[70:73]
	v_mfma_f32_16x16x32_bf16 v[70:73], v[134:137], v[166:169], v[70:73]
	v_mfma_f32_16x16x32_bf16 v[66:69], v[138:141], v[162:165], v[66:69]
	v_mfma_f32_16x16x32_bf16 v[66:69], v[142:145], v[166:169], v[66:69]
	s_setprio 0
	s_nop 0
	ds_read_b128 v[186:189], v209 offset:16384
	ds_read_b128 v[190:193], v209 offset:17408
	ds_read_b128 v[178:181], v209 offset:18432
	ds_read_b128 v[182:185], v209 offset:19456
	ds_read_b128 v[170:173], v209 offset:20480
	ds_read_b128 v[174:177], v209 offset:21504
	ds_read_b128 v[162:165], v209 offset:22528
	ds_read_b128 v[166:169], v209 offset:23552
	s_mov_b32 m0, s58
	s_nop 0
	global_load_lds_dwordx4 v195, s[46:47]
	s_add_u32 m0, s58, 0x2000
	s_nop 0
	global_load_lds_dwordx4 v203, s[46:47]
	s_add_u32 s52, s46, 0x4000
	s_addc_u32 s53, s47, 0
	s_mov_b32 m0, s59
	s_nop 0
	global_load_lds_dwordx4 v195, s[52:53]
	s_add_u32 m0, s59, 0x2000
	s_nop 0
	global_load_lds_dwordx4 v203, s[52:53]
	s_andn2_b64 vcc, exec, s[50:51]
	s_mov_b32 m0, s11
	s_nop 0
	global_load_lds_dwordx4 v195, s[48:49]
	s_add_u32 m0, s11, 0x2000
	s_nop 0
	global_load_lds_dwordx4 v203, s[48:49]
	s_cbranch_vccnz .LBB0_1714
	v_mov_b32_e32 v2, 0
	v_mov_b32_e32 v3, v2
	v_mov_b32_e32 v4, v2
	v_mov_b32_e32 v5, v2
	v_mov_b32_e32 v6, v2
	v_mov_b32_e32 v7, v2
	v_mov_b32_e32 v8, v2
	v_mov_b32_e32 v9, v2
	v_mov_b32_e32 v10, v2
	v_mov_b32_e32 v11, v2
	v_mov_b32_e32 v12, v2
	v_mov_b32_e32 v13, v2
	v_mov_b32_e32 v14, v2
	v_mov_b32_e32 v15, v2
	v_mov_b32_e32 v16, v2
	v_mov_b32_e32 v17, v2
	v_mov_b32_e32 v18, v2
	v_mov_b32_e32 v19, v2
	v_mov_b32_e32 v20, v2
	v_mov_b32_e32 v21, v2
	v_mov_b32_e32 v22, v2
	v_mov_b32_e32 v23, v2
	v_mov_b32_e32 v24, v2
	v_mov_b32_e32 v25, v2
	v_mov_b32_e32 v26, v2
	v_mov_b32_e32 v27, v2
	v_mov_b32_e32 v28, v2
	v_mov_b32_e32 v29, v2
	v_mov_b32_e32 v30, v2
	v_mov_b32_e32 v31, v2
	v_mov_b32_e32 v32, v2
	v_mov_b32_e32 v33, v2
	v_mov_b32_e32 v34, v2
	v_mov_b32_e32 v35, v2
	v_mov_b32_e32 v36, v2
	v_mov_b32_e32 v37, v2
	v_mov_b32_e32 v38, v2
	v_mov_b32_e32 v39, v2
	v_mov_b32_e32 v40, v2
	v_mov_b32_e32 v41, v2
	v_mov_b32_e32 v42, v2
	v_mov_b32_e32 v43, v2
	v_mov_b32_e32 v44, v2
	v_mov_b32_e32 v45, v2
	v_mov_b32_e32 v46, v2
	v_mov_b32_e32 v47, v2
	v_mov_b32_e32 v48, v2
	v_mov_b32_e32 v49, v2
	v_mov_b32_e32 v50, v2
	v_mov_b32_e32 v51, v2
	v_mov_b32_e32 v52, v2
	v_mov_b32_e32 v53, v2
	v_mov_b32_e32 v54, v2
	v_mov_b32_e32 v55, v2
	v_mov_b32_e32 v56, v2
	v_mov_b32_e32 v57, v2
	v_mov_b32_e32 v58, v2
	v_mov_b32_e32 v59, v2
	v_mov_b32_e32 v60, v2
	v_mov_b32_e32 v61, v2
	v_mov_b32_e32 v62, v2
	v_mov_b32_e32 v63, v2
	v_mov_b32_e32 v64, v2
	v_mov_b32_e32 v65, v2
.LBB0_1714:
	s_waitcnt vmcnt(8)
	s_add_u32 s50, s48, 0x8000
	s_waitcnt lgkmcnt(0)
	s_addc_u32 s51, s49, 0
	s_add_u32 s52, s46, 0x8000
	s_addc_u32 s53, s47, 0
	s_setprio 1
	s_barrier
	v_mfma_f32_16x16x32_bf16 v[62:65], v[146:149], v[186:189], v[62:65]
	v_mfma_f32_16x16x32_bf16 v[62:65], v[150:153], v[190:193], v[62:65]
	s_waitcnt lgkmcnt(5)
	v_mfma_f32_16x16x32_bf16 v[58:61], v[154:157], v[186:189], v[58:61]
	v_mfma_f32_16x16x32_bf16 v[58:61], v[158:161], v[190:193], v[58:61]
	s_waitcnt lgkmcnt(3)
	v_mfma_f32_16x16x32_bf16 v[54:57], v[146:149], v[178:181], v[54:57]
	v_mfma_f32_16x16x32_bf16 v[54:57], v[150:153], v[182:185], v[54:57]
	s_waitcnt lgkmcnt(1)
	v_mfma_f32_16x16x32_bf16 v[50:53], v[154:157], v[178:181], v[50:53]
	v_mfma_f32_16x16x32_bf16 v[50:53], v[158:161], v[182:185], v[50:53]
	v_mfma_f32_16x16x32_bf16 v[46:49], v[146:149], v[170:173], v[46:49]
	v_mfma_f32_16x16x32_bf16 v[46:49], v[150:153], v[174:177], v[46:49]
	v_mfma_f32_16x16x32_bf16 v[42:45], v[154:157], v[170:173], v[42:45]
	v_mfma_f32_16x16x32_bf16 v[42:45], v[158:161], v[174:177], v[42:45]
	v_mfma_f32_16x16x32_bf16 v[38:41], v[146:149], v[162:165], v[38:41]
	v_mfma_f32_16x16x32_bf16 v[38:41], v[150:153], v[166:169], v[38:41]
	s_waitcnt lgkmcnt(0)
	v_mfma_f32_16x16x32_bf16 v[34:37], v[154:157], v[162:165], v[34:37]
	v_mfma_f32_16x16x32_bf16 v[34:37], v[158:161], v[166:169], v[34:37]
	s_setprio 0
	s_setprio 1
	v_mfma_f32_16x16x32_bf16 v[30:33], v[130:133], v[186:189], v[30:33]
	v_mfma_f32_16x16x32_bf16 v[30:33], v[134:137], v[190:193], v[30:33]
	v_mfma_f32_16x16x32_bf16 v[26:29], v[138:141], v[186:189], v[26:29]
	v_mfma_f32_16x16x32_bf16 v[26:29], v[142:145], v[190:193], v[26:29]
	v_mfma_f32_16x16x32_bf16 v[22:25], v[130:133], v[178:181], v[22:25]
	v_mfma_f32_16x16x32_bf16 v[22:25], v[134:137], v[182:185], v[22:25]
	v_mfma_f32_16x16x32_bf16 v[18:21], v[138:141], v[178:181], v[18:21]
	v_mfma_f32_16x16x32_bf16 v[18:21], v[142:145], v[182:185], v[18:21]
	v_mfma_f32_16x16x32_bf16 v[14:17], v[130:133], v[170:173], v[14:17]
	v_mfma_f32_16x16x32_bf16 v[14:17], v[134:137], v[174:177], v[14:17]
	v_mfma_f32_16x16x32_bf16 v[10:13], v[138:141], v[170:173], v[10:13]
	v_mfma_f32_16x16x32_bf16 v[10:13], v[142:145], v[174:177], v[10:13]
	s_setprio 2
	s_barrier
	v_mfma_f32_16x16x32_bf16 v[6:9], v[130:133], v[162:165], v[6:9]
	v_mfma_f32_16x16x32_bf16 v[6:9], v[134:137], v[166:169], v[6:9]
	v_mfma_f32_16x16x32_bf16 v[2:5], v[138:141], v[162:165], v[2:5]
	v_mfma_f32_16x16x32_bf16 v[2:5], v[142:145], v[166:169], v[2:5]
	s_setprio 0
	s_nop 0
	v_add_u32_e32 v142, 0x18000, v208
	v_add_u32_e32 v158, 0x1c000, v208
	ds_read_b128 v[130:133], v142
	ds_read_b128 v[134:137], v142 offset:1024
	ds_read_b128 v[138:141], v142 offset:2048
	ds_read_b128 v[142:145], v142 offset:3072
	ds_read_b128 v[146:149], v158
	ds_read_b128 v[150:153], v158 offset:1024
	ds_read_b128 v[154:157], v158 offset:2048
	ds_read_b128 v[158:161], v158 offset:3072
	ds_read_b128 v[162:165], v209 offset:32768
	ds_read_b128 v[166:169], v209 offset:33792
	ds_read_b128 v[170:173], v209 offset:34816
	ds_read_b128 v[174:177], v209 offset:35840
	ds_read_b128 v[178:181], v209 offset:36864
	ds_read_b128 v[182:185], v209 offset:37888
	ds_read_b128 v[186:189], v209 offset:38912
	ds_read_b128 v[190:193], v209 offset:39936
	s_add_u32 s48, s48, 0x4000
	s_addc_u32 s49, s49, 0
	s_mov_b32 m0, s60
	s_nop 0
	global_load_lds_dwordx4 v195, s[48:49]
	s_add_u32 m0, s60, 0x2000
	s_nop 0
	global_load_lds_dwordx4 v203, s[48:49]
	s_waitcnt vmcnt(8)
	s_waitcnt lgkmcnt(0)
	s_setprio 1
	s_barrier
	v_mfma_f32_16x16x32_bf16 v[126:129], v[130:133], v[162:165], v[126:129]
	v_mfma_f32_16x16x32_bf16 v[126:129], v[134:137], v[166:169], v[126:129]
	s_waitcnt lgkmcnt(5)
	v_mfma_f32_16x16x32_bf16 v[122:125], v[138:141], v[162:165], v[122:125]
	v_mfma_f32_16x16x32_bf16 v[122:125], v[142:145], v[166:169], v[122:125]
	s_waitcnt lgkmcnt(3)
	v_mfma_f32_16x16x32_bf16 v[118:121], v[130:133], v[170:173], v[118:121]
	v_mfma_f32_16x16x32_bf16 v[118:121], v[134:137], v[174:177], v[118:121]
	s_waitcnt lgkmcnt(1)
	v_mfma_f32_16x16x32_bf16 v[114:117], v[138:141], v[170:173], v[114:117]
	v_mfma_f32_16x16x32_bf16 v[114:117], v[142:145], v[174:177], v[114:117]
	v_mfma_f32_16x16x32_bf16 v[110:113], v[130:133], v[178:181], v[110:113]
	v_mfma_f32_16x16x32_bf16 v[110:113], v[134:137], v[182:185], v[110:113]
	v_mfma_f32_16x16x32_bf16 v[106:109], v[138:141], v[178:181], v[106:109]
	v_mfma_f32_16x16x32_bf16 v[106:109], v[142:145], v[182:185], v[106:109]
	v_mfma_f32_16x16x32_bf16 v[102:105], v[130:133], v[186:189], v[102:105]
	v_mfma_f32_16x16x32_bf16 v[102:105], v[134:137], v[190:193], v[102:105]
	s_waitcnt lgkmcnt(0)
	v_mfma_f32_16x16x32_bf16 v[98:101], v[138:141], v[186:189], v[98:101]
	v_mfma_f32_16x16x32_bf16 v[98:101], v[142:145], v[190:193], v[98:101]
	s_setprio 0
	s_setprio 1
	v_mfma_f32_16x16x32_bf16 v[94:97], v[146:149], v[162:165], v[94:97]
	v_mfma_f32_16x16x32_bf16 v[94:97], v[150:153], v[166:169], v[94:97]
	v_mfma_f32_16x16x32_bf16 v[90:93], v[154:157], v[162:165], v[90:93]
	v_mfma_f32_16x16x32_bf16 v[90:93], v[158:161], v[166:169], v[90:93]
	v_mfma_f32_16x16x32_bf16 v[86:89], v[146:149], v[170:173], v[86:89]
	v_mfma_f32_16x16x32_bf16 v[86:89], v[150:153], v[174:177], v[86:89]
	v_mfma_f32_16x16x32_bf16 v[82:85], v[154:157], v[170:173], v[82:85]
	v_mfma_f32_16x16x32_bf16 v[82:85], v[158:161], v[174:177], v[82:85]
	v_mfma_f32_16x16x32_bf16 v[78:81], v[146:149], v[178:181], v[78:81]
	v_mfma_f32_16x16x32_bf16 v[78:81], v[150:153], v[182:185], v[78:81]
	v_mfma_f32_16x16x32_bf16 v[74:77], v[154:157], v[178:181], v[74:77]
	v_mfma_f32_16x16x32_bf16 v[74:77], v[158:161], v[182:185], v[74:77]
	s_setprio 2
	s_barrier
	v_mfma_f32_16x16x32_bf16 v[70:73], v[146:149], v[186:189], v[70:73]
	v_mfma_f32_16x16x32_bf16 v[70:73], v[150:153], v[190:193], v[70:73]
	v_mfma_f32_16x16x32_bf16 v[66:69], v[154:157], v[186:189], v[66:69]
	v_mfma_f32_16x16x32_bf16 v[66:69], v[158:161], v[190:193], v[66:69]
	s_setprio 0
	s_nop 0
	ds_read_b128 v[162:165], v209 offset:49152
	ds_read_b128 v[166:169], v209 offset:50176
	ds_read_b128 v[170:173], v209 offset:51200
	ds_read_b128 v[174:177], v209 offset:52224
	ds_read_b128 v[178:181], v209 offset:53248
	ds_read_b128 v[182:185], v209 offset:54272
	ds_read_b128 v[186:189], v209 offset:55296
	ds_read_b128 v[190:193], v209 offset:56320
	s_mov_b32 m0, s64
	s_nop 0
	global_load_lds_dwordx4 v195, s[52:53]
	s_add_u32 m0, s64, 0x2000
	s_nop 0
	global_load_lds_dwordx4 v203, s[52:53]
	s_add_u32 s46, s46, 0xc000
	s_addc_u32 s47, s47, 0
	s_mov_b32 m0, s66
	s_nop 0
	global_load_lds_dwordx4 v195, s[46:47]
	s_add_u32 m0, s66, 0x2000
	s_nop 0
	global_load_lds_dwordx4 v203, s[46:47]
	s_nop 0
	s_mov_b32 m0, s65
	s_nop 0
	global_load_lds_dwordx4 v195, s[50:51]
	s_add_u32 m0, s65, 0x2000
	s_nop 0
	global_load_lds_dwordx4 v203, s[50:51]
	s_waitcnt vmcnt(8)
	s_waitcnt lgkmcnt(0)
	s_setprio 1
	s_barrier
	v_mfma_f32_16x16x32_bf16 v[62:65], v[130:133], v[162:165], v[62:65]
	v_mfma_f32_16x16x32_bf16 v[62:65], v[134:137], v[166:169], v[62:65]
	s_waitcnt lgkmcnt(5)
	v_mfma_f32_16x16x32_bf16 v[58:61], v[138:141], v[162:165], v[58:61]
	v_mfma_f32_16x16x32_bf16 v[58:61], v[142:145], v[166:169], v[58:61]
	s_waitcnt lgkmcnt(3)
	v_mfma_f32_16x16x32_bf16 v[54:57], v[130:133], v[170:173], v[54:57]
	v_mfma_f32_16x16x32_bf16 v[54:57], v[134:137], v[174:177], v[54:57]
	s_waitcnt lgkmcnt(1)
	v_mfma_f32_16x16x32_bf16 v[50:53], v[138:141], v[170:173], v[50:53]
	v_mfma_f32_16x16x32_bf16 v[50:53], v[142:145], v[174:177], v[50:53]
	v_mfma_f32_16x16x32_bf16 v[46:49], v[130:133], v[178:181], v[46:49]
	v_mfma_f32_16x16x32_bf16 v[46:49], v[134:137], v[182:185], v[46:49]
	v_mfma_f32_16x16x32_bf16 v[42:45], v[138:141], v[178:181], v[42:45]
	v_mfma_f32_16x16x32_bf16 v[42:45], v[142:145], v[182:185], v[42:45]
	v_mfma_f32_16x16x32_bf16 v[38:41], v[130:133], v[186:189], v[38:41]
	v_mfma_f32_16x16x32_bf16 v[38:41], v[134:137], v[190:193], v[38:41]
	s_waitcnt lgkmcnt(0)
	v_mfma_f32_16x16x32_bf16 v[34:37], v[138:141], v[186:189], v[34:37]
	v_mfma_f32_16x16x32_bf16 v[34:37], v[142:145], v[190:193], v[34:37]
	s_setprio 0
	s_setprio 1
	v_mfma_f32_16x16x32_bf16 v[30:33], v[146:149], v[162:165], v[30:33]
	v_mfma_f32_16x16x32_bf16 v[30:33], v[150:153], v[166:169], v[30:33]
	v_mfma_f32_16x16x32_bf16 v[26:29], v[154:157], v[162:165], v[26:29]
	v_mfma_f32_16x16x32_bf16 v[26:29], v[158:161], v[166:169], v[26:29]
	v_mfma_f32_16x16x32_bf16 v[22:25], v[146:149], v[170:173], v[22:25]
	v_mfma_f32_16x16x32_bf16 v[22:25], v[150:153], v[174:177], v[22:25]
	v_mfma_f32_16x16x32_bf16 v[18:21], v[154:157], v[170:173], v[18:21]
	v_mfma_f32_16x16x32_bf16 v[18:21], v[158:161], v[174:177], v[18:21]
	v_mfma_f32_16x16x32_bf16 v[14:17], v[146:149], v[178:181], v[14:17]
	v_mfma_f32_16x16x32_bf16 v[14:17], v[150:153], v[182:185], v[14:17]
	v_mfma_f32_16x16x32_bf16 v[10:13], v[154:157], v[178:181], v[10:13]
	v_mfma_f32_16x16x32_bf16 v[10:13], v[158:161], v[182:185], v[10:13]
	s_setprio 2
	s_barrier
	v_mfma_f32_16x16x32_bf16 v[6:9], v[146:149], v[186:189], v[6:9]
	v_mfma_f32_16x16x32_bf16 v[6:9], v[150:153], v[190:193], v[6:9]
	v_mfma_f32_16x16x32_bf16 v[2:5], v[154:157], v[186:189], v[2:5]
	v_mfma_f32_16x16x32_bf16 v[2:5], v[158:161], v[190:193], v[2:5]
	s_setprio 0
	s_nop 0
	s_add_i32 s13, s77, 2
	s_cmp_gt_u32 s77, 13
	s_cbranch_scc1 .LBB0_1716
	s_mov_b32 s77, s13
	s_branch .LBB0_1693

.LBB0_1919:
	s_or_b64 exec, exec, s[10:11]
	s_add_u32 s50, s16, s6
	ds_read_b128 v[134:137], v201
	ds_read_b128 v[138:141], v201 offset:1024
	ds_read_b128 v[142:145], v201 offset:2048
	ds_read_b128 v[146:149], v201 offset:3072
	ds_read_b128 v[150:153], v202
	ds_read_b128 v[154:157], v202 offset:1024
	ds_read_b128 v[162:165], v202 offset:2048
	ds_read_b128 v[166:169], v202 offset:3072
	s_addc_u32 s51, s17, s7
	s_add_u32 s10, s50, 0x20000
	s_addc_u32 s11, s51, 0
	s_add_u32 s42, s75, s6
	s_addc_u32 s43, s76, s7
	s_cmp_eq_u32 s6, 0x60000
	s_cselect_b32 s46, s29, s10
	s_cselect_b32 s47, s20, s11
	s_cselect_b32 s11, s27, s43
	s_cselect_b32 s10, s48, s42
	s_add_u32 s42, s46, 0x8000
	s_addc_u32 s43, s47, 0
	s_add_u32 s44, s10, 0x8000
	s_addc_u32 s45, s11, 0
	ds_read_b128 v[170:173], v203
	ds_read_b128 v[174:177], v203 offset:1024
	ds_read_b128 v[178:181], v203 offset:2048
	ds_read_b128 v[182:185], v203 offset:3072
	ds_read_b128 v[186:189], v203 offset:4096
	ds_read_b128 v[190:193], v203 offset:5120
	ds_read_b128 v[212:215], v203 offset:6144
	ds_read_b128 v[216:219], v203 offset:7168
	s_add_u32 s50, s50, 0x1c000
	s_addc_u32 s51, s51, 0
	s_mov_b32 m0, s65
	s_nop 0
	global_load_lds_dwordx4 v195, s[50:51]
	s_add_u32 m0, s65, 0x2000
	s_nop 0
	global_load_lds_dwordx4 v197, s[50:51]
	s_waitcnt vmcnt(8)
	s_waitcnt lgkmcnt(0)
	s_setprio 1
	s_barrier
	v_mfma_f32_16x16x32_bf16 v[130:133], v[134:137], v[170:173], v[130:133]
	v_mfma_f32_16x16x32_bf16 v[126:129], v[142:145], v[170:173], v[126:129]
	s_waitcnt lgkmcnt(5)
	v_mfma_f32_16x16x32_bf16 v[110:113], v[134:137], v[178:181], v[110:113]
	v_mfma_f32_16x16x32_bf16 v[106:109], v[142:145], v[178:181], v[106:109]
	s_waitcnt lgkmcnt(3)
	v_mfma_f32_16x16x32_bf16 v[94:97], v[134:137], v[186:189], v[94:97]
	v_mfma_f32_16x16x32_bf16 v[90:93], v[142:145], v[186:189], v[90:93]
	s_waitcnt lgkmcnt(1)
	v_mfma_f32_16x16x32_bf16 v[78:81], v[134:137], v[212:215], v[78:81]
	v_mfma_f32_16x16x32_bf16 v[74:77], v[142:145], v[212:215], v[74:77]
	v_mfma_f32_16x16x32_bf16 v[130:133], v[138:141], v[174:177], v[130:133]
	v_mfma_f32_16x16x32_bf16 v[126:129], v[146:149], v[174:177], v[126:129]
	v_mfma_f32_16x16x32_bf16 v[110:113], v[138:141], v[182:185], v[110:113]
	v_mfma_f32_16x16x32_bf16 v[106:109], v[146:149], v[182:185], v[106:109]
	v_mfma_f32_16x16x32_bf16 v[94:97], v[138:141], v[190:193], v[94:97]
	v_mfma_f32_16x16x32_bf16 v[90:93], v[146:149], v[190:193], v[90:93]
	s_waitcnt lgkmcnt(0)
	v_mfma_f32_16x16x32_bf16 v[78:81], v[138:141], v[216:219], v[78:81]
	v_mfma_f32_16x16x32_bf16 v[74:77], v[146:149], v[216:219], v[74:77]
	s_setprio 0
	s_setprio 1
	v_mfma_f32_16x16x32_bf16 v[122:125], v[150:153], v[170:173], v[122:125]
	v_mfma_f32_16x16x32_bf16 v[116:119], v[162:165], v[170:173], v[118:121]
	v_mfma_f32_16x16x32_bf16 v[102:105], v[150:153], v[178:181], v[102:105]
	v_mfma_f32_16x16x32_bf16 v[98:101], v[162:165], v[178:181], v[98:101]
	v_mfma_f32_16x16x32_bf16 v[86:89], v[150:153], v[186:189], v[86:89]
	v_mfma_f32_16x16x32_bf16 v[82:85], v[162:165], v[186:189], v[82:85]
	v_mfma_f32_16x16x32_bf16 v[70:73], v[150:153], v[212:215], v[70:73]
	v_mfma_f32_16x16x32_bf16 v[66:69], v[162:165], v[212:215], v[66:69]
	v_mfma_f32_16x16x32_bf16 v[122:125], v[154:157], v[174:177], v[122:125]
	v_mfma_f32_16x16x32_bf16 v[116:119], v[166:169], v[174:177], v[116:119]
	v_mfma_f32_16x16x32_bf16 v[102:105], v[154:157], v[182:185], v[102:105]
	v_mfma_f32_16x16x32_bf16 v[98:101], v[166:169], v[182:185], v[98:101]
	v_mfma_f32_16x16x32_bf16 v[86:89], v[154:157], v[190:193], v[86:89]
	v_mfma_f32_16x16x32_bf16 v[82:85], v[166:169], v[190:193], v[82:85]
	s_setprio 2
	s_barrier
	v_mfma_f32_16x16x32_bf16 v[70:73], v[154:157], v[216:219], v[70:73]
	v_mfma_f32_16x16x32_bf16 v[66:69], v[166:169], v[216:219], v[66:69]
	s_setprio 0
	s_nop 0
	ds_read_b128 v[170:173], v203 offset:16384
	ds_read_b128 v[174:177], v203 offset:17408
	ds_read_b128 v[178:181], v203 offset:18432
	ds_read_b128 v[182:185], v203 offset:19456
	ds_read_b128 v[186:189], v203 offset:20480
	ds_read_b128 v[190:193], v203 offset:21504
	ds_read_b128 v[212:215], v203 offset:22528
	ds_read_b128 v[216:219], v203 offset:23552
	s_mov_b32 m0, s13
	s_nop 0
	global_load_lds_dwordx4 v195, s[10:11]
	s_add_u32 m0, s13, 0x2000
	s_nop 0
	global_load_lds_dwordx4 v197, s[10:11]
	s_add_u32 s50, s10, 0x4000
	s_addc_u32 s51, s11, 0
	s_mov_b32 m0, s57
	s_nop 0
	global_load_lds_dwordx4 v195, s[50:51]
	s_add_u32 m0, s57, 0x2000
	s_nop 0
	global_load_lds_dwordx4 v197, s[50:51]
	s_nop 0
	s_mov_b32 m0, s56
	s_nop 0
	global_load_lds_dwordx4 v195, s[46:47]
	s_add_u32 m0, s56, 0x2000
	s_nop 0
	global_load_lds_dwordx4 v197, s[46:47]
	s_waitcnt vmcnt(8)
	s_waitcnt lgkmcnt(0)
	s_setprio 1
	s_barrier
	v_mfma_f32_16x16x32_bf16 v[62:65], v[134:137], v[170:173], v[62:65]
	v_mfma_f32_16x16x32_bf16 v[62:65], v[138:141], v[174:177], v[62:65]
	s_waitcnt lgkmcnt(5)
	v_mfma_f32_16x16x32_bf16 v[58:61], v[142:145], v[170:173], v[58:61]
	v_mfma_f32_16x16x32_bf16 v[58:61], v[146:149], v[174:177], v[58:61]
	s_waitcnt lgkmcnt(3)
	v_mfma_f32_16x16x32_bf16 v[46:49], v[134:137], v[178:181], v[46:49]
	v_mfma_f32_16x16x32_bf16 v[46:49], v[138:141], v[182:185], v[46:49]
	s_waitcnt lgkmcnt(1)
	v_mfma_f32_16x16x32_bf16 v[42:45], v[142:145], v[178:181], v[42:45]
	v_mfma_f32_16x16x32_bf16 v[42:45], v[146:149], v[182:185], v[42:45]
	v_mfma_f32_16x16x32_bf16 v[30:33], v[134:137], v[186:189], v[30:33]
	v_mfma_f32_16x16x32_bf16 v[30:33], v[138:141], v[190:193], v[30:33]
	v_mfma_f32_16x16x32_bf16 v[26:29], v[142:145], v[186:189], v[26:29]
	v_mfma_f32_16x16x32_bf16 v[26:29], v[146:149], v[190:193], v[26:29]
	v_mfma_f32_16x16x32_bf16 v[14:17], v[134:137], v[212:215], v[14:17]
	v_mfma_f32_16x16x32_bf16 v[14:17], v[138:141], v[216:219], v[14:17]
	s_waitcnt lgkmcnt(0)
	v_mfma_f32_16x16x32_bf16 v[10:13], v[142:145], v[212:215], v[10:13]
	v_mfma_f32_16x16x32_bf16 v[10:13], v[146:149], v[216:219], v[10:13]
	s_setprio 0
	s_setprio 1
	v_mfma_f32_16x16x32_bf16 v[54:57], v[150:153], v[170:173], v[54:57]
	v_mfma_f32_16x16x32_bf16 v[54:57], v[154:157], v[174:177], v[54:57]
	v_mfma_f32_16x16x32_bf16 v[50:53], v[162:165], v[170:173], v[50:53]
	v_mfma_f32_16x16x32_bf16 v[50:53], v[166:169], v[174:177], v[50:53]
	v_mfma_f32_16x16x32_bf16 v[38:41], v[150:153], v[178:181], v[38:41]
	v_mfma_f32_16x16x32_bf16 v[38:41], v[154:157], v[182:185], v[38:41]
	v_mfma_f32_16x16x32_bf16 v[34:37], v[162:165], v[178:181], v[34:37]
	v_mfma_f32_16x16x32_bf16 v[34:37], v[166:169], v[182:185], v[34:37]
	v_mfma_f32_16x16x32_bf16 v[22:25], v[150:153], v[186:189], v[22:25]
	v_mfma_f32_16x16x32_bf16 v[22:25], v[154:157], v[190:193], v[22:25]
	v_mfma_f32_16x16x32_bf16 v[18:21], v[162:165], v[186:189], v[18:21]
	v_mfma_f32_16x16x32_bf16 v[18:21], v[166:169], v[190:193], v[18:21]
	s_setprio 2
	s_barrier
	v_mfma_f32_16x16x32_bf16 v[6:9], v[150:153], v[212:215], v[6:9]
	v_mfma_f32_16x16x32_bf16 v[6:9], v[154:157], v[216:219], v[6:9]
	v_mfma_f32_16x16x32_bf16 v[2:5], v[162:165], v[212:215], v[2:5]
	v_mfma_f32_16x16x32_bf16 v[2:5], v[166:169], v[216:219], v[2:5]
	s_setprio 0
	s_nop 0
	ds_read_b128 v[134:137], v204
	ds_read_b128 v[138:141], v204 offset:1024
	ds_read_b128 v[142:145], v204 offset:2048
	ds_read_b128 v[146:149], v204 offset:3072
	ds_read_b128 v[150:153], v205
	ds_read_b128 v[154:157], v205 offset:1024
	ds_read_b128 v[162:165], v205 offset:2048
	ds_read_b128 v[166:169], v205 offset:3072
	ds_read_b128 v[170:173], v203 offset:32768
	ds_read_b128 v[174:177], v203 offset:33792
	ds_read_b128 v[178:181], v203 offset:34816
	ds_read_b128 v[182:185], v203 offset:35840
	ds_read_b128 v[186:189], v203 offset:36864
	ds_read_b128 v[190:193], v203 offset:37888
	ds_read_b128 v[212:215], v203 offset:38912
	ds_read_b128 v[216:219], v203 offset:39936
	s_add_u32 s46, s46, 0x4000
	s_addc_u32 s47, s47, 0
	s_mov_b32 m0, s58
	s_nop 0
	global_load_lds_dwordx4 v195, s[46:47]
	s_add_u32 m0, s58, 0x2000
	s_nop 0
	global_load_lds_dwordx4 v197, s[46:47]
	s_waitcnt vmcnt(8)
	s_waitcnt lgkmcnt(0)
	s_setprio 1
	s_barrier
	v_mfma_f32_16x16x32_bf16 v[130:133], v[134:137], v[170:173], v[130:133]
	v_mfma_f32_16x16x32_bf16 v[126:129], v[142:145], v[170:173], v[126:129]
	s_waitcnt lgkmcnt(5)
	v_mfma_f32_16x16x32_bf16 v[110:113], v[134:137], v[178:181], v[110:113]
	v_mfma_f32_16x16x32_bf16 v[106:109], v[142:145], v[178:181], v[106:109]
	s_waitcnt lgkmcnt(3)
	v_mfma_f32_16x16x32_bf16 v[94:97], v[134:137], v[186:189], v[94:97]
	v_mfma_f32_16x16x32_bf16 v[90:93], v[142:145], v[186:189], v[90:93]
	s_waitcnt lgkmcnt(1)
	v_mfma_f32_16x16x32_bf16 v[78:81], v[134:137], v[212:215], v[78:81]
	v_mfma_f32_16x16x32_bf16 v[74:77], v[142:145], v[212:215], v[74:77]
	v_mfma_f32_16x16x32_bf16 v[130:133], v[138:141], v[174:177], v[130:133]
	v_mfma_f32_16x16x32_bf16 v[126:129], v[146:149], v[174:177], v[126:129]
	v_mfma_f32_16x16x32_bf16 v[110:113], v[138:141], v[182:185], v[110:113]
	v_mfma_f32_16x16x32_bf16 v[106:109], v[146:149], v[182:185], v[106:109]
	v_mfma_f32_16x16x32_bf16 v[94:97], v[138:141], v[190:193], v[94:97]
	v_mfma_f32_16x16x32_bf16 v[90:93], v[146:149], v[190:193], v[90:93]
	s_waitcnt lgkmcnt(0)
	v_mfma_f32_16x16x32_bf16 v[78:81], v[138:141], v[216:219], v[78:81]
	v_mfma_f32_16x16x32_bf16 v[74:77], v[146:149], v[216:219], v[74:77]
	s_setprio 0
	s_setprio 1
	v_mfma_f32_16x16x32_bf16 v[120:123], v[150:153], v[170:173], v[122:125]
	v_mfma_f32_16x16x32_bf16 v[116:119], v[162:165], v[170:173], v[116:119]
	v_mfma_f32_16x16x32_bf16 v[102:105], v[150:153], v[178:181], v[102:105]
	v_mfma_f32_16x16x32_bf16 v[98:101], v[162:165], v[178:181], v[98:101]
	v_mfma_f32_16x16x32_bf16 v[86:89], v[150:153], v[186:189], v[86:89]
	v_mfma_f32_16x16x32_bf16 v[82:85], v[162:165], v[186:189], v[82:85]
	v_mfma_f32_16x16x32_bf16 v[70:73], v[150:153], v[212:215], v[70:73]
	v_mfma_f32_16x16x32_bf16 v[66:69], v[162:165], v[212:215], v[66:69]
	v_mfma_f32_16x16x32_bf16 v[122:125], v[154:157], v[174:177], v[120:123]
	v_mfma_f32_16x16x32_bf16 v[118:121], v[166:169], v[174:177], v[116:119]
	v_mfma_f32_16x16x32_bf16 v[102:105], v[154:157], v[182:185], v[102:105]
	v_mfma_f32_16x16x32_bf16 v[98:101], v[166:169], v[182:185], v[98:101]
	v_mfma_f32_16x16x32_bf16 v[86:89], v[154:157], v[190:193], v[86:89]
	v_mfma_f32_16x16x32_bf16 v[82:85], v[166:169], v[190:193], v[82:85]
	s_setprio 2
	s_barrier
	v_mfma_f32_16x16x32_bf16 v[70:73], v[154:157], v[216:219], v[70:73]
	v_mfma_f32_16x16x32_bf16 v[66:69], v[166:169], v[216:219], v[66:69]
	s_setprio 0
	s_nop 0
	ds_read_b128 v[170:173], v203 offset:49152
	ds_read_b128 v[174:177], v203 offset:50176
	ds_read_b128 v[178:181], v203 offset:51200
	ds_read_b128 v[182:185], v203 offset:52224
	ds_read_b128 v[186:189], v203 offset:53248
	ds_read_b128 v[190:193], v203 offset:54272
	ds_read_b128 v[212:215], v203 offset:55296
	ds_read_b128 v[216:219], v203 offset:56320
	s_mov_b32 m0, s62
	s_nop 0
	global_load_lds_dwordx4 v195, s[44:45]
	s_add_u32 m0, s62, 0x2000
	s_nop 0
	global_load_lds_dwordx4 v197, s[44:45]
	s_add_u32 s10, s10, 0xc000
	s_addc_u32 s11, s11, 0
	s_mov_b32 m0, s64
	s_nop 0
	global_load_lds_dwordx4 v195, s[10:11]
	s_add_u32 m0, s64, 0x2000
	s_nop 0
	global_load_lds_dwordx4 v197, s[10:11]
	s_nop 0
	s_mov_b32 m0, s63
	s_nop 0
	global_load_lds_dwordx4 v195, s[42:43]
	s_add_u32 m0, s63, 0x2000
	s_nop 0
	global_load_lds_dwordx4 v197, s[42:43]
	s_waitcnt vmcnt(8)
	s_waitcnt lgkmcnt(0)
	s_setprio 1
	s_barrier
	v_mfma_f32_16x16x32_bf16 v[62:65], v[134:137], v[170:173], v[62:65]
	v_mfma_f32_16x16x32_bf16 v[62:65], v[138:141], v[174:177], v[62:65]
	s_waitcnt lgkmcnt(5)
	v_mfma_f32_16x16x32_bf16 v[58:61], v[142:145], v[170:173], v[58:61]
	v_mfma_f32_16x16x32_bf16 v[58:61], v[146:149], v[174:177], v[58:61]
	s_waitcnt lgkmcnt(3)
	v_mfma_f32_16x16x32_bf16 v[46:49], v[134:137], v[178:181], v[46:49]
	v_mfma_f32_16x16x32_bf16 v[46:49], v[138:141], v[182:185], v[46:49]
	s_waitcnt lgkmcnt(1)
	v_mfma_f32_16x16x32_bf16 v[42:45], v[142:145], v[178:181], v[42:45]
	v_mfma_f32_16x16x32_bf16 v[42:45], v[146:149], v[182:185], v[42:45]
	v_mfma_f32_16x16x32_bf16 v[30:33], v[134:137], v[186:189], v[30:33]
	v_mfma_f32_16x16x32_bf16 v[30:33], v[138:141], v[190:193], v[30:33]
	v_mfma_f32_16x16x32_bf16 v[26:29], v[142:145], v[186:189], v[26:29]
	v_mfma_f32_16x16x32_bf16 v[26:29], v[146:149], v[190:193], v[26:29]
	v_mfma_f32_16x16x32_bf16 v[14:17], v[134:137], v[212:215], v[14:17]
	v_mfma_f32_16x16x32_bf16 v[14:17], v[138:141], v[216:219], v[14:17]
	s_waitcnt lgkmcnt(0)
	v_mfma_f32_16x16x32_bf16 v[10:13], v[142:145], v[212:215], v[10:13]
	v_mfma_f32_16x16x32_bf16 v[10:13], v[146:149], v[216:219], v[10:13]
	s_setprio 0
	s_setprio 1
	v_mfma_f32_16x16x32_bf16 v[54:57], v[150:153], v[170:173], v[54:57]
	v_mfma_f32_16x16x32_bf16 v[54:57], v[154:157], v[174:177], v[54:57]
	v_mfma_f32_16x16x32_bf16 v[50:53], v[162:165], v[170:173], v[50:53]
	v_mfma_f32_16x16x32_bf16 v[50:53], v[166:169], v[174:177], v[50:53]
	v_mfma_f32_16x16x32_bf16 v[38:41], v[150:153], v[178:181], v[38:41]
	v_mfma_f32_16x16x32_bf16 v[38:41], v[154:157], v[182:185], v[38:41]
	v_mfma_f32_16x16x32_bf16 v[34:37], v[162:165], v[178:181], v[34:37]
	v_mfma_f32_16x16x32_bf16 v[34:37], v[166:169], v[182:185], v[34:37]
	v_mfma_f32_16x16x32_bf16 v[22:25], v[150:153], v[186:189], v[22:25]
	v_mfma_f32_16x16x32_bf16 v[22:25], v[154:157], v[190:193], v[22:25]
	v_mfma_f32_16x16x32_bf16 v[18:21], v[162:165], v[186:189], v[18:21]
	v_mfma_f32_16x16x32_bf16 v[18:21], v[166:169], v[190:193], v[18:21]
	s_setprio 2
	s_barrier
	v_mfma_f32_16x16x32_bf16 v[6:9], v[150:153], v[212:215], v[6:9]
	v_mfma_f32_16x16x32_bf16 v[6:9], v[154:157], v[216:219], v[6:9]
	v_mfma_f32_16x16x32_bf16 v[2:5], v[162:165], v[212:215], v[2:5]
	v_mfma_f32_16x16x32_bf16 v[2:5], v[166:169], v[216:219], v[2:5]
	s_setprio 0
	s_nop 0
	s_add_i32 s49, s49, 2
	s_add_u32 s6, s6, 0x10000
	s_addc_u32 s7, s7, 0
	s_cmp_gt_u32 s49, 13
	v_mov_b32_e32 v115, v114
	s_cbranch_scc1 .LBB0_1922

.LBB0_2120:
	s_add_u32 s56, s52, 0x10000
	s_addc_u32 s57, s53, 0
	s_and_b64 s[52:53], s[50:51], exec
	s_cselect_b32 s53, s57, s43
	s_cselect_b32 s52, s56, s88
	s_add_u32 s15, s18, s15
	s_addc_u32 s56, s19, 0
	s_add_u32 s15, s15, 0x10000
	s_waitcnt vmcnt(8)
	s_addc_u32 s56, s56, 0
	s_waitcnt lgkmcnt(0)
	s_and_b64 s[50:51], s[50:51], exec
	s_cselect_b32 s51, s56, s41
	s_cselect_b32 s50, s15, s89
	s_setprio 1
	s_barrier
	v_mfma_f32_16x16x32_bf16 v[126:129], v[146:149], v[186:189], v[126:129]
	v_mfma_f32_16x16x32_bf16 v[126:129], v[150:153], v[190:193], v[126:129]
	s_waitcnt lgkmcnt(5)
	v_mfma_f32_16x16x32_bf16 v[122:125], v[154:157], v[186:189], v[122:125]
	v_mfma_f32_16x16x32_bf16 v[122:125], v[158:161], v[190:193], v[122:125]
	s_waitcnt lgkmcnt(3)
	v_mfma_f32_16x16x32_bf16 v[118:121], v[146:149], v[178:181], v[118:121]
	v_mfma_f32_16x16x32_bf16 v[118:121], v[150:153], v[182:185], v[118:121]
	s_waitcnt lgkmcnt(1)
	v_mfma_f32_16x16x32_bf16 v[114:117], v[154:157], v[178:181], v[114:117]
	v_mfma_f32_16x16x32_bf16 v[114:117], v[158:161], v[182:185], v[114:117]
	v_mfma_f32_16x16x32_bf16 v[110:113], v[146:149], v[170:173], v[110:113]
	v_mfma_f32_16x16x32_bf16 v[110:113], v[150:153], v[174:177], v[110:113]
	v_mfma_f32_16x16x32_bf16 v[106:109], v[154:157], v[170:173], v[106:109]
	v_mfma_f32_16x16x32_bf16 v[106:109], v[158:161], v[174:177], v[106:109]
	v_mfma_f32_16x16x32_bf16 v[102:105], v[146:149], v[162:165], v[102:105]
	v_mfma_f32_16x16x32_bf16 v[102:105], v[150:153], v[166:169], v[102:105]
	s_waitcnt lgkmcnt(0)
	v_mfma_f32_16x16x32_bf16 v[98:101], v[154:157], v[162:165], v[98:101]
	v_mfma_f32_16x16x32_bf16 v[98:101], v[158:161], v[166:169], v[98:101]
	s_setprio 0
	s_setprio 1
	v_mfma_f32_16x16x32_bf16 v[94:97], v[130:133], v[186:189], v[94:97]
	v_mfma_f32_16x16x32_bf16 v[94:97], v[134:137], v[190:193], v[94:97]
	v_mfma_f32_16x16x32_bf16 v[90:93], v[138:141], v[186:189], v[90:93]
	v_mfma_f32_16x16x32_bf16 v[90:93], v[142:145], v[190:193], v[90:93]
	v_mfma_f32_16x16x32_bf16 v[86:89], v[130:133], v[178:181], v[86:89]
	v_mfma_f32_16x16x32_bf16 v[86:89], v[134:137], v[182:185], v[86:89]
	v_mfma_f32_16x16x32_bf16 v[82:85], v[138:141], v[178:181], v[82:85]
	v_mfma_f32_16x16x32_bf16 v[82:85], v[142:145], v[182:185], v[82:85]
	v_mfma_f32_16x16x32_bf16 v[78:81], v[130:133], v[170:173], v[78:81]
	v_mfma_f32_16x16x32_bf16 v[78:81], v[134:137], v[174:177], v[78:81]
	v_mfma_f32_16x16x32_bf16 v[74:77], v[138:141], v[170:173], v[74:77]
	v_mfma_f32_16x16x32_bf16 v[74:77], v[142:145], v[174:177], v[74:77]
	s_setprio 2
	s_barrier
	v_mfma_f32_16x16x32_bf16 v[70:73], v[130:133], v[162:165], v[70:73]
	v_mfma_f32_16x16x32_bf16 v[70:73], v[134:137], v[166:169], v[70:73]
	v_mfma_f32_16x16x32_bf16 v[66:69], v[138:141], v[162:165], v[66:69]
	v_mfma_f32_16x16x32_bf16 v[66:69], v[142:145], v[166:169], v[66:69]
	s_setprio 0
	s_nop 0
	ds_read_b128 v[186:189], v207 offset:16384
	ds_read_b128 v[190:193], v207 offset:17408
	ds_read_b128 v[178:181], v207 offset:18432
	ds_read_b128 v[182:185], v207 offset:19456
	ds_read_b128 v[170:173], v207 offset:20480
	ds_read_b128 v[174:177], v207 offset:21504
	ds_read_b128 v[162:165], v207 offset:22528
	ds_read_b128 v[166:169], v207 offset:23552
	s_mov_b32 m0, s62
	s_nop 0
	global_load_lds_dwordx4 v195, s[50:51]
	s_add_u32 m0, s62, 0x2000
	s_nop 0
	global_load_lds_dwordx4 v197, s[50:51]
	s_add_u32 s56, s50, 0x4000
	s_addc_u32 s57, s51, 0
	s_mov_b32 m0, s63
	s_nop 0
	global_load_lds_dwordx4 v195, s[56:57]
	s_add_u32 m0, s63, 0x2000
	s_nop 0
	global_load_lds_dwordx4 v197, s[56:57]
	s_andn2_b64 vcc, exec, s[54:55]
	s_mov_b32 m0, s61
	s_nop 0
	global_load_lds_dwordx4 v195, s[52:53]
	s_add_u32 m0, s61, 0x2000
	s_nop 0
	global_load_lds_dwordx4 v197, s[52:53]
	s_cbranch_vccnz .LBB0_2122
	v_mov_b32_e32 v2, 0
	v_mov_b32_e32 v3, v2
	v_mov_b32_e32 v4, v2
	v_mov_b32_e32 v5, v2
	v_mov_b32_e32 v6, v2
	v_mov_b32_e32 v7, v2
	v_mov_b32_e32 v8, v2
	v_mov_b32_e32 v9, v2
	v_mov_b32_e32 v10, v2
	v_mov_b32_e32 v11, v2
	v_mov_b32_e32 v12, v2
	v_mov_b32_e32 v13, v2
	v_mov_b32_e32 v14, v2
	v_mov_b32_e32 v15, v2
	v_mov_b32_e32 v16, v2
	v_mov_b32_e32 v17, v2
	v_mov_b32_e32 v18, v2
	v_mov_b32_e32 v19, v2
	v_mov_b32_e32 v20, v2
	v_mov_b32_e32 v21, v2
	v_mov_b32_e32 v22, v2
	v_mov_b32_e32 v23, v2
	v_mov_b32_e32 v24, v2
	v_mov_b32_e32 v25, v2
	v_mov_b32_e32 v26, v2
	v_mov_b32_e32 v27, v2
	v_mov_b32_e32 v28, v2
	v_mov_b32_e32 v29, v2
	v_mov_b32_e32 v30, v2
	v_mov_b32_e32 v31, v2
	v_mov_b32_e32 v32, v2
	v_mov_b32_e32 v33, v2
	v_mov_b32_e32 v34, v2
	v_mov_b32_e32 v35, v2
	v_mov_b32_e32 v36, v2
	v_mov_b32_e32 v37, v2
	v_mov_b32_e32 v38, v2
	v_mov_b32_e32 v39, v2
	v_mov_b32_e32 v40, v2
	v_mov_b32_e32 v41, v2
	v_mov_b32_e32 v42, v2
	v_mov_b32_e32 v43, v2
	v_mov_b32_e32 v44, v2
	v_mov_b32_e32 v45, v2
	v_mov_b32_e32 v46, v2
	v_mov_b32_e32 v47, v2
	v_mov_b32_e32 v48, v2
	v_mov_b32_e32 v49, v2
	v_mov_b32_e32 v50, v2
	v_mov_b32_e32 v51, v2
	v_mov_b32_e32 v52, v2
	v_mov_b32_e32 v53, v2
	v_mov_b32_e32 v54, v2
	v_mov_b32_e32 v55, v2
	v_mov_b32_e32 v56, v2
	v_mov_b32_e32 v57, v2
	v_mov_b32_e32 v58, v2
	v_mov_b32_e32 v59, v2
	v_mov_b32_e32 v60, v2
	v_mov_b32_e32 v61, v2
	v_mov_b32_e32 v62, v2
	v_mov_b32_e32 v63, v2
	v_mov_b32_e32 v64, v2
	v_mov_b32_e32 v65, v2
.LBB0_2122:
	s_waitcnt vmcnt(8)
	s_add_u32 s54, s52, 0x8000
	s_waitcnt lgkmcnt(0)
	s_addc_u32 s55, s53, 0
	s_add_u32 s56, s50, 0x8000
	s_addc_u32 s57, s51, 0
	s_setprio 1
	s_barrier
	v_mfma_f32_16x16x32_bf16 v[62:65], v[146:149], v[186:189], v[62:65]
	v_mfma_f32_16x16x32_bf16 v[62:65], v[150:153], v[190:193], v[62:65]
	s_waitcnt lgkmcnt(5)
	v_mfma_f32_16x16x32_bf16 v[58:61], v[154:157], v[186:189], v[58:61]
	v_mfma_f32_16x16x32_bf16 v[58:61], v[158:161], v[190:193], v[58:61]
	s_waitcnt lgkmcnt(3)
	v_mfma_f32_16x16x32_bf16 v[54:57], v[146:149], v[178:181], v[54:57]
	v_mfma_f32_16x16x32_bf16 v[54:57], v[150:153], v[182:185], v[54:57]
	s_waitcnt lgkmcnt(1)
	v_mfma_f32_16x16x32_bf16 v[50:53], v[154:157], v[178:181], v[50:53]
	v_mfma_f32_16x16x32_bf16 v[50:53], v[158:161], v[182:185], v[50:53]
	v_mfma_f32_16x16x32_bf16 v[46:49], v[146:149], v[170:173], v[46:49]
	v_mfma_f32_16x16x32_bf16 v[46:49], v[150:153], v[174:177], v[46:49]
	v_mfma_f32_16x16x32_bf16 v[42:45], v[154:157], v[170:173], v[42:45]
	v_mfma_f32_16x16x32_bf16 v[42:45], v[158:161], v[174:177], v[42:45]
	v_mfma_f32_16x16x32_bf16 v[38:41], v[146:149], v[162:165], v[38:41]
	v_mfma_f32_16x16x32_bf16 v[38:41], v[150:153], v[166:169], v[38:41]
	s_waitcnt lgkmcnt(0)
	v_mfma_f32_16x16x32_bf16 v[34:37], v[154:157], v[162:165], v[34:37]
	v_mfma_f32_16x16x32_bf16 v[34:37], v[158:161], v[166:169], v[34:37]
	s_setprio 0
	s_setprio 1
	v_mfma_f32_16x16x32_bf16 v[30:33], v[130:133], v[186:189], v[30:33]
	v_mfma_f32_16x16x32_bf16 v[30:33], v[134:137], v[190:193], v[30:33]
	v_mfma_f32_16x16x32_bf16 v[26:29], v[138:141], v[186:189], v[26:29]
	v_mfma_f32_16x16x32_bf16 v[26:29], v[142:145], v[190:193], v[26:29]
	v_mfma_f32_16x16x32_bf16 v[22:25], v[130:133], v[178:181], v[22:25]
	v_mfma_f32_16x16x32_bf16 v[22:25], v[134:137], v[182:185], v[22:25]
	v_mfma_f32_16x16x32_bf16 v[18:21], v[138:141], v[178:181], v[18:21]
	v_mfma_f32_16x16x32_bf16 v[18:21], v[142:145], v[182:185], v[18:21]
	v_mfma_f32_16x16x32_bf16 v[14:17], v[130:133], v[170:173], v[14:17]
	v_mfma_f32_16x16x32_bf16 v[14:17], v[134:137], v[174:177], v[14:17]
	v_mfma_f32_16x16x32_bf16 v[10:13], v[138:141], v[170:173], v[10:13]
	v_mfma_f32_16x16x32_bf16 v[10:13], v[142:145], v[174:177], v[10:13]
	s_setprio 2
	s_barrier
	v_mfma_f32_16x16x32_bf16 v[6:9], v[130:133], v[162:165], v[6:9]
	v_mfma_f32_16x16x32_bf16 v[6:9], v[134:137], v[166:169], v[6:9]
	v_mfma_f32_16x16x32_bf16 v[2:5], v[138:141], v[162:165], v[2:5]
	v_mfma_f32_16x16x32_bf16 v[2:5], v[142:145], v[166:169], v[2:5]
	s_setprio 0
	s_nop 0
	v_add_u32_e32 v142, 0x18000, v206
	v_add_u32_e32 v158, 0x1c000, v206
	ds_read_b128 v[130:133], v142
	ds_read_b128 v[134:137], v142 offset:1024
	ds_read_b128 v[138:141], v142 offset:2048
	ds_read_b128 v[142:145], v142 offset:3072
	ds_read_b128 v[146:149], v158
	ds_read_b128 v[150:153], v158 offset:1024
	ds_read_b128 v[154:157], v158 offset:2048
	ds_read_b128 v[158:161], v158 offset:3072
	ds_read_b128 v[162:165], v207 offset:32768
	ds_read_b128 v[166:169], v207 offset:33792
	ds_read_b128 v[170:173], v207 offset:34816
	ds_read_b128 v[174:177], v207 offset:35840
	ds_read_b128 v[178:181], v207 offset:36864
	ds_read_b128 v[182:185], v207 offset:37888
	ds_read_b128 v[186:189], v207 offset:38912
	ds_read_b128 v[190:193], v207 offset:39936
	s_add_u32 s52, s52, 0x4000
	s_addc_u32 s53, s53, 0
	s_mov_b32 m0, s64
	s_nop 0
	global_load_lds_dwordx4 v195, s[52:53]
	s_add_u32 m0, s64, 0x2000
	s_nop 0
	global_load_lds_dwordx4 v197, s[52:53]
	s_waitcnt vmcnt(8)
	s_waitcnt lgkmcnt(0)
	s_setprio 1
	s_barrier
	v_mfma_f32_16x16x32_bf16 v[126:129], v[130:133], v[162:165], v[126:129]
	v_mfma_f32_16x16x32_bf16 v[126:129], v[134:137], v[166:169], v[126:129]
	s_waitcnt lgkmcnt(5)
	v_mfma_f32_16x16x32_bf16 v[122:125], v[138:141], v[162:165], v[122:125]
	v_mfma_f32_16x16x32_bf16 v[122:125], v[142:145], v[166:169], v[122:125]
	s_waitcnt lgkmcnt(3)
	v_mfma_f32_16x16x32_bf16 v[118:121], v[130:133], v[170:173], v[118:121]
	v_mfma_f32_16x16x32_bf16 v[118:121], v[134:137], v[174:177], v[118:121]
	s_waitcnt lgkmcnt(1)
	v_mfma_f32_16x16x32_bf16 v[114:117], v[138:141], v[170:173], v[114:117]
	v_mfma_f32_16x16x32_bf16 v[114:117], v[142:145], v[174:177], v[114:117]
	v_mfma_f32_16x16x32_bf16 v[110:113], v[130:133], v[178:181], v[110:113]
	v_mfma_f32_16x16x32_bf16 v[110:113], v[134:137], v[182:185], v[110:113]
	v_mfma_f32_16x16x32_bf16 v[106:109], v[138:141], v[178:181], v[106:109]
	v_mfma_f32_16x16x32_bf16 v[106:109], v[142:145], v[182:185], v[106:109]
	v_mfma_f32_16x16x32_bf16 v[102:105], v[130:133], v[186:189], v[102:105]
	v_mfma_f32_16x16x32_bf16 v[102:105], v[134:137], v[190:193], v[102:105]
	s_waitcnt lgkmcnt(0)
	v_mfma_f32_16x16x32_bf16 v[98:101], v[138:141], v[186:189], v[98:101]
	v_mfma_f32_16x16x32_bf16 v[98:101], v[142:145], v[190:193], v[98:101]
	s_setprio 0
	s_setprio 1
	v_mfma_f32_16x16x32_bf16 v[94:97], v[146:149], v[162:165], v[94:97]
	v_mfma_f32_16x16x32_bf16 v[94:97], v[150:153], v[166:169], v[94:97]
	v_mfma_f32_16x16x32_bf16 v[90:93], v[154:157], v[162:165], v[90:93]
	v_mfma_f32_16x16x32_bf16 v[90:93], v[158:161], v[166:169], v[90:93]
	v_mfma_f32_16x16x32_bf16 v[86:89], v[146:149], v[170:173], v[86:89]
	v_mfma_f32_16x16x32_bf16 v[86:89], v[150:153], v[174:177], v[86:89]
	v_mfma_f32_16x16x32_bf16 v[82:85], v[154:157], v[170:173], v[82:85]
	v_mfma_f32_16x16x32_bf16 v[82:85], v[158:161], v[174:177], v[82:85]
	v_mfma_f32_16x16x32_bf16 v[78:81], v[146:149], v[178:181], v[78:81]
	v_mfma_f32_16x16x32_bf16 v[78:81], v[150:153], v[182:185], v[78:81]
	v_mfma_f32_16x16x32_bf16 v[74:77], v[154:157], v[178:181], v[74:77]
	v_mfma_f32_16x16x32_bf16 v[74:77], v[158:161], v[182:185], v[74:77]
	s_setprio 2
	s_barrier
	v_mfma_f32_16x16x32_bf16 v[70:73], v[146:149], v[186:189], v[70:73]
	v_mfma_f32_16x16x32_bf16 v[70:73], v[150:153], v[190:193], v[70:73]
	v_mfma_f32_16x16x32_bf16 v[66:69], v[154:157], v[186:189], v[66:69]
	v_mfma_f32_16x16x32_bf16 v[66:69], v[158:161], v[190:193], v[66:69]
	s_setprio 0
	s_nop 0
	ds_read_b128 v[162:165], v207 offset:49152
	ds_read_b128 v[166:169], v207 offset:50176
	ds_read_b128 v[170:173], v207 offset:51200
	ds_read_b128 v[174:177], v207 offset:52224
	ds_read_b128 v[178:181], v207 offset:53248
	ds_read_b128 v[182:185], v207 offset:54272
	ds_read_b128 v[186:189], v207 offset:55296
	ds_read_b128 v[190:193], v207 offset:56320
	s_mov_b32 m0, s70
	s_nop 0
	global_load_lds_dwordx4 v195, s[56:57]
	s_add_u32 m0, s70, 0x2000
	s_nop 0
	global_load_lds_dwordx4 v197, s[56:57]
	s_add_u32 s50, s50, 0xc000
	s_addc_u32 s51, s51, 0
	s_mov_b32 m0, s72
	s_nop 0
	global_load_lds_dwordx4 v195, s[50:51]
	s_add_u32 m0, s72, 0x2000
	s_nop 0
	global_load_lds_dwordx4 v197, s[50:51]
	s_nop 0
	s_mov_b32 m0, s71
	s_nop 0
	global_load_lds_dwordx4 v195, s[54:55]
	s_add_u32 m0, s71, 0x2000
	s_nop 0
	global_load_lds_dwordx4 v197, s[54:55]
	s_waitcnt vmcnt(8)
	s_waitcnt lgkmcnt(0)
	s_setprio 1
	s_barrier
	v_mfma_f32_16x16x32_bf16 v[62:65], v[130:133], v[162:165], v[62:65]
	v_mfma_f32_16x16x32_bf16 v[62:65], v[134:137], v[166:169], v[62:65]
	s_waitcnt lgkmcnt(5)
	v_mfma_f32_16x16x32_bf16 v[58:61], v[138:141], v[162:165], v[58:61]
	v_mfma_f32_16x16x32_bf16 v[58:61], v[142:145], v[166:169], v[58:61]
	s_waitcnt lgkmcnt(3)
	v_mfma_f32_16x16x32_bf16 v[54:57], v[130:133], v[170:173], v[54:57]
	v_mfma_f32_16x16x32_bf16 v[54:57], v[134:137], v[174:177], v[54:57]
	s_waitcnt lgkmcnt(1)
	v_mfma_f32_16x16x32_bf16 v[50:53], v[138:141], v[170:173], v[50:53]
	v_mfma_f32_16x16x32_bf16 v[50:53], v[142:145], v[174:177], v[50:53]
	v_mfma_f32_16x16x32_bf16 v[46:49], v[130:133], v[178:181], v[46:49]
	v_mfma_f32_16x16x32_bf16 v[46:49], v[134:137], v[182:185], v[46:49]
	v_mfma_f32_16x16x32_bf16 v[42:45], v[138:141], v[178:181], v[42:45]
	v_mfma_f32_16x16x32_bf16 v[42:45], v[142:145], v[182:185], v[42:45]
	v_mfma_f32_16x16x32_bf16 v[38:41], v[130:133], v[186:189], v[38:41]
	v_mfma_f32_16x16x32_bf16 v[38:41], v[134:137], v[190:193], v[38:41]
	s_waitcnt lgkmcnt(0)
	v_mfma_f32_16x16x32_bf16 v[34:37], v[138:141], v[186:189], v[34:37]
	v_mfma_f32_16x16x32_bf16 v[34:37], v[142:145], v[190:193], v[34:37]
	s_setprio 0
	s_setprio 1
	v_mfma_f32_16x16x32_bf16 v[30:33], v[146:149], v[162:165], v[30:33]
	v_mfma_f32_16x16x32_bf16 v[30:33], v[150:153], v[166:169], v[30:33]
	v_mfma_f32_16x16x32_bf16 v[26:29], v[154:157], v[162:165], v[26:29]
	v_mfma_f32_16x16x32_bf16 v[26:29], v[158:161], v[166:169], v[26:29]
	v_mfma_f32_16x16x32_bf16 v[22:25], v[146:149], v[170:173], v[22:25]
	v_mfma_f32_16x16x32_bf16 v[22:25], v[150:153], v[174:177], v[22:25]
	v_mfma_f32_16x16x32_bf16 v[18:21], v[154:157], v[170:173], v[18:21]
	v_mfma_f32_16x16x32_bf16 v[18:21], v[158:161], v[174:177], v[18:21]
	v_mfma_f32_16x16x32_bf16 v[14:17], v[146:149], v[178:181], v[14:17]
	v_mfma_f32_16x16x32_bf16 v[14:17], v[150:153], v[182:185], v[14:17]
	v_mfma_f32_16x16x32_bf16 v[10:13], v[154:157], v[178:181], v[10:13]
	v_mfma_f32_16x16x32_bf16 v[10:13], v[158:161], v[182:185], v[10:13]
	s_setprio 2
	s_barrier
	v_mfma_f32_16x16x32_bf16 v[6:9], v[146:149], v[186:189], v[6:9]
	v_mfma_f32_16x16x32_bf16 v[6:9], v[150:153], v[190:193], v[6:9]
	v_mfma_f32_16x16x32_bf16 v[2:5], v[154:157], v[186:189], v[2:5]
	v_mfma_f32_16x16x32_bf16 v[2:5], v[158:161], v[190:193], v[2:5]
	s_setprio 0
	s_nop 0
	s_add_i32 s15, s90, 2
	s_cmp_gt_u32 s90, 13
	s_cbranch_scc1 .LBB0_2124
	v_mov_b32_e32 v130, v198
	s_mov_b32 s90, s15
	s_branch .LBB0_2099

.LBB0_2229:
	s_add_i32 s22, s46, 2
	s_lshl_b64 s[42:43], s[22:23], 15
	s_add_u32 s44, s2, s42
	s_addc_u32 s45, s3, s43
	s_and_b64 s[38:39], s[14:15], exec
	s_cselect_b32 s39, s45, s29
	s_cselect_b32 s38, s44, s28
	s_add_u32 s42, s16, s42
	s_waitcnt vmcnt(8)
	s_addc_u32 s43, s17, s43
	s_waitcnt lgkmcnt(0)
	s_and_b64 s[14:15], s[14:15], exec
	s_cselect_b32 s15, s43, s31
	s_cselect_b32 s14, s42, s30
	s_setprio 1
	s_barrier
	v_mfma_f32_16x16x32_bf16 v[126:129], v[146:149], v[186:189], v[126:129]
	v_mfma_f32_16x16x32_bf16 v[126:129], v[150:153], v[190:193], v[126:129]
	s_waitcnt lgkmcnt(5)
	v_mfma_f32_16x16x32_bf16 v[122:125], v[154:157], v[186:189], v[122:125]
	v_mfma_f32_16x16x32_bf16 v[122:125], v[158:161], v[190:193], v[122:125]
	s_waitcnt lgkmcnt(3)
	v_mfma_f32_16x16x32_bf16 v[118:121], v[146:149], v[178:181], v[118:121]
	v_mfma_f32_16x16x32_bf16 v[118:121], v[150:153], v[182:185], v[118:121]
	s_waitcnt lgkmcnt(1)
	v_mfma_f32_16x16x32_bf16 v[114:117], v[154:157], v[178:181], v[114:117]
	v_mfma_f32_16x16x32_bf16 v[114:117], v[158:161], v[182:185], v[114:117]
	v_mfma_f32_16x16x32_bf16 v[110:113], v[146:149], v[170:173], v[110:113]
	v_mfma_f32_16x16x32_bf16 v[110:113], v[150:153], v[174:177], v[110:113]
	v_mfma_f32_16x16x32_bf16 v[106:109], v[154:157], v[170:173], v[106:109]
	v_mfma_f32_16x16x32_bf16 v[106:109], v[158:161], v[174:177], v[106:109]
	v_mfma_f32_16x16x32_bf16 v[102:105], v[146:149], v[162:165], v[102:105]
	v_mfma_f32_16x16x32_bf16 v[102:105], v[150:153], v[166:169], v[102:105]
	s_waitcnt lgkmcnt(0)
	v_mfma_f32_16x16x32_bf16 v[98:101], v[154:157], v[162:165], v[98:101]
	v_mfma_f32_16x16x32_bf16 v[98:101], v[158:161], v[166:169], v[98:101]
	s_setprio 0
	s_setprio 1
	v_mfma_f32_16x16x32_bf16 v[94:97], v[130:133], v[186:189], v[94:97]
	v_mfma_f32_16x16x32_bf16 v[94:97], v[134:137], v[190:193], v[94:97]
	v_mfma_f32_16x16x32_bf16 v[90:93], v[138:141], v[186:189], v[90:93]
	v_mfma_f32_16x16x32_bf16 v[90:93], v[142:145], v[190:193], v[90:93]
	v_mfma_f32_16x16x32_bf16 v[86:89], v[130:133], v[178:181], v[86:89]
	v_mfma_f32_16x16x32_bf16 v[86:89], v[134:137], v[182:185], v[86:89]
	v_mfma_f32_16x16x32_bf16 v[82:85], v[138:141], v[178:181], v[82:85]
	v_mfma_f32_16x16x32_bf16 v[82:85], v[142:145], v[182:185], v[82:85]
	v_mfma_f32_16x16x32_bf16 v[78:81], v[130:133], v[170:173], v[78:81]
	v_mfma_f32_16x16x32_bf16 v[78:81], v[134:137], v[174:177], v[78:81]
	v_mfma_f32_16x16x32_bf16 v[74:77], v[138:141], v[170:173], v[74:77]
	v_mfma_f32_16x16x32_bf16 v[74:77], v[142:145], v[174:177], v[74:77]
	s_setprio 2
	s_barrier
	v_mfma_f32_16x16x32_bf16 v[70:73], v[130:133], v[162:165], v[70:73]
	v_mfma_f32_16x16x32_bf16 v[70:73], v[134:137], v[166:169], v[70:73]
	v_mfma_f32_16x16x32_bf16 v[66:69], v[138:141], v[162:165], v[66:69]
	v_mfma_f32_16x16x32_bf16 v[66:69], v[142:145], v[166:169], v[66:69]
	s_setprio 0
	s_nop 0
	ds_read_b128 v[186:189], v215 offset:16384
	ds_read_b128 v[190:193], v215 offset:17408
	ds_read_b128 v[178:181], v215 offset:18432
	ds_read_b128 v[182:185], v215 offset:19456
	ds_read_b128 v[170:173], v215 offset:20480
	ds_read_b128 v[174:177], v215 offset:21504
	ds_read_b128 v[162:165], v215 offset:22528
	ds_read_b128 v[166:169], v215 offset:23552
	s_mov_b32 m0, s57
	s_nop 0
	global_load_lds_dwordx4 v195, s[14:15]
	s_add_u32 m0, s57, 0x2000
	s_nop 0
	global_load_lds_dwordx4 v208, s[14:15]
	s_add_u32 s42, s14, 0x4000
	s_addc_u32 s43, s15, 0
	s_mov_b32 m0, s58
	s_nop 0
	global_load_lds_dwordx4 v195, s[42:43]
	s_add_u32 m0, s58, 0x2000
	s_nop 0
	global_load_lds_dwordx4 v208, s[42:43]
	s_andn2_b64 vcc, exec, s[40:41]
	s_mov_b32 m0, s56
	s_nop 0
	global_load_lds_dwordx4 v195, s[38:39]
	s_add_u32 m0, s56, 0x2000
	s_nop 0
	global_load_lds_dwordx4 v208, s[38:39]
	s_cbranch_vccnz .LBB0_2231
	v_mov_b32_e32 v2, 0
	v_mov_b32_e32 v3, v2
	v_mov_b32_e32 v4, v2
	v_mov_b32_e32 v5, v2
	v_mov_b32_e32 v6, v2
	v_mov_b32_e32 v7, v2
	v_mov_b32_e32 v8, v2
	v_mov_b32_e32 v9, v2
	v_mov_b32_e32 v10, v2
	v_mov_b32_e32 v11, v2
	v_mov_b32_e32 v12, v2
	v_mov_b32_e32 v13, v2
	v_mov_b32_e32 v14, v2
	v_mov_b32_e32 v15, v2
	v_mov_b32_e32 v16, v2
	v_mov_b32_e32 v17, v2
	v_mov_b32_e32 v18, v2
	v_mov_b32_e32 v19, v2
	v_mov_b32_e32 v20, v2
	v_mov_b32_e32 v21, v2
	v_mov_b32_e32 v22, v2
	v_mov_b32_e32 v23, v2
	v_mov_b32_e32 v24, v2
	v_mov_b32_e32 v25, v2
	v_mov_b32_e32 v26, v2
	v_mov_b32_e32 v27, v2
	v_mov_b32_e32 v28, v2
	v_mov_b32_e32 v29, v2
	v_mov_b32_e32 v30, v2
	v_mov_b32_e32 v31, v2
	v_mov_b32_e32 v32, v2
	v_mov_b32_e32 v33, v2
	v_mov_b32_e32 v34, v2
	v_mov_b32_e32 v35, v2
	v_mov_b32_e32 v36, v2
	v_mov_b32_e32 v37, v2
	v_mov_b32_e32 v38, v2
	v_mov_b32_e32 v39, v2
	v_mov_b32_e32 v40, v2
	v_mov_b32_e32 v41, v2
	v_mov_b32_e32 v42, v2
	v_mov_b32_e32 v43, v2
	v_mov_b32_e32 v44, v2
	v_mov_b32_e32 v45, v2
	v_mov_b32_e32 v46, v2
	v_mov_b32_e32 v47, v2
	v_mov_b32_e32 v48, v2
	v_mov_b32_e32 v49, v2
	v_mov_b32_e32 v50, v2
	v_mov_b32_e32 v51, v2
	v_mov_b32_e32 v52, v2
	v_mov_b32_e32 v53, v2
	v_mov_b32_e32 v54, v2
	v_mov_b32_e32 v55, v2
	v_mov_b32_e32 v56, v2
	v_mov_b32_e32 v57, v2
	v_mov_b32_e32 v58, v2
	v_mov_b32_e32 v59, v2
	v_mov_b32_e32 v60, v2
	v_mov_b32_e32 v61, v2
	v_mov_b32_e32 v62, v2
	v_mov_b32_e32 v63, v2
	v_mov_b32_e32 v64, v2
	v_mov_b32_e32 v65, v2
.LBB0_2231:
	s_waitcnt vmcnt(8)
	s_add_u32 s40, s38, 0x8000
	s_waitcnt lgkmcnt(0)
	s_addc_u32 s41, s39, 0
	s_add_u32 s42, s14, 0x8000
	s_addc_u32 s43, s15, 0
	s_setprio 1
	s_barrier
	v_mfma_f32_16x16x32_bf16 v[62:65], v[146:149], v[186:189], v[62:65]
	v_mfma_f32_16x16x32_bf16 v[62:65], v[150:153], v[190:193], v[62:65]
	s_waitcnt lgkmcnt(5)
	v_mfma_f32_16x16x32_bf16 v[58:61], v[154:157], v[186:189], v[58:61]
	v_mfma_f32_16x16x32_bf16 v[58:61], v[158:161], v[190:193], v[58:61]
	s_waitcnt lgkmcnt(3)
	v_mfma_f32_16x16x32_bf16 v[54:57], v[146:149], v[178:181], v[54:57]
	v_mfma_f32_16x16x32_bf16 v[54:57], v[150:153], v[182:185], v[54:57]
	s_waitcnt lgkmcnt(1)
	v_mfma_f32_16x16x32_bf16 v[50:53], v[154:157], v[178:181], v[50:53]
	v_mfma_f32_16x16x32_bf16 v[50:53], v[158:161], v[182:185], v[50:53]
	v_mfma_f32_16x16x32_bf16 v[46:49], v[146:149], v[170:173], v[46:49]
	v_mfma_f32_16x16x32_bf16 v[46:49], v[150:153], v[174:177], v[46:49]
	v_mfma_f32_16x16x32_bf16 v[42:45], v[154:157], v[170:173], v[42:45]
	v_mfma_f32_16x16x32_bf16 v[42:45], v[158:161], v[174:177], v[42:45]
	v_mfma_f32_16x16x32_bf16 v[38:41], v[146:149], v[162:165], v[38:41]
	v_mfma_f32_16x16x32_bf16 v[38:41], v[150:153], v[166:169], v[38:41]
	s_waitcnt lgkmcnt(0)
	v_mfma_f32_16x16x32_bf16 v[34:37], v[154:157], v[162:165], v[34:37]
	v_mfma_f32_16x16x32_bf16 v[34:37], v[158:161], v[166:169], v[34:37]
	s_setprio 0
	s_setprio 1
	v_mfma_f32_16x16x32_bf16 v[30:33], v[130:133], v[186:189], v[30:33]
	v_mfma_f32_16x16x32_bf16 v[30:33], v[134:137], v[190:193], v[30:33]
	v_mfma_f32_16x16x32_bf16 v[26:29], v[138:141], v[186:189], v[26:29]
	v_mfma_f32_16x16x32_bf16 v[26:29], v[142:145], v[190:193], v[26:29]
	v_mfma_f32_16x16x32_bf16 v[22:25], v[130:133], v[178:181], v[22:25]
	v_mfma_f32_16x16x32_bf16 v[22:25], v[134:137], v[182:185], v[22:25]
	v_mfma_f32_16x16x32_bf16 v[18:21], v[138:141], v[178:181], v[18:21]
	v_mfma_f32_16x16x32_bf16 v[18:21], v[142:145], v[182:185], v[18:21]
	v_mfma_f32_16x16x32_bf16 v[14:17], v[130:133], v[170:173], v[14:17]
	v_mfma_f32_16x16x32_bf16 v[14:17], v[134:137], v[174:177], v[14:17]
	v_mfma_f32_16x16x32_bf16 v[10:13], v[138:141], v[170:173], v[10:13]
	v_mfma_f32_16x16x32_bf16 v[10:13], v[142:145], v[174:177], v[10:13]
	s_setprio 2
	s_barrier
	v_mfma_f32_16x16x32_bf16 v[6:9], v[130:133], v[162:165], v[6:9]
	v_mfma_f32_16x16x32_bf16 v[6:9], v[134:137], v[166:169], v[6:9]
	v_mfma_f32_16x16x32_bf16 v[2:5], v[138:141], v[162:165], v[2:5]
	v_mfma_f32_16x16x32_bf16 v[2:5], v[142:145], v[166:169], v[2:5]
	s_setprio 0
	s_nop 0
	v_add_u32_e32 v142, 0x18000, v214
	v_add_u32_e32 v158, 0x1c000, v214
	ds_read_b128 v[130:133], v142
	ds_read_b128 v[134:137], v142 offset:1024
	ds_read_b128 v[138:141], v142 offset:2048
	ds_read_b128 v[142:145], v142 offset:3072
	ds_read_b128 v[146:149], v158
	ds_read_b128 v[150:153], v158 offset:1024
	ds_read_b128 v[154:157], v158 offset:2048
	ds_read_b128 v[158:161], v158 offset:3072
	ds_read_b128 v[162:165], v215 offset:32768
	ds_read_b128 v[166:169], v215 offset:33792
	ds_read_b128 v[170:173], v215 offset:34816
	ds_read_b128 v[174:177], v215 offset:35840
	ds_read_b128 v[178:181], v215 offset:36864
	ds_read_b128 v[182:185], v215 offset:37888
	ds_read_b128 v[186:189], v215 offset:38912
	ds_read_b128 v[190:193], v215 offset:39936
	s_add_u32 s38, s38, 0x4000
	s_addc_u32 s39, s39, 0
	s_mov_b32 m0, s59
	s_nop 0
	global_load_lds_dwordx4 v195, s[38:39]
	s_add_u32 m0, s59, 0x2000
	s_nop 0
	global_load_lds_dwordx4 v208, s[38:39]
	s_waitcnt vmcnt(8)
	s_waitcnt lgkmcnt(0)
	s_setprio 1
	s_barrier
	v_mfma_f32_16x16x32_bf16 v[126:129], v[130:133], v[162:165], v[126:129]
	v_mfma_f32_16x16x32_bf16 v[126:129], v[134:137], v[166:169], v[126:129]
	s_waitcnt lgkmcnt(5)
	v_mfma_f32_16x16x32_bf16 v[122:125], v[138:141], v[162:165], v[122:125]
	v_mfma_f32_16x16x32_bf16 v[122:125], v[142:145], v[166:169], v[122:125]
	s_waitcnt lgkmcnt(3)
	v_mfma_f32_16x16x32_bf16 v[118:121], v[130:133], v[170:173], v[118:121]
	v_mfma_f32_16x16x32_bf16 v[118:121], v[134:137], v[174:177], v[118:121]
	s_waitcnt lgkmcnt(1)
	v_mfma_f32_16x16x32_bf16 v[114:117], v[138:141], v[170:173], v[114:117]
	v_mfma_f32_16x16x32_bf16 v[114:117], v[142:145], v[174:177], v[114:117]
	v_mfma_f32_16x16x32_bf16 v[110:113], v[130:133], v[178:181], v[110:113]
	v_mfma_f32_16x16x32_bf16 v[110:113], v[134:137], v[182:185], v[110:113]
	v_mfma_f32_16x16x32_bf16 v[106:109], v[138:141], v[178:181], v[106:109]
	v_mfma_f32_16x16x32_bf16 v[106:109], v[142:145], v[182:185], v[106:109]
	v_mfma_f32_16x16x32_bf16 v[102:105], v[130:133], v[186:189], v[102:105]
	v_mfma_f32_16x16x32_bf16 v[102:105], v[134:137], v[190:193], v[102:105]
	s_waitcnt lgkmcnt(0)
	v_mfma_f32_16x16x32_bf16 v[98:101], v[138:141], v[186:189], v[98:101]
	v_mfma_f32_16x16x32_bf16 v[98:101], v[142:145], v[190:193], v[98:101]
	s_setprio 0
	s_setprio 1
	v_mfma_f32_16x16x32_bf16 v[94:97], v[146:149], v[162:165], v[94:97]
	v_mfma_f32_16x16x32_bf16 v[94:97], v[150:153], v[166:169], v[94:97]
	v_mfma_f32_16x16x32_bf16 v[90:93], v[154:157], v[162:165], v[90:93]
	v_mfma_f32_16x16x32_bf16 v[90:93], v[158:161], v[166:169], v[90:93]
	v_mfma_f32_16x16x32_bf16 v[86:89], v[146:149], v[170:173], v[86:89]
	v_mfma_f32_16x16x32_bf16 v[86:89], v[150:153], v[174:177], v[86:89]
	v_mfma_f32_16x16x32_bf16 v[82:85], v[154:157], v[170:173], v[82:85]
	v_mfma_f32_16x16x32_bf16 v[82:85], v[158:161], v[174:177], v[82:85]
	v_mfma_f32_16x16x32_bf16 v[78:81], v[146:149], v[178:181], v[78:81]
	v_mfma_f32_16x16x32_bf16 v[78:81], v[150:153], v[182:185], v[78:81]
	v_mfma_f32_16x16x32_bf16 v[74:77], v[154:157], v[178:181], v[74:77]
	v_mfma_f32_16x16x32_bf16 v[74:77], v[158:161], v[182:185], v[74:77]
	s_setprio 2
	s_barrier
	v_mfma_f32_16x16x32_bf16 v[70:73], v[146:149], v[186:189], v[70:73]
	v_mfma_f32_16x16x32_bf16 v[70:73], v[150:153], v[190:193], v[70:73]
	v_mfma_f32_16x16x32_bf16 v[66:69], v[154:157], v[186:189], v[66:69]
	v_mfma_f32_16x16x32_bf16 v[66:69], v[158:161], v[190:193], v[66:69]
	s_setprio 0
	s_nop 0
	ds_read_b128 v[162:165], v215 offset:49152
	ds_read_b128 v[166:169], v215 offset:50176
	ds_read_b128 v[170:173], v215 offset:51200
	ds_read_b128 v[174:177], v215 offset:52224
	ds_read_b128 v[178:181], v215 offset:53248
	ds_read_b128 v[182:185], v215 offset:54272
	ds_read_b128 v[186:189], v215 offset:55296
	ds_read_b128 v[190:193], v215 offset:56320
	s_mov_b32 m0, s63
	s_nop 0
	global_load_lds_dwordx4 v195, s[42:43]
	s_add_u32 m0, s63, 0x2000
	s_nop 0
	global_load_lds_dwordx4 v208, s[42:43]
	s_add_u32 s14, s14, 0xc000
	s_addc_u32 s15, s15, 0
	s_mov_b32 m0, s65
	s_nop 0
	global_load_lds_dwordx4 v195, s[14:15]
	s_add_u32 m0, s65, 0x2000
	s_nop 0
	global_load_lds_dwordx4 v208, s[14:15]
	s_nop 0
	s_mov_b32 m0, s64
	s_nop 0
	global_load_lds_dwordx4 v195, s[40:41]
	s_add_u32 m0, s64, 0x2000
	s_nop 0
	global_load_lds_dwordx4 v208, s[40:41]
	s_waitcnt vmcnt(8)
	s_waitcnt lgkmcnt(0)
	s_setprio 1
	s_barrier
	v_mfma_f32_16x16x32_bf16 v[62:65], v[130:133], v[162:165], v[62:65]
	v_mfma_f32_16x16x32_bf16 v[62:65], v[134:137], v[166:169], v[62:65]
	s_waitcnt lgkmcnt(5)
	v_mfma_f32_16x16x32_bf16 v[58:61], v[138:141], v[162:165], v[58:61]
	v_mfma_f32_16x16x32_bf16 v[58:61], v[142:145], v[166:169], v[58:61]
	s_waitcnt lgkmcnt(3)
	v_mfma_f32_16x16x32_bf16 v[54:57], v[130:133], v[170:173], v[54:57]
	v_mfma_f32_16x16x32_bf16 v[54:57], v[134:137], v[174:177], v[54:57]
	s_waitcnt lgkmcnt(1)
	v_mfma_f32_16x16x32_bf16 v[50:53], v[138:141], v[170:173], v[50:53]
	v_mfma_f32_16x16x32_bf16 v[50:53], v[142:145], v[174:177], v[50:53]
	v_mfma_f32_16x16x32_bf16 v[46:49], v[130:133], v[178:181], v[46:49]
	v_mfma_f32_16x16x32_bf16 v[46:49], v[134:137], v[182:185], v[46:49]
	v_mfma_f32_16x16x32_bf16 v[42:45], v[138:141], v[178:181], v[42:45]
	v_mfma_f32_16x16x32_bf16 v[42:45], v[142:145], v[182:185], v[42:45]
	v_mfma_f32_16x16x32_bf16 v[38:41], v[130:133], v[186:189], v[38:41]
	v_mfma_f32_16x16x32_bf16 v[38:41], v[134:137], v[190:193], v[38:41]
	s_waitcnt lgkmcnt(0)
	v_mfma_f32_16x16x32_bf16 v[34:37], v[138:141], v[186:189], v[34:37]
	v_mfma_f32_16x16x32_bf16 v[34:37], v[142:145], v[190:193], v[34:37]
	s_setprio 0
	s_setprio 1
	v_mfma_f32_16x16x32_bf16 v[30:33], v[146:149], v[162:165], v[30:33]
	v_mfma_f32_16x16x32_bf16 v[30:33], v[150:153], v[166:169], v[30:33]
	v_mfma_f32_16x16x32_bf16 v[26:29], v[154:157], v[162:165], v[26:29]
	v_mfma_f32_16x16x32_bf16 v[26:29], v[158:161], v[166:169], v[26:29]
	v_mfma_f32_16x16x32_bf16 v[22:25], v[146:149], v[170:173], v[22:25]
	v_mfma_f32_16x16x32_bf16 v[22:25], v[150:153], v[174:177], v[22:25]
	v_mfma_f32_16x16x32_bf16 v[18:21], v[154:157], v[170:173], v[18:21]
	v_mfma_f32_16x16x32_bf16 v[18:21], v[158:161], v[174:177], v[18:21]
	v_mfma_f32_16x16x32_bf16 v[14:17], v[146:149], v[178:181], v[14:17]
	v_mfma_f32_16x16x32_bf16 v[14:17], v[150:153], v[182:185], v[14:17]
	v_mfma_f32_16x16x32_bf16 v[10:13], v[154:157], v[178:181], v[10:13]
	v_mfma_f32_16x16x32_bf16 v[10:13], v[158:161], v[182:185], v[10:13]
	s_setprio 2
	s_barrier
	v_mfma_f32_16x16x32_bf16 v[6:9], v[146:149], v[186:189], v[6:9]
	v_mfma_f32_16x16x32_bf16 v[6:9], v[150:153], v[190:193], v[6:9]
	v_mfma_f32_16x16x32_bf16 v[2:5], v[154:157], v[186:189], v[2:5]
	v_mfma_f32_16x16x32_bf16 v[2:5], v[158:161], v[190:193], v[2:5]
	s_setprio 0
	s_nop 0
	s_cmp_gt_u32 s46, 41
	s_cbranch_scc1 .LBB0_2233
	v_mov_b32_e32 v130, v196
	s_mov_b32 s46, s22
	s_branch .LBB0_2208
